# K-loops: MFMA segments made bare - priority raise moved ahead of the opening barrier, priority drop behind the closing barrier, duplicate lgkmcnt wait and mid-segment flip removed
# speedup vs baseline: 1.0132x; 1.0132x over previous
; #define PG8_STAGE(bufoff, gbase, voff) do { _Pragma("unroll") for (int _i = 0; _i < 2; ++_i) \
;         __builtin_amdgcn_global_load_lds((const unsigned*)((const char*)(gbase) + (voff)[_i]), (LAS unsigned*)(lds + (bufoff) + ldsw + _i * 8192), 16, 0, 0); } while (0)
; #define PG8_LDA(dst, b, h) do { _Pragma("unroll") for (int m = 0; m < 4; ++m) _Pragma("unroll") for (int k = 0; k < 2; ++k) dst[m][k] = *(const LAS bf16x8*)(lds + PG8_SA(b, h) + aoff + m * 2048 + k * 1024); } while (0)
; #define PG8_LDB(dst, b, h) do { _Pragma("unroll") for (int n = 0; n < 2; ++n) _Pragma("unroll") for (int k = 0; k < 2; ++k) dst[n][k] = *(const LAS bf16x8*)(lds + PG8_SB(b, h) + boff + n * 2048 + k * 1024); } while (0)
; #define PG8_WAIT_V(n) asm volatile("s_waitcnt vmcnt(" #n ")" ::: "memory")
; #define PG8_WAIT_L(n) asm volatile("s_waitcnt lgkmcnt(" #n ")" ::: "memory")
; #define PG8_BAR __builtin_amdgcn_s_barrier()
; #define PG8_SCHED __builtin_amdgcn_sched_barrier(0)
; template <bool F16, class Sched, class Epi>
; __device__ __forceinline__ void gemm_phase(LAS unsigned char* lds, const Gemm g, const Sched& S, const Epi& E, int wave_s) {
;     ...
;         for (int t = 0; t < nt; t += 2) {
;             const bool last = (t == nt - 2);
;             const char* a1 = cA + (size_t)(t + 1) * kstep;
;             const char* a2 = last ? nA : cA + (size_t)(t + 2) * kstep; const char* b2 = last ? nB : cB + (size_t)(t + 2) * kstep;
;             const char* a3 = a2 + kstep; const char* b3 = b2 + kstep;
;             PG8_LDB(B0, 0, 0); PG8_LDB(B1, 0, 1); PG8_SCHED; PG8_LDA(At, 0, 0); PG8_STAGE(PG8_SA(1, 1), a1 + hstepA, voffA);
;             PG8_WAIT_V(8); PG8_WAIT_L(0); PG8_BAR; PG8_MMA(0, 0, At, B0); PG8_MMA(0, 1, At, B1); PG8_BAR; PG8_SCHED;
;             PG8_LDA(At, 0, 1); PG8_STAGE(PG8_SB(0, 0), b2, voffB); PG8_STAGE(PG8_SB(0, 1), b2 + hstepB, voffB); PG8_STAGE(PG8_SA(0, 0), a2, voffA);
;             PG8_WAIT_V(8); PG8_WAIT_L(0); PG8_BAR; PG8_MMA(1, 0, At, B0); PG8_MMA(1, 1, At, B1); PG8_BAR; PG8_SCHED;
.LBB0_234:
	s_add_i32 s60, 0, 0x10000
	s_add_i32 s62, 0, 0x14000
	v_add_u32_e32 v150, s60, v163
	v_add_u32_e32 v170, s62, v163
	ds_read_b128 v[138:141], v150
	ds_read_b128 v[142:145], v150 offset:1024
	ds_read_b128 v[146:149], v150 offset:2048
	ds_read_b128 v[150:153], v150 offset:3072
	ds_read_b128 v[154:157], v170
	ds_read_b128 v[158:161], v170 offset:1024
	ds_read_b128 v[166:169], v170 offset:2048
	ds_read_b128 v[170:173], v170 offset:3072
	s_add_i32 m0, s41, 0xc000
	ds_read_b128 v[178:181], v165
	ds_read_b128 v[182:185], v165 offset:1024
	ds_read_b128 v[186:189], v165 offset:2048
	ds_read_b128 v[190:193], v165 offset:3072
	ds_read_b128 v[208:211], v165 offset:4096
	ds_read_b128 v[212:215], v165 offset:5120
	ds_read_b128 v[216:219], v165 offset:6144
	ds_read_b128 v[220:223], v165 offset:7168
	global_load_lds_dwordx4 v134, s[26:27]
	s_add_i32 m0, s41, 0xe000
	s_nop 0
	global_load_lds_dwordx4 v136, s[26:27]
	s_waitcnt vmcnt(8)
	s_waitcnt lgkmcnt(0)
	s_setprio 1
	s_barrier
	v_mfma_f32_16x16x32_bf16 v[124:127], v[138:141], v[178:181], v[124:127]
	v_mfma_f32_16x16x32_bf16 v[120:123], v[146:149], v[178:181], v[120:123]
	v_mfma_f32_16x16x32_bf16 v[108:111], v[138:141], v[186:189], v[108:111]
	v_mfma_f32_16x16x32_bf16 v[104:107], v[146:149], v[186:189], v[104:107]
	v_mfma_f32_16x16x32_bf16 v[96:99], v[138:141], v[208:211], v[96:99]
	v_mfma_f32_16x16x32_bf16 v[92:95], v[146:149], v[208:211], v[92:95]
	v_mfma_f32_16x16x32_bf16 v[84:87], v[138:141], v[216:219], v[84:87]
	v_mfma_f32_16x16x32_bf16 v[76:79], v[146:149], v[216:219], v[76:79]
	v_mfma_f32_16x16x32_bf16 v[124:127], v[142:145], v[182:185], v[124:127]
	v_mfma_f32_16x16x32_bf16 v[120:123], v[150:153], v[182:185], v[120:123]
	v_mfma_f32_16x16x32_bf16 v[108:111], v[142:145], v[190:193], v[108:111]
	v_mfma_f32_16x16x32_bf16 v[104:107], v[150:153], v[190:193], v[104:107]
	v_mfma_f32_16x16x32_bf16 v[96:99], v[142:145], v[212:215], v[96:99]
	v_mfma_f32_16x16x32_bf16 v[92:95], v[150:153], v[212:215], v[92:95]
	v_mfma_f32_16x16x32_bf16 v[84:87], v[142:145], v[220:223], v[84:87]
	v_mfma_f32_16x16x32_bf16 v[76:79], v[150:153], v[220:223], v[76:79]
	v_mfma_f32_16x16x32_bf16 v[116:119], v[154:157], v[178:181], v[116:119]
	v_mfma_f32_16x16x32_bf16 v[112:115], v[166:169], v[178:181], v[112:115]
	v_mfma_f32_16x16x32_bf16 v[100:103], v[154:157], v[186:189], v[100:103]
	v_mfma_f32_16x16x32_bf16 v[88:91], v[166:169], v[186:189], v[88:91]
	v_mfma_f32_16x16x32_bf16 v[80:83], v[154:157], v[208:211], v[80:83]
	v_mfma_f32_16x16x32_bf16 v[72:75], v[166:169], v[208:211], v[72:75]
	v_mfma_f32_16x16x32_bf16 v[68:71], v[154:157], v[216:219], v[68:71]
	v_mfma_f32_16x16x32_bf16 v[64:67], v[166:169], v[216:219], v[64:67]
	v_mfma_f32_16x16x32_bf16 v[116:119], v[158:161], v[182:185], v[116:119]
	v_mfma_f32_16x16x32_bf16 v[112:115], v[170:173], v[182:185], v[112:115]
	v_mfma_f32_16x16x32_bf16 v[100:103], v[158:161], v[190:193], v[100:103]
	v_mfma_f32_16x16x32_bf16 v[88:91], v[170:173], v[190:193], v[88:91]
	v_mfma_f32_16x16x32_bf16 v[80:83], v[158:161], v[212:215], v[80:83]
	v_mfma_f32_16x16x32_bf16 v[72:75], v[170:173], v[212:215], v[72:75]
	v_mfma_f32_16x16x32_bf16 v[68:71], v[158:161], v[220:223], v[68:71]
	v_mfma_f32_16x16x32_bf16 v[64:67], v[170:173], v[220:223], v[64:67]
	s_barrier
	s_setprio 0
	s_add_u32 s28, s26, 0xfff80080
	s_addc_u32 s29, s27, -1
	s_cmp_eq_u32 s59, 4
	s_cselect_b32 s31, s13, s29
	s_cselect_b32 s30, s12, s28
	s_cselect_b32 s29, s0, s58
	s_cselect_b32 s28, s1, s53
	s_add_i32 s60, s60, s39
	v_lshl_add_u64 v[174:175], s[28:29], 0, v[176:177]
	s_mov_b32 m0, s60
	ds_read_b128 v[178:181], v165 offset:16384
	ds_read_b128 v[182:185], v165 offset:17408
	ds_read_b128 v[186:189], v165 offset:18432
	ds_read_b128 v[190:193], v165 offset:19456
	ds_read_b128 v[208:211], v165 offset:20480
	ds_read_b128 v[212:215], v165 offset:21504
	ds_read_b128 v[216:219], v165 offset:22528
	ds_read_b128 v[220:223], v165 offset:23552
	global_load_lds_dwordx4 v[174:175], off
	s_add_i32 m0, s60, 0x2000
	s_add_u32 s60, s28, 0x20000
	v_lshl_add_u64 v[194:195], s[28:29], 0, v[128:129]
	s_addc_u32 s61, s29, 0
	s_add_i32 s62, s62, s39
	global_load_lds_dwordx4 v[194:195], off
	v_lshl_add_u64 v[198:199], s[60:61], 0, v[176:177]
	s_mov_b32 m0, s62
	v_lshl_add_u64 v[200:201], s[30:31], 0, v[130:131]
	global_load_lds_dwordx4 v[198:199], off
	v_lshl_add_u64 v[198:199], s[60:61], 0, v[128:129]
	s_add_i32 m0, s62, 0x2000
	s_nop 0
	global_load_lds_dwordx4 v[198:199], off
	v_lshl_add_u64 v[198:199], s[30:31], 0, v[132:133]
	s_mov_b32 m0, s41
	s_nop 0
	global_load_lds_dwordx4 v[198:199], off
	s_mov_b32 m0, s42
	s_nop 0
	global_load_lds_dwordx4 v[200:201], off
	s_add_u32 s30, s30, 0x80000
	s_addc_u32 s31, s31, 0
	s_waitcnt vmcnt(8)
	s_waitcnt lgkmcnt(0)
	s_setprio 1
	s_barrier
; #define PG8_STAGE(bufoff, gbase, voff) do { _Pragma("unroll") for (int _i = 0; _i < 2; ++_i) \
;         __builtin_amdgcn_global_load_lds((const unsigned*)((const char*)(gbase) + (voff)[_i]), (LAS unsigned*)(lds + (bufoff) + ldsw + _i * 8192), 16, 0, 0); } while (0)
; #define PG8_LDA(dst, b, h) do { _Pragma("unroll") for (int m = 0; m < 4; ++m) _Pragma("unroll") for (int k = 0; k < 2; ++k) dst[m][k] = *(const LAS bf16x8*)(lds + PG8_SA(b, h) + aoff + m * 2048 + k * 1024); } while (0)
; #define PG8_LDB(dst, b, h) do { _Pragma("unroll") for (int n = 0; n < 2; ++n) _Pragma("unroll") for (int k = 0; k < 2; ++k) dst[n][k] = *(const LAS bf16x8*)(lds + PG8_SB(b, h) + boff + n * 2048 + k * 1024); } while (0)
; #define PG8_WAIT_V(n) asm volatile("s_waitcnt vmcnt(" #n ")" ::: "memory")
; #define PG8_WAIT_L(n) asm volatile("s_waitcnt lgkmcnt(" #n ")" ::: "memory")
; #define PG8_BAR __builtin_amdgcn_s_barrier()
; #define PG8_SCHED __builtin_amdgcn_sched_barrier(0)
; template <bool F16, class Sched, class Epi>
; __device__ __forceinline__ void gemm_phase(LAS unsigned char* lds, const Gemm g, const Sched& S, const Epi& E, int wave_s) {
;     ...
;             PG8_WAIT_V(8); PG8_WAIT_L(0); PG8_BAR; PG8_MMA(1, 0, At, B0); PG8_MMA(1, 1, At, B1); PG8_BAR; PG8_SCHED;
;             PG8_LDB(B0, 1, 0); PG8_LDB(B1, 1, 1); PG8_SCHED; PG8_LDA(At, 1, 0); PG8_STAGE(PG8_SA(0, 1), a2 + hstepA, voffA);
;             PG8_WAIT_V(8); PG8_WAIT_L(0); PG8_BAR; PG8_MMA(0, 0, At, B0); PG8_MMA(0, 1, At, B1); PG8_BAR; PG8_SCHED;
	v_mfma_f32_16x16x32_bf16 v[60:63], v[138:141], v[178:181], v[60:63]
	v_mfma_f32_16x16x32_bf16 v[56:59], v[146:149], v[178:181], v[56:59]
	v_mfma_f32_16x16x32_bf16 v[52:55], v[138:141], v[186:189], v[52:55]
	v_mfma_f32_16x16x32_bf16 v[44:47], v[146:149], v[186:189], v[44:47]
	v_mfma_f32_16x16x32_bf16 v[36:39], v[138:141], v[208:211], v[36:39]
	v_mfma_f32_16x16x32_bf16 v[28:31], v[146:149], v[208:211], v[28:31]
	v_mfma_f32_16x16x32_bf16 v[20:23], v[138:141], v[216:219], v[20:23]
	v_mfma_f32_16x16x32_bf16 v[12:15], v[146:149], v[216:219], v[12:15]
	v_mfma_f32_16x16x32_bf16 v[60:63], v[142:145], v[182:185], v[60:63]
	v_mfma_f32_16x16x32_bf16 v[56:59], v[150:153], v[182:185], v[56:59]
	v_mfma_f32_16x16x32_bf16 v[52:55], v[142:145], v[190:193], v[52:55]
	v_mfma_f32_16x16x32_bf16 v[44:47], v[150:153], v[190:193], v[44:47]
	v_mfma_f32_16x16x32_bf16 v[36:39], v[142:145], v[212:215], v[36:39]
	v_mfma_f32_16x16x32_bf16 v[28:31], v[150:153], v[212:215], v[28:31]
	v_mfma_f32_16x16x32_bf16 v[20:23], v[142:145], v[220:223], v[20:23]
	v_mfma_f32_16x16x32_bf16 v[12:15], v[150:153], v[220:223], v[12:15]
	v_mfma_f32_16x16x32_bf16 v[48:51], v[154:157], v[178:181], v[48:51]
	v_mfma_f32_16x16x32_bf16 v[40:43], v[166:169], v[178:181], v[40:43]
	v_mfma_f32_16x16x32_bf16 v[32:35], v[154:157], v[186:189], v[32:35]
	v_mfma_f32_16x16x32_bf16 v[24:27], v[166:169], v[186:189], v[24:27]
	v_mfma_f32_16x16x32_bf16 v[16:19], v[154:157], v[208:211], v[16:19]
	v_mfma_f32_16x16x32_bf16 v[8:11], v[166:169], v[208:211], v[8:11]
	v_mfma_f32_16x16x32_bf16 v[4:7], v[154:157], v[216:219], v[4:7]
	v_mfma_f32_16x16x32_bf16 v[0:3], v[166:169], v[216:219], v[0:3]
	v_mfma_f32_16x16x32_bf16 v[48:51], v[158:161], v[182:185], v[48:51]
	v_mfma_f32_16x16x32_bf16 v[40:43], v[170:173], v[182:185], v[40:43]
	v_mfma_f32_16x16x32_bf16 v[32:35], v[158:161], v[190:193], v[32:35]
	v_mfma_f32_16x16x32_bf16 v[24:27], v[170:173], v[190:193], v[24:27]
	v_mfma_f32_16x16x32_bf16 v[16:19], v[158:161], v[212:215], v[16:19]
	v_mfma_f32_16x16x32_bf16 v[8:11], v[170:173], v[212:215], v[8:11]
	v_mfma_f32_16x16x32_bf16 v[4:7], v[158:161], v[220:223], v[4:7]
	v_mfma_f32_16x16x32_bf16 v[0:3], v[170:173], v[220:223], v[0:3]
	s_barrier
	s_setprio 0
	s_add_i32 s60, 0, 0x18000
	s_add_i32 s61, 0, 0x1c000
	v_add_u32_e32 v150, s60, v163
	v_add_u32_e32 v170, s61, v163
	ds_read_b128 v[138:141], v150
	ds_read_b128 v[142:145], v150 offset:1024
	ds_read_b128 v[146:149], v150 offset:2048
	ds_read_b128 v[150:153], v150 offset:3072
	ds_read_b128 v[154:157], v170
	ds_read_b128 v[158:161], v170 offset:1024
	ds_read_b128 v[166:169], v170 offset:2048
	ds_read_b128 v[170:173], v170 offset:3072
	s_mov_b32 m0, s43
	ds_read_b128 v[178:181], v165 offset:32768
	ds_read_b128 v[182:185], v165 offset:33792
	ds_read_b128 v[186:189], v165 offset:34816
	ds_read_b128 v[190:193], v165 offset:35840
	ds_read_b128 v[208:211], v165 offset:36864
	ds_read_b128 v[212:215], v165 offset:37888
	ds_read_b128 v[216:219], v165 offset:38912
	ds_read_b128 v[220:223], v165 offset:39936
	global_load_lds_dwordx4 v132, s[30:31]
	s_mov_b32 m0, s44
	s_nop 0
	global_load_lds_dwordx4 v130, s[30:31]
	s_waitcnt vmcnt(8)
	s_waitcnt lgkmcnt(0)
	s_setprio 1
	s_barrier
	v_mfma_f32_16x16x32_bf16 v[124:127], v[138:141], v[178:181], v[124:127]
	v_mfma_f32_16x16x32_bf16 v[120:123], v[146:149], v[178:181], v[120:123]
	v_mfma_f32_16x16x32_bf16 v[108:111], v[138:141], v[186:189], v[108:111]
	v_mfma_f32_16x16x32_bf16 v[104:107], v[146:149], v[186:189], v[104:107]
	v_mfma_f32_16x16x32_bf16 v[96:99], v[138:141], v[208:211], v[96:99]
	v_mfma_f32_16x16x32_bf16 v[92:95], v[146:149], v[208:211], v[92:95]
	v_mfma_f32_16x16x32_bf16 v[84:87], v[138:141], v[216:219], v[84:87]
	v_mfma_f32_16x16x32_bf16 v[76:79], v[146:149], v[216:219], v[76:79]
	v_mfma_f32_16x16x32_bf16 v[124:127], v[142:145], v[182:185], v[124:127]
	v_mfma_f32_16x16x32_bf16 v[120:123], v[150:153], v[182:185], v[120:123]
	v_mfma_f32_16x16x32_bf16 v[108:111], v[142:145], v[190:193], v[108:111]
	v_mfma_f32_16x16x32_bf16 v[104:107], v[150:153], v[190:193], v[104:107]
	v_mfma_f32_16x16x32_bf16 v[96:99], v[142:145], v[212:215], v[96:99]
	v_mfma_f32_16x16x32_bf16 v[92:95], v[150:153], v[212:215], v[92:95]
	v_mfma_f32_16x16x32_bf16 v[84:87], v[142:145], v[220:223], v[84:87]
	v_mfma_f32_16x16x32_bf16 v[76:79], v[150:153], v[220:223], v[76:79]
	v_mfma_f32_16x16x32_bf16 v[116:119], v[154:157], v[178:181], v[116:119]
	v_mfma_f32_16x16x32_bf16 v[112:115], v[166:169], v[178:181], v[112:115]
	v_mfma_f32_16x16x32_bf16 v[100:103], v[154:157], v[186:189], v[100:103]
	v_mfma_f32_16x16x32_bf16 v[88:91], v[166:169], v[186:189], v[88:91]
	v_mfma_f32_16x16x32_bf16 v[80:83], v[154:157], v[208:211], v[80:83]
	v_mfma_f32_16x16x32_bf16 v[72:75], v[166:169], v[208:211], v[72:75]
	v_mfma_f32_16x16x32_bf16 v[68:71], v[154:157], v[216:219], v[68:71]
	v_mfma_f32_16x16x32_bf16 v[64:67], v[166:169], v[216:219], v[64:67]
	v_mfma_f32_16x16x32_bf16 v[116:119], v[158:161], v[182:185], v[116:119]
	v_mfma_f32_16x16x32_bf16 v[112:115], v[170:173], v[182:185], v[112:115]
	v_mfma_f32_16x16x32_bf16 v[100:103], v[158:161], v[190:193], v[100:103]
	v_mfma_f32_16x16x32_bf16 v[88:91], v[170:173], v[190:193], v[88:91]
	v_mfma_f32_16x16x32_bf16 v[80:83], v[158:161], v[212:215], v[80:83]
	v_mfma_f32_16x16x32_bf16 v[72:75], v[170:173], v[212:215], v[72:75]
	v_mfma_f32_16x16x32_bf16 v[68:71], v[158:161], v[220:223], v[68:71]
	v_mfma_f32_16x16x32_bf16 v[64:67], v[170:173], v[220:223], v[64:67]
	s_barrier
; #define PG8_STAGE(bufoff, gbase, voff) do { _Pragma("unroll") for (int _i = 0; _i < 2; ++_i) \
;         __builtin_amdgcn_global_load_lds((const unsigned*)((const char*)(gbase) + (voff)[_i]), (LAS unsigned*)(lds + (bufoff) + ldsw + _i * 8192), 16, 0, 0); } while (0)
; #define PG8_LDA(dst, b, h) do { _Pragma("unroll") for (int m = 0; m < 4; ++m) _Pragma("unroll") for (int k = 0; k < 2; ++k) dst[m][k] = *(const LAS bf16x8*)(lds + PG8_SA(b, h) + aoff + m * 2048 + k * 1024); } while (0)
; #define PG8_WAIT_V(n) asm volatile("s_waitcnt vmcnt(" #n ")" ::: "memory")
; #define PG8_WAIT_L(n) asm volatile("s_waitcnt lgkmcnt(" #n ")" ::: "memory")
; #define PG8_BAR __builtin_amdgcn_s_barrier()
; #define PG8_SCHED __builtin_amdgcn_sched_barrier(0)
; template <bool F16, class Sched, class Epi>
; __device__ __forceinline__ void gemm_phase(LAS unsigned char* lds, const Gemm g, const Sched& S, const Epi& E, int wave_s) {
;     ...
;             PG8_LDA(At, 1, 1); PG8_STAGE(PG8_SB(1, 0), b3, voffB); PG8_STAGE(PG8_SB(1, 1), b3 + hstepB, voffB); PG8_STAGE(PG8_SA(1, 0), a3, voffA);
;             PG8_WAIT_V(8); PG8_WAIT_L(0); PG8_BAR; PG8_MMA(1, 0, At, B0); PG8_MMA(1, 1, At, B1); PG8_BAR; PG8_SCHED;
;         }
	s_setprio 0
	s_add_i32 s30, s60, s39
	v_lshl_add_u64 v[174:175], v[174:175], 0, s[54:55]
	s_mov_b32 m0, s30
	ds_read_b128 v[178:181], v165 offset:49152
	ds_read_b128 v[182:185], v165 offset:50176
	ds_read_b128 v[186:189], v165 offset:51200
	ds_read_b128 v[190:193], v165 offset:52224
	ds_read_b128 v[208:211], v165 offset:53248
	ds_read_b128 v[212:215], v165 offset:54272
	ds_read_b128 v[216:219], v165 offset:55296
	ds_read_b128 v[220:223], v165 offset:56320
	global_load_lds_dwordx4 v[174:175], off
	s_add_i32 m0, s30, 0x2000
	s_add_u32 s28, s28, 0x20080
	v_lshl_add_u64 v[174:175], v[194:195], 0, s[54:55]
	s_addc_u32 s29, s29, 0
	s_add_i32 s30, s61, s39
	global_load_lds_dwordx4 v[174:175], off
	v_lshl_add_u64 v[174:175], s[28:29], 0, v[176:177]
	s_mov_b32 m0, s30
	s_nop 0
	global_load_lds_dwordx4 v[174:175], off
	v_lshl_add_u64 v[174:175], s[28:29], 0, v[128:129]
	s_add_i32 m0, s30, 0x2000
	s_nop 0
	global_load_lds_dwordx4 v[174:175], off
	v_lshl_add_u64 v[174:175], v[198:199], 0, s[54:55]
	s_mov_b32 m0, s19
	s_nop 0
	global_load_lds_dwordx4 v[174:175], off
	v_lshl_add_u64 v[174:175], v[200:201], 0, s[54:55]
	s_mov_b32 m0, s45
	s_nop 0
	global_load_lds_dwordx4 v[174:175], off
	s_waitcnt vmcnt(8)
	s_waitcnt lgkmcnt(0)
	s_setprio 1
	s_barrier
	v_mfma_f32_16x16x32_bf16 v[60:63], v[138:141], v[178:181], v[60:63]
	v_mfma_f32_16x16x32_bf16 v[56:59], v[146:149], v[178:181], v[56:59]
	v_mfma_f32_16x16x32_bf16 v[52:55], v[138:141], v[186:189], v[52:55]
	v_mfma_f32_16x16x32_bf16 v[44:47], v[146:149], v[186:189], v[44:47]
	v_mfma_f32_16x16x32_bf16 v[36:39], v[138:141], v[208:211], v[36:39]
	v_mfma_f32_16x16x32_bf16 v[28:31], v[146:149], v[208:211], v[28:31]
	v_mfma_f32_16x16x32_bf16 v[20:23], v[138:141], v[216:219], v[20:23]
	v_mfma_f32_16x16x32_bf16 v[12:15], v[146:149], v[216:219], v[12:15]
	v_mfma_f32_16x16x32_bf16 v[60:63], v[142:145], v[182:185], v[60:63]
	v_mfma_f32_16x16x32_bf16 v[56:59], v[150:153], v[182:185], v[56:59]
	v_mfma_f32_16x16x32_bf16 v[52:55], v[142:145], v[190:193], v[52:55]
	v_mfma_f32_16x16x32_bf16 v[44:47], v[150:153], v[190:193], v[44:47]
	v_mfma_f32_16x16x32_bf16 v[36:39], v[142:145], v[212:215], v[36:39]
	v_mfma_f32_16x16x32_bf16 v[28:31], v[150:153], v[212:215], v[28:31]
	v_mfma_f32_16x16x32_bf16 v[20:23], v[142:145], v[220:223], v[20:23]
	v_mfma_f32_16x16x32_bf16 v[12:15], v[150:153], v[220:223], v[12:15]
	v_mfma_f32_16x16x32_bf16 v[48:51], v[154:157], v[178:181], v[48:51]
	v_mfma_f32_16x16x32_bf16 v[40:43], v[166:169], v[178:181], v[40:43]
	v_mfma_f32_16x16x32_bf16 v[32:35], v[154:157], v[186:189], v[32:35]
	v_mfma_f32_16x16x32_bf16 v[24:27], v[166:169], v[186:189], v[24:27]
	v_mfma_f32_16x16x32_bf16 v[16:19], v[154:157], v[208:211], v[16:19]
	v_mfma_f32_16x16x32_bf16 v[8:11], v[166:169], v[208:211], v[8:11]
	v_mfma_f32_16x16x32_bf16 v[4:7], v[154:157], v[216:219], v[4:7]
	v_mfma_f32_16x16x32_bf16 v[0:3], v[166:169], v[216:219], v[0:3]
	v_mfma_f32_16x16x32_bf16 v[48:51], v[158:161], v[182:185], v[48:51]
	v_mfma_f32_16x16x32_bf16 v[40:43], v[170:173], v[182:185], v[40:43]
	v_mfma_f32_16x16x32_bf16 v[32:35], v[158:161], v[190:193], v[32:35]
	v_mfma_f32_16x16x32_bf16 v[24:27], v[170:173], v[190:193], v[24:27]
	v_mfma_f32_16x16x32_bf16 v[16:19], v[158:161], v[212:215], v[16:19]
	v_mfma_f32_16x16x32_bf16 v[8:11], v[170:173], v[212:215], v[8:11]
	v_mfma_f32_16x16x32_bf16 v[4:7], v[158:161], v[220:223], v[4:7]
	v_mfma_f32_16x16x32_bf16 v[0:3], v[170:173], v[220:223], v[0:3]
	s_barrier
	s_setprio 0
	s_add_i32 s59, s59, 2
	s_add_u32 s26, s26, 0x100
	s_addc_u32 s27, s27, 0
	s_add_u32 s53, s53, 0x100
	s_addc_u32 s58, s58, 0
	s_cmp_gt_u32 s59, 5
	s_cbranch_scc0 .LBB0_234
	s_and_b64 vcc, exec, s[10:11]
	s_cbranch_vccz .LBB0_237
	s_barrier

; #define PG8_STAGE(bufoff, gbase, voff) do { _Pragma("unroll") for (int _i = 0; _i < 2; ++_i) \
;         __builtin_amdgcn_global_load_lds((const unsigned*)((const char*)(gbase) + (voff)[_i]), (LAS unsigned*)(lds + (bufoff) + ldsw + _i * 8192), 16, 0, 0); } while (0)
; #define PG8_LDA(dst, b, h) do { _Pragma("unroll") for (int m = 0; m < 4; ++m) _Pragma("unroll") for (int k = 0; k < 2; ++k) dst[m][k] = *(const LAS bf16x8*)(lds + PG8_SA(b, h) + aoff + m * 2048 + k * 1024); } while (0)
; #define PG8_LDB(dst, b, h) do { _Pragma("unroll") for (int n = 0; n < 2; ++n) _Pragma("unroll") for (int k = 0; k < 2; ++k) dst[n][k] = *(const LAS bf16x8*)(lds + PG8_SB(b, h) + boff + n * 2048 + k * 1024); } while (0)
; #define PG8_WAIT_V(n) asm volatile("s_waitcnt vmcnt(" #n ")" ::: "memory")
; #define PG8_WAIT_L(n) asm volatile("s_waitcnt lgkmcnt(" #n ")" ::: "memory")
; #define PG8_BAR __builtin_amdgcn_s_barrier()
; #define PG8_SCHED __builtin_amdgcn_sched_barrier(0)
; template <bool F16, class Sched, class Epi>
; __device__ __forceinline__ void gemm_phase(LAS unsigned char* lds, const Gemm g, const Sched& S, const Epi& E, int wave_s) {
;     ...
;         for (int t = 0; t < nt; t += 2) {
;             const bool last = (t == nt - 2);
;             const char* a1 = cA + (size_t)(t + 1) * kstep;
;             const char* a2 = last ? nA : cA + (size_t)(t + 2) * kstep; const char* b2 = last ? nB : cB + (size_t)(t + 2) * kstep;
;             const char* a3 = a2 + kstep; const char* b3 = b2 + kstep;
;             PG8_LDB(B0, 0, 0); PG8_LDB(B1, 0, 1); PG8_SCHED; PG8_LDA(At, 0, 0); PG8_STAGE(PG8_SA(1, 1), a1 + hstepA, voffA);
;             PG8_WAIT_V(8); PG8_WAIT_L(0); PG8_BAR; PG8_MMA(0, 0, At, B0); PG8_MMA(0, 1, At, B1); PG8_BAR; PG8_SCHED;
;             PG8_LDA(At, 0, 1); PG8_STAGE(PG8_SB(0, 0), b2, voffB); PG8_STAGE(PG8_SB(0, 1), b2 + hstepB, voffB); PG8_STAGE(PG8_SA(0, 0), a2, voffA);
;             PG8_WAIT_V(8); PG8_WAIT_L(0); PG8_BAR; PG8_MMA(1, 0, At, B0); PG8_MMA(1, 1, At, B1); PG8_BAR; PG8_SCHED;
.LBB0_304:
	s_add_i32 s71, 0, 0x10000
	s_add_i32 s74, 0, 0x14000
	v_add_u32_e32 v150, s71, v162
	v_add_u32_e32 v158, s74, v162
	ds_read_b128 v[138:141], v150
	ds_read_b128 v[142:145], v150 offset:1024
	ds_read_b128 v[146:149], v150 offset:2048
	ds_read_b128 v[150:153], v150 offset:3072
	ds_read_b128 v[154:157], v158
	ds_read_b128 v[166:169], v158 offset:1024
	ds_read_b128 v[170:173], v158 offset:2048
	ds_read_b128 v[178:181], v158 offset:3072
	s_add_i32 m0, s49, 0xc000
	ds_read_b128 v[182:185], v164
	ds_read_b128 v[186:189], v164 offset:1024
	ds_read_b128 v[190:193], v164 offset:2048
	ds_read_b128 v[208:211], v164 offset:3072
	ds_read_b128 v[212:215], v164 offset:4096
	ds_read_b128 v[216:219], v164 offset:5120
	ds_read_b128 v[220:223], v164 offset:6144
	ds_read_b128 v[224:227], v164 offset:7168
	global_load_lds_dwordx4 v134, s[2:3]
	s_add_i32 m0, s49, 0xe000
	s_nop 0
	global_load_lds_dwordx4 v136, s[2:3]
	s_waitcnt vmcnt(8)
	s_waitcnt lgkmcnt(0)
	s_setprio 1
	s_barrier
	v_mfma_f32_16x16x32_bf16 v[124:127], v[138:141], v[182:185], v[124:127]
	v_mfma_f32_16x16x32_bf16 v[120:123], v[146:149], v[182:185], v[120:123]
	v_mfma_f32_16x16x32_bf16 v[108:111], v[138:141], v[190:193], v[108:111]
	v_mfma_f32_16x16x32_bf16 v[104:107], v[146:149], v[190:193], v[104:107]
	v_mfma_f32_16x16x32_bf16 v[92:95], v[138:141], v[212:215], v[92:95]
	v_mfma_f32_16x16x32_bf16 v[88:91], v[146:149], v[212:215], v[88:91]
	v_mfma_f32_16x16x32_bf16 v[76:79], v[138:141], v[220:223], v[76:79]
	v_mfma_f32_16x16x32_bf16 v[72:75], v[146:149], v[220:223], v[72:75]
	v_mfma_f32_16x16x32_bf16 v[124:127], v[142:145], v[186:189], v[124:127]
	v_mfma_f32_16x16x32_bf16 v[120:123], v[150:153], v[186:189], v[120:123]
	v_mfma_f32_16x16x32_bf16 v[108:111], v[142:145], v[208:211], v[108:111]
	v_mfma_f32_16x16x32_bf16 v[104:107], v[150:153], v[208:211], v[104:107]
	v_mfma_f32_16x16x32_bf16 v[92:95], v[142:145], v[216:219], v[92:95]
	v_mfma_f32_16x16x32_bf16 v[88:91], v[150:153], v[216:219], v[88:91]
	v_mfma_f32_16x16x32_bf16 v[76:79], v[142:145], v[224:227], v[76:79]
	v_mfma_f32_16x16x32_bf16 v[72:75], v[150:153], v[224:227], v[72:75]
	v_mfma_f32_16x16x32_bf16 v[116:119], v[154:157], v[182:185], v[116:119]
	v_mfma_f32_16x16x32_bf16 v[112:115], v[170:173], v[182:185], v[112:115]
	v_mfma_f32_16x16x32_bf16 v[100:103], v[154:157], v[190:193], v[100:103]
	v_mfma_f32_16x16x32_bf16 v[96:99], v[170:173], v[190:193], v[96:99]
	v_mfma_f32_16x16x32_bf16 v[84:87], v[154:157], v[212:215], v[84:87]
	v_mfma_f32_16x16x32_bf16 v[80:83], v[170:173], v[212:215], v[80:83]
	v_mfma_f32_16x16x32_bf16 v[68:71], v[154:157], v[220:223], v[68:71]
	v_mfma_f32_16x16x32_bf16 v[64:67], v[170:173], v[220:223], v[64:67]
	v_mfma_f32_16x16x32_bf16 v[116:119], v[166:169], v[186:189], v[116:119]
	v_mfma_f32_16x16x32_bf16 v[112:115], v[178:181], v[186:189], v[112:115]
	v_mfma_f32_16x16x32_bf16 v[100:103], v[166:169], v[208:211], v[100:103]
	v_mfma_f32_16x16x32_bf16 v[96:99], v[178:181], v[208:211], v[96:99]
	v_mfma_f32_16x16x32_bf16 v[84:87], v[166:169], v[216:219], v[84:87]
	v_mfma_f32_16x16x32_bf16 v[80:83], v[178:181], v[216:219], v[80:83]
	v_mfma_f32_16x16x32_bf16 v[68:71], v[166:169], v[224:227], v[68:71]
	v_mfma_f32_16x16x32_bf16 v[64:67], v[178:181], v[224:227], v[64:67]
	s_barrier
	s_setprio 0
	s_add_u32 s4, s2, 0xfff80080
	s_addc_u32 s5, s3, -1
	s_cmp_eq_u32 s70, 28
	s_cselect_b32 s39, s62, s5
	s_cselect_b32 s38, s63, s4
	s_cselect_b32 s5, s64, s69
	s_cselect_b32 s4, s65, s68
	s_add_i32 s71, s71, s46
	v_lshl_add_u64 v[158:159], s[4:5], 0, v[176:177]
	s_mov_b32 m0, s71
	ds_read_b128 v[182:185], v164 offset:16384
	ds_read_b128 v[186:189], v164 offset:17408
	ds_read_b128 v[190:193], v164 offset:18432
	ds_read_b128 v[208:211], v164 offset:19456
	ds_read_b128 v[212:215], v164 offset:20480
	ds_read_b128 v[216:219], v164 offset:21504
	ds_read_b128 v[220:223], v164 offset:22528
	ds_read_b128 v[224:227], v164 offset:23552
	global_load_lds_dwordx4 v[158:159], off
	s_add_i32 m0, s71, 0x2000
	s_add_u32 s72, s4, 0x80000
	v_lshl_add_u64 v[174:175], s[4:5], 0, v[128:129]
	s_addc_u32 s73, s5, 0
	s_add_i32 s71, s74, s46
	global_load_lds_dwordx4 v[174:175], off
	v_lshl_add_u64 v[194:195], s[72:73], 0, v[176:177]
	s_mov_b32 m0, s71
	v_lshl_add_u64 v[198:199], s[38:39], 0, v[130:131]
	global_load_lds_dwordx4 v[194:195], off
	v_lshl_add_u64 v[194:195], s[72:73], 0, v[128:129]
	s_add_i32 m0, s71, 0x2000
	s_nop 0
	global_load_lds_dwordx4 v[194:195], off
	v_lshl_add_u64 v[194:195], s[38:39], 0, v[132:133]
	s_mov_b32 m0, s49
	s_nop 0
	global_load_lds_dwordx4 v[194:195], off
	s_mov_b32 m0, s52
	s_nop 0
	global_load_lds_dwordx4 v[198:199], off
	s_add_u32 s38, s38, 0x80000
	s_addc_u32 s39, s39, 0
	s_waitcnt vmcnt(8)
	s_waitcnt lgkmcnt(0)
	s_setprio 1
	s_barrier
; #define PG8_STAGE(bufoff, gbase, voff) do { _Pragma("unroll") for (int _i = 0; _i < 2; ++_i) \
;         __builtin_amdgcn_global_load_lds((const unsigned*)((const char*)(gbase) + (voff)[_i]), (LAS unsigned*)(lds + (bufoff) + ldsw + _i * 8192), 16, 0, 0); } while (0)
; #define PG8_LDA(dst, b, h) do { _Pragma("unroll") for (int m = 0; m < 4; ++m) _Pragma("unroll") for (int k = 0; k < 2; ++k) dst[m][k] = *(const LAS bf16x8*)(lds + PG8_SA(b, h) + aoff + m * 2048 + k * 1024); } while (0)
; #define PG8_LDB(dst, b, h) do { _Pragma("unroll") for (int n = 0; n < 2; ++n) _Pragma("unroll") for (int k = 0; k < 2; ++k) dst[n][k] = *(const LAS bf16x8*)(lds + PG8_SB(b, h) + boff + n * 2048 + k * 1024); } while (0)
; #define PG8_WAIT_V(n) asm volatile("s_waitcnt vmcnt(" #n ")" ::: "memory")
; #define PG8_WAIT_L(n) asm volatile("s_waitcnt lgkmcnt(" #n ")" ::: "memory")
; #define PG8_BAR __builtin_amdgcn_s_barrier()
; #define PG8_SCHED __builtin_amdgcn_sched_barrier(0)
; template <bool F16, class Sched, class Epi>
; __device__ __forceinline__ void gemm_phase(LAS unsigned char* lds, const Gemm g, const Sched& S, const Epi& E, int wave_s) {
;     ...
;             PG8_WAIT_V(8); PG8_WAIT_L(0); PG8_BAR; PG8_MMA(1, 0, At, B0); PG8_MMA(1, 1, At, B1); PG8_BAR; PG8_SCHED;
;             PG8_LDB(B0, 1, 0); PG8_LDB(B1, 1, 1); PG8_SCHED; PG8_LDA(At, 1, 0); PG8_STAGE(PG8_SA(0, 1), a2 + hstepA, voffA);
;             PG8_WAIT_V(8); PG8_WAIT_L(0); PG8_BAR; PG8_MMA(0, 0, At, B0); PG8_MMA(0, 1, At, B1); PG8_BAR; PG8_SCHED;
	v_mfma_f32_16x16x32_bf16 v[60:63], v[138:141], v[182:185], v[60:63]
	v_mfma_f32_16x16x32_bf16 v[56:59], v[146:149], v[182:185], v[56:59]
	v_mfma_f32_16x16x32_bf16 v[44:47], v[138:141], v[190:193], v[44:47]
	v_mfma_f32_16x16x32_bf16 v[40:43], v[146:149], v[190:193], v[40:43]
	v_mfma_f32_16x16x32_bf16 v[28:31], v[138:141], v[212:215], v[28:31]
	v_mfma_f32_16x16x32_bf16 v[24:27], v[146:149], v[212:215], v[24:27]
	v_mfma_f32_16x16x32_bf16 v[12:15], v[138:141], v[220:223], v[12:15]
	v_mfma_f32_16x16x32_bf16 v[8:11], v[146:149], v[220:223], v[8:11]
	v_mfma_f32_16x16x32_bf16 v[60:63], v[142:145], v[186:189], v[60:63]
	v_mfma_f32_16x16x32_bf16 v[56:59], v[150:153], v[186:189], v[56:59]
	v_mfma_f32_16x16x32_bf16 v[44:47], v[142:145], v[208:211], v[44:47]
	v_mfma_f32_16x16x32_bf16 v[40:43], v[150:153], v[208:211], v[40:43]
	v_mfma_f32_16x16x32_bf16 v[28:31], v[142:145], v[216:219], v[28:31]
	v_mfma_f32_16x16x32_bf16 v[24:27], v[150:153], v[216:219], v[24:27]
	v_mfma_f32_16x16x32_bf16 v[12:15], v[142:145], v[224:227], v[12:15]
	v_mfma_f32_16x16x32_bf16 v[8:11], v[150:153], v[224:227], v[8:11]
	v_mfma_f32_16x16x32_bf16 v[52:55], v[154:157], v[182:185], v[52:55]
	v_mfma_f32_16x16x32_bf16 v[48:51], v[170:173], v[182:185], v[48:51]
	v_mfma_f32_16x16x32_bf16 v[36:39], v[154:157], v[190:193], v[36:39]
	v_mfma_f32_16x16x32_bf16 v[32:35], v[170:173], v[190:193], v[32:35]
	v_mfma_f32_16x16x32_bf16 v[20:23], v[154:157], v[212:215], v[20:23]
	v_mfma_f32_16x16x32_bf16 v[16:19], v[170:173], v[212:215], v[16:19]
	v_mfma_f32_16x16x32_bf16 v[4:7], v[154:157], v[220:223], v[4:7]
	v_mfma_f32_16x16x32_bf16 v[0:3], v[170:173], v[220:223], v[0:3]
	v_mfma_f32_16x16x32_bf16 v[52:55], v[166:169], v[186:189], v[52:55]
	v_mfma_f32_16x16x32_bf16 v[48:51], v[178:181], v[186:189], v[48:51]
	v_mfma_f32_16x16x32_bf16 v[36:39], v[166:169], v[208:211], v[36:39]
	v_mfma_f32_16x16x32_bf16 v[32:35], v[178:181], v[208:211], v[32:35]
	v_mfma_f32_16x16x32_bf16 v[20:23], v[166:169], v[216:219], v[20:23]
	v_mfma_f32_16x16x32_bf16 v[16:19], v[178:181], v[216:219], v[16:19]
	v_mfma_f32_16x16x32_bf16 v[4:7], v[166:169], v[224:227], v[4:7]
	v_mfma_f32_16x16x32_bf16 v[0:3], v[178:181], v[224:227], v[0:3]
	s_barrier
	s_setprio 0
	s_add_i32 s71, 0, 0x18000
	s_add_i32 s72, 0, 0x1c000
	v_add_u32_e32 v150, s71, v162
	v_add_u32_e32 v160, s72, v162
	ds_read_b128 v[138:141], v150
	ds_read_b128 v[142:145], v150 offset:1024
	ds_read_b128 v[146:149], v150 offset:2048
	ds_read_b128 v[150:153], v150 offset:3072
	ds_read_b128 v[154:157], v160
	ds_read_b128 v[166:169], v160 offset:1024
	ds_read_b128 v[170:173], v160 offset:2048
	ds_read_b128 v[178:181], v160 offset:3072
	s_mov_b32 m0, s53
	ds_read_b128 v[182:185], v164 offset:32768
	ds_read_b128 v[186:189], v164 offset:33792
	ds_read_b128 v[190:193], v164 offset:34816
	ds_read_b128 v[208:211], v164 offset:35840
	ds_read_b128 v[212:215], v164 offset:36864
	ds_read_b128 v[216:219], v164 offset:37888
	ds_read_b128 v[220:223], v164 offset:38912
	ds_read_b128 v[224:227], v164 offset:39936
	global_load_lds_dwordx4 v132, s[38:39]
	s_mov_b32 m0, s58
	s_nop 0
	global_load_lds_dwordx4 v130, s[38:39]
	s_waitcnt vmcnt(8)
	s_waitcnt lgkmcnt(0)
	s_setprio 1
	s_barrier
	v_mfma_f32_16x16x32_bf16 v[124:127], v[138:141], v[182:185], v[124:127]
	v_mfma_f32_16x16x32_bf16 v[120:123], v[146:149], v[182:185], v[120:123]
	v_mfma_f32_16x16x32_bf16 v[108:111], v[138:141], v[190:193], v[108:111]
	v_mfma_f32_16x16x32_bf16 v[104:107], v[146:149], v[190:193], v[104:107]
	v_mfma_f32_16x16x32_bf16 v[92:95], v[138:141], v[212:215], v[92:95]
	v_mfma_f32_16x16x32_bf16 v[88:91], v[146:149], v[212:215], v[88:91]
	v_mfma_f32_16x16x32_bf16 v[76:79], v[138:141], v[220:223], v[76:79]
	v_mfma_f32_16x16x32_bf16 v[72:75], v[146:149], v[220:223], v[72:75]
	v_mfma_f32_16x16x32_bf16 v[124:127], v[142:145], v[186:189], v[124:127]
	v_mfma_f32_16x16x32_bf16 v[120:123], v[150:153], v[186:189], v[120:123]
	v_mfma_f32_16x16x32_bf16 v[108:111], v[142:145], v[208:211], v[108:111]
	v_mfma_f32_16x16x32_bf16 v[104:107], v[150:153], v[208:211], v[104:107]
	v_mfma_f32_16x16x32_bf16 v[92:95], v[142:145], v[216:219], v[92:95]
	v_mfma_f32_16x16x32_bf16 v[88:91], v[150:153], v[216:219], v[88:91]
	v_mfma_f32_16x16x32_bf16 v[76:79], v[142:145], v[224:227], v[76:79]
	v_mfma_f32_16x16x32_bf16 v[72:75], v[150:153], v[224:227], v[72:75]
	v_mfma_f32_16x16x32_bf16 v[116:119], v[154:157], v[182:185], v[116:119]
	v_mfma_f32_16x16x32_bf16 v[112:115], v[170:173], v[182:185], v[112:115]
	v_mfma_f32_16x16x32_bf16 v[100:103], v[154:157], v[190:193], v[100:103]
	v_mfma_f32_16x16x32_bf16 v[96:99], v[170:173], v[190:193], v[96:99]
	v_mfma_f32_16x16x32_bf16 v[84:87], v[154:157], v[212:215], v[84:87]
	v_mfma_f32_16x16x32_bf16 v[80:83], v[170:173], v[212:215], v[80:83]
	v_mfma_f32_16x16x32_bf16 v[68:71], v[154:157], v[220:223], v[68:71]
	v_mfma_f32_16x16x32_bf16 v[64:67], v[170:173], v[220:223], v[64:67]
	v_mfma_f32_16x16x32_bf16 v[116:119], v[166:169], v[186:189], v[116:119]
	v_mfma_f32_16x16x32_bf16 v[112:115], v[178:181], v[186:189], v[112:115]
	v_mfma_f32_16x16x32_bf16 v[100:103], v[166:169], v[208:211], v[100:103]
	v_mfma_f32_16x16x32_bf16 v[96:99], v[178:181], v[208:211], v[96:99]
	v_mfma_f32_16x16x32_bf16 v[84:87], v[166:169], v[216:219], v[84:87]
	v_mfma_f32_16x16x32_bf16 v[80:83], v[178:181], v[216:219], v[80:83]
	v_mfma_f32_16x16x32_bf16 v[68:71], v[166:169], v[224:227], v[68:71]
	v_mfma_f32_16x16x32_bf16 v[64:67], v[178:181], v[224:227], v[64:67]
	s_barrier
; #define PG8_STAGE(bufoff, gbase, voff) do { _Pragma("unroll") for (int _i = 0; _i < 2; ++_i) \
;         __builtin_amdgcn_global_load_lds((const unsigned*)((const char*)(gbase) + (voff)[_i]), (LAS unsigned*)(lds + (bufoff) + ldsw + _i * 8192), 16, 0, 0); } while (0)
; #define PG8_LDA(dst, b, h) do { _Pragma("unroll") for (int m = 0; m < 4; ++m) _Pragma("unroll") for (int k = 0; k < 2; ++k) dst[m][k] = *(const LAS bf16x8*)(lds + PG8_SA(b, h) + aoff + m * 2048 + k * 1024); } while (0)
; #define PG8_WAIT_V(n) asm volatile("s_waitcnt vmcnt(" #n ")" ::: "memory")
; #define PG8_WAIT_L(n) asm volatile("s_waitcnt lgkmcnt(" #n ")" ::: "memory")
; #define PG8_BAR __builtin_amdgcn_s_barrier()
; #define PG8_SCHED __builtin_amdgcn_sched_barrier(0)
; template <bool F16, class Sched, class Epi>
; __device__ __forceinline__ void gemm_phase(LAS unsigned char* lds, const Gemm g, const Sched& S, const Epi& E, int wave_s) {
;     ...
;             PG8_LDA(At, 1, 1); PG8_STAGE(PG8_SB(1, 0), b3, voffB); PG8_STAGE(PG8_SB(1, 1), b3 + hstepB, voffB); PG8_STAGE(PG8_SA(1, 0), a3, voffA);
;             PG8_WAIT_V(8); PG8_WAIT_L(0); PG8_BAR; PG8_MMA(1, 0, At, B0); PG8_MMA(1, 1, At, B1); PG8_BAR; PG8_SCHED;
;         }
	s_setprio 0
	s_add_i32 s38, s71, s46
	v_lshl_add_u64 v[158:159], v[158:159], 0, s[54:55]
	s_mov_b32 m0, s38
	ds_read_b128 v[182:185], v164 offset:49152
	ds_read_b128 v[186:189], v164 offset:50176
	ds_read_b128 v[190:193], v164 offset:51200
	ds_read_b128 v[208:211], v164 offset:52224
	ds_read_b128 v[212:215], v164 offset:53248
	ds_read_b128 v[216:219], v164 offset:54272
	ds_read_b128 v[220:223], v164 offset:55296
	ds_read_b128 v[224:227], v164 offset:56320
	global_load_lds_dwordx4 v[158:159], off
	s_add_i32 m0, s38, 0x2000
	s_add_u32 s4, s4, 0x80080
	v_lshl_add_u64 v[158:159], v[174:175], 0, s[54:55]
	s_addc_u32 s5, s5, 0
	s_add_i32 s38, s72, s46
	global_load_lds_dwordx4 v[158:159], off
	v_lshl_add_u64 v[158:159], s[4:5], 0, v[176:177]
	s_mov_b32 m0, s38
	s_nop 0
	global_load_lds_dwordx4 v[158:159], off
	v_lshl_add_u64 v[158:159], s[4:5], 0, v[128:129]
	s_add_i32 m0, s38, 0x2000
	s_nop 0
	global_load_lds_dwordx4 v[158:159], off
	v_lshl_add_u64 v[158:159], v[194:195], 0, s[54:55]
	s_mov_b32 m0, s59
	s_nop 0
	global_load_lds_dwordx4 v[158:159], off
	v_lshl_add_u64 v[158:159], v[198:199], 0, s[54:55]
	s_mov_b32 m0, s60
	s_nop 0
	global_load_lds_dwordx4 v[158:159], off
	s_waitcnt vmcnt(8)
	s_waitcnt lgkmcnt(0)
	s_setprio 1
	s_barrier
	v_mfma_f32_16x16x32_bf16 v[60:63], v[138:141], v[182:185], v[60:63]
	v_mfma_f32_16x16x32_bf16 v[56:59], v[146:149], v[182:185], v[56:59]
	v_mfma_f32_16x16x32_bf16 v[44:47], v[138:141], v[190:193], v[44:47]
	v_mfma_f32_16x16x32_bf16 v[40:43], v[146:149], v[190:193], v[40:43]
	v_mfma_f32_16x16x32_bf16 v[28:31], v[138:141], v[212:215], v[28:31]
	v_mfma_f32_16x16x32_bf16 v[24:27], v[146:149], v[212:215], v[24:27]
	v_mfma_f32_16x16x32_bf16 v[12:15], v[138:141], v[220:223], v[12:15]
	v_mfma_f32_16x16x32_bf16 v[8:11], v[146:149], v[220:223], v[8:11]
	v_mfma_f32_16x16x32_bf16 v[60:63], v[142:145], v[186:189], v[60:63]
	v_mfma_f32_16x16x32_bf16 v[56:59], v[150:153], v[186:189], v[56:59]
	v_mfma_f32_16x16x32_bf16 v[44:47], v[142:145], v[208:211], v[44:47]
	v_mfma_f32_16x16x32_bf16 v[40:43], v[150:153], v[208:211], v[40:43]
	v_mfma_f32_16x16x32_bf16 v[28:31], v[142:145], v[216:219], v[28:31]
	v_mfma_f32_16x16x32_bf16 v[24:27], v[150:153], v[216:219], v[24:27]
	v_mfma_f32_16x16x32_bf16 v[12:15], v[142:145], v[224:227], v[12:15]
	v_mfma_f32_16x16x32_bf16 v[8:11], v[150:153], v[224:227], v[8:11]
	v_mfma_f32_16x16x32_bf16 v[52:55], v[154:157], v[182:185], v[52:55]
	v_mfma_f32_16x16x32_bf16 v[48:51], v[170:173], v[182:185], v[48:51]
	v_mfma_f32_16x16x32_bf16 v[36:39], v[154:157], v[190:193], v[36:39]
	v_mfma_f32_16x16x32_bf16 v[32:35], v[170:173], v[190:193], v[32:35]
	v_mfma_f32_16x16x32_bf16 v[20:23], v[154:157], v[212:215], v[20:23]
	v_mfma_f32_16x16x32_bf16 v[16:19], v[170:173], v[212:215], v[16:19]
	v_mfma_f32_16x16x32_bf16 v[4:7], v[154:157], v[220:223], v[4:7]
	v_mfma_f32_16x16x32_bf16 v[0:3], v[170:173], v[220:223], v[0:3]
	v_mfma_f32_16x16x32_bf16 v[52:55], v[166:169], v[186:189], v[52:55]
	v_mfma_f32_16x16x32_bf16 v[48:51], v[178:181], v[186:189], v[48:51]
	v_mfma_f32_16x16x32_bf16 v[36:39], v[166:169], v[208:211], v[36:39]
	v_mfma_f32_16x16x32_bf16 v[32:35], v[178:181], v[208:211], v[32:35]
	v_mfma_f32_16x16x32_bf16 v[20:23], v[166:169], v[216:219], v[20:23]
	v_mfma_f32_16x16x32_bf16 v[16:19], v[178:181], v[216:219], v[16:19]
	v_mfma_f32_16x16x32_bf16 v[4:7], v[166:169], v[224:227], v[4:7]
	v_mfma_f32_16x16x32_bf16 v[0:3], v[178:181], v[224:227], v[0:3]
	s_barrier
	s_setprio 0
	s_add_i32 s70, s70, 2
	s_add_u32 s2, s2, 0x100
	s_addc_u32 s3, s3, 0
	s_add_u32 s68, s68, 0x100
	s_addc_u32 s69, s69, 0
	s_cmp_gt_u32 s70, 29
	s_cbranch_scc0 .LBB0_304
	s_and_b64 vcc, exec, s[28:29]
	s_cbranch_vccz .LBB0_307
	s_barrier

; #define PG8_STAGE(bufoff, gbase, voff) do { _Pragma("unroll") for (int _i = 0; _i < 2; ++_i) \
;         __builtin_amdgcn_global_load_lds((const unsigned*)((const char*)(gbase) + (voff)[_i]), (LAS unsigned*)(lds + (bufoff) + ldsw + _i * 8192), 16, 0, 0); } while (0)
; #define PG8_LDA(dst, b, h) do { _Pragma("unroll") for (int m = 0; m < 4; ++m) _Pragma("unroll") for (int k = 0; k < 2; ++k) dst[m][k] = *(const LAS bf16x8*)(lds + PG8_SA(b, h) + aoff + m * 2048 + k * 1024); } while (0)
; #define PG8_LDB(dst, b, h) do { _Pragma("unroll") for (int n = 0; n < 2; ++n) _Pragma("unroll") for (int k = 0; k < 2; ++k) dst[n][k] = *(const LAS bf16x8*)(lds + PG8_SB(b, h) + boff + n * 2048 + k * 1024); } while (0)
; #define PG8_WAIT_V(n) asm volatile("s_waitcnt vmcnt(" #n ")" ::: "memory")
; #define PG8_WAIT_L(n) asm volatile("s_waitcnt lgkmcnt(" #n ")" ::: "memory")
; #define PG8_BAR __builtin_amdgcn_s_barrier()
; #define PG8_SCHED __builtin_amdgcn_sched_barrier(0)
; template <bool F16, class Sched, class Epi>
; __device__ __forceinline__ void gemm_phase(LAS unsigned char* lds, const Gemm g, const Sched& S, const Epi& E, int wave_s) {
;     ...
;         for (int t = 0; t < nt; t += 2) {
;             const bool last = (t == nt - 2);
;             const char* a1 = cA + (size_t)(t + 1) * kstep;
;             const char* a2 = last ? nA : cA + (size_t)(t + 2) * kstep; const char* b2 = last ? nB : cB + (size_t)(t + 2) * kstep;
;             const char* a3 = a2 + kstep; const char* b3 = b2 + kstep;
;             PG8_LDB(B0, 0, 0); PG8_LDB(B1, 0, 1); PG8_SCHED; PG8_LDA(At, 0, 0); PG8_STAGE(PG8_SA(1, 1), a1 + hstepA, voffA);
;             PG8_WAIT_V(8); PG8_WAIT_L(0); PG8_BAR; PG8_MMA(0, 0, At, B0); PG8_MMA(0, 1, At, B1); PG8_BAR; PG8_SCHED;
;             PG8_LDA(At, 0, 1); PG8_STAGE(PG8_SB(0, 0), b2, voffB); PG8_STAGE(PG8_SB(0, 1), b2 + hstepB, voffB); PG8_STAGE(PG8_SA(0, 0), a2, voffA);
;             PG8_WAIT_V(8); PG8_WAIT_L(0); PG8_BAR; PG8_MMA(1, 0, At, B0); PG8_MMA(1, 1, At, B1); PG8_BAR; PG8_SCHED;
.LBB0_358:
	s_add_i32 s65, 0, 0x10000
	s_add_i32 s70, 0, 0x14000
	v_add_u32_e32 v150, s65, v163
	v_add_u32_e32 v158, s70, v163
	ds_read_b128 v[138:141], v150
	ds_read_b128 v[142:145], v150 offset:1024
	ds_read_b128 v[146:149], v150 offset:2048
	ds_read_b128 v[150:153], v150 offset:3072
	ds_read_b128 v[154:157], v158
	ds_read_b128 v[168:171], v158 offset:1024
	ds_read_b128 v[172:175], v158 offset:2048
	ds_read_b128 v[178:181], v158 offset:3072
	s_add_i32 m0, s44, 0xc000
	ds_read_b128 v[182:185], v167
	ds_read_b128 v[186:189], v167 offset:1024
	ds_read_b128 v[190:193], v167 offset:2048
	ds_read_b128 v[208:211], v167 offset:3072
	ds_read_b128 v[212:215], v167 offset:4096
	ds_read_b128 v[216:219], v167 offset:5120
	ds_read_b128 v[220:223], v167 offset:6144
	ds_read_b128 v[224:227], v167 offset:7168
	global_load_lds_dwordx4 v134, s[2:3]
	s_add_i32 m0, s44, 0xe000
	s_nop 0
	global_load_lds_dwordx4 v136, s[2:3]
	s_waitcnt vmcnt(8)
	s_waitcnt lgkmcnt(0)
	s_setprio 1
	s_barrier
	v_mfma_f32_16x16x32_bf16 v[124:127], v[138:141], v[182:185], v[124:127]
	v_mfma_f32_16x16x32_bf16 v[120:123], v[146:149], v[182:185], v[120:123]
	v_mfma_f32_16x16x32_bf16 v[108:111], v[138:141], v[190:193], v[108:111]
	v_mfma_f32_16x16x32_bf16 v[104:107], v[146:149], v[190:193], v[104:107]
	v_mfma_f32_16x16x32_bf16 v[92:95], v[138:141], v[212:215], v[92:95]
	v_mfma_f32_16x16x32_bf16 v[88:91], v[146:149], v[212:215], v[88:91]
	v_mfma_f32_16x16x32_bf16 v[76:79], v[138:141], v[220:223], v[76:79]
	v_mfma_f32_16x16x32_bf16 v[72:75], v[146:149], v[220:223], v[72:75]
	v_mfma_f32_16x16x32_bf16 v[124:127], v[142:145], v[186:189], v[124:127]
	v_mfma_f32_16x16x32_bf16 v[120:123], v[150:153], v[186:189], v[120:123]
	v_mfma_f32_16x16x32_bf16 v[108:111], v[142:145], v[208:211], v[108:111]
	v_mfma_f32_16x16x32_bf16 v[104:107], v[150:153], v[208:211], v[104:107]
	v_mfma_f32_16x16x32_bf16 v[92:95], v[142:145], v[216:219], v[92:95]
	v_mfma_f32_16x16x32_bf16 v[88:91], v[150:153], v[216:219], v[88:91]
	v_mfma_f32_16x16x32_bf16 v[76:79], v[142:145], v[224:227], v[76:79]
	v_mfma_f32_16x16x32_bf16 v[72:75], v[150:153], v[224:227], v[72:75]
	v_mfma_f32_16x16x32_bf16 v[116:119], v[154:157], v[182:185], v[116:119]
	v_mfma_f32_16x16x32_bf16 v[112:115], v[172:175], v[182:185], v[112:115]
	v_mfma_f32_16x16x32_bf16 v[100:103], v[154:157], v[190:193], v[100:103]
	v_mfma_f32_16x16x32_bf16 v[96:99], v[172:175], v[190:193], v[96:99]
	v_mfma_f32_16x16x32_bf16 v[84:87], v[154:157], v[212:215], v[84:87]
	v_mfma_f32_16x16x32_bf16 v[80:83], v[172:175], v[212:215], v[80:83]
	v_mfma_f32_16x16x32_bf16 v[68:71], v[154:157], v[220:223], v[68:71]
	v_mfma_f32_16x16x32_bf16 v[64:67], v[172:175], v[220:223], v[64:67]
	v_mfma_f32_16x16x32_bf16 v[116:119], v[168:171], v[186:189], v[116:119]
	v_mfma_f32_16x16x32_bf16 v[112:115], v[178:181], v[186:189], v[112:115]
	v_mfma_f32_16x16x32_bf16 v[100:103], v[168:171], v[208:211], v[100:103]
	v_mfma_f32_16x16x32_bf16 v[96:99], v[178:181], v[208:211], v[96:99]
	v_mfma_f32_16x16x32_bf16 v[84:87], v[168:171], v[216:219], v[84:87]
	v_mfma_f32_16x16x32_bf16 v[80:83], v[178:181], v[216:219], v[80:83]
	v_mfma_f32_16x16x32_bf16 v[68:71], v[168:171], v[224:227], v[68:71]
	v_mfma_f32_16x16x32_bf16 v[64:67], v[178:181], v[224:227], v[64:67]
	s_barrier
	s_setprio 0
	s_add_u32 s30, s2, 0xfff80080
	s_addc_u32 s31, s3, -1
	s_cmp_eq_u32 s64, 28
	s_cselect_b32 s35, s58, s31
	s_cselect_b32 s34, s59, s30
	s_cselect_b32 s31, s60, s63
	s_cselect_b32 s30, s61, s62
	s_add_i32 s65, s65, s42
	v_lshl_add_u64 v[158:159], s[30:31], 0, v[176:177]
	s_mov_b32 m0, s65
	ds_read_b128 v[182:185], v167 offset:16384
	ds_read_b128 v[186:189], v167 offset:17408
	ds_read_b128 v[190:193], v167 offset:18432
	ds_read_b128 v[208:211], v167 offset:19456
	ds_read_b128 v[212:215], v167 offset:20480
	ds_read_b128 v[216:219], v167 offset:21504
	ds_read_b128 v[220:223], v167 offset:22528
	ds_read_b128 v[224:227], v167 offset:23552
	global_load_lds_dwordx4 v[158:159], off
	s_add_i32 m0, s65, 0x2000
	s_add_u32 s68, s30, 0x80000
	v_lshl_add_u64 v[194:195], s[30:31], 0, v[128:129]
	s_addc_u32 s69, s31, 0
	s_add_i32 s65, s70, s42
	global_load_lds_dwordx4 v[194:195], off
	v_lshl_add_u64 v[198:199], s[68:69], 0, v[176:177]
	s_mov_b32 m0, s65
	v_lshl_add_u64 v[200:201], s[34:35], 0, v[130:131]
	global_load_lds_dwordx4 v[198:199], off
	v_lshl_add_u64 v[198:199], s[68:69], 0, v[128:129]
	s_add_i32 m0, s65, 0x2000
	s_nop 0
	global_load_lds_dwordx4 v[198:199], off
	v_lshl_add_u64 v[198:199], s[34:35], 0, v[132:133]
	s_mov_b32 m0, s44
	s_nop 0
	global_load_lds_dwordx4 v[198:199], off
	s_mov_b32 m0, s46
	s_nop 0
	global_load_lds_dwordx4 v[200:201], off
	s_add_u32 s34, s34, 0x80000
	s_addc_u32 s35, s35, 0
	s_waitcnt vmcnt(8)
	s_waitcnt lgkmcnt(0)
	s_setprio 1
	s_barrier
; #define PG8_STAGE(bufoff, gbase, voff) do { _Pragma("unroll") for (int _i = 0; _i < 2; ++_i) \
;         __builtin_amdgcn_global_load_lds((const unsigned*)((const char*)(gbase) + (voff)[_i]), (LAS unsigned*)(lds + (bufoff) + ldsw + _i * 8192), 16, 0, 0); } while (0)
; #define PG8_LDA(dst, b, h) do { _Pragma("unroll") for (int m = 0; m < 4; ++m) _Pragma("unroll") for (int k = 0; k < 2; ++k) dst[m][k] = *(const LAS bf16x8*)(lds + PG8_SA(b, h) + aoff + m * 2048 + k * 1024); } while (0)
; #define PG8_LDB(dst, b, h) do { _Pragma("unroll") for (int n = 0; n < 2; ++n) _Pragma("unroll") for (int k = 0; k < 2; ++k) dst[n][k] = *(const LAS bf16x8*)(lds + PG8_SB(b, h) + boff + n * 2048 + k * 1024); } while (0)
; #define PG8_WAIT_V(n) asm volatile("s_waitcnt vmcnt(" #n ")" ::: "memory")
; #define PG8_WAIT_L(n) asm volatile("s_waitcnt lgkmcnt(" #n ")" ::: "memory")
; #define PG8_BAR __builtin_amdgcn_s_barrier()
; #define PG8_SCHED __builtin_amdgcn_sched_barrier(0)
; template <bool F16, class Sched, class Epi>
; __device__ __forceinline__ void gemm_phase(LAS unsigned char* lds, const Gemm g, const Sched& S, const Epi& E, int wave_s) {
;     ...
;             PG8_WAIT_V(8); PG8_WAIT_L(0); PG8_BAR; PG8_MMA(1, 0, At, B0); PG8_MMA(1, 1, At, B1); PG8_BAR; PG8_SCHED;
;             PG8_LDB(B0, 1, 0); PG8_LDB(B1, 1, 1); PG8_SCHED; PG8_LDA(At, 1, 0); PG8_STAGE(PG8_SA(0, 1), a2 + hstepA, voffA);
;             PG8_WAIT_V(8); PG8_WAIT_L(0); PG8_BAR; PG8_MMA(0, 0, At, B0); PG8_MMA(0, 1, At, B1); PG8_BAR; PG8_SCHED;
	v_mfma_f32_16x16x32_bf16 v[60:63], v[138:141], v[182:185], v[60:63]
	v_mfma_f32_16x16x32_bf16 v[56:59], v[146:149], v[182:185], v[56:59]
	v_mfma_f32_16x16x32_bf16 v[48:51], v[138:141], v[190:193], v[48:51]
	v_mfma_f32_16x16x32_bf16 v[40:43], v[146:149], v[190:193], v[40:43]
	v_mfma_f32_16x16x32_bf16 v[32:35], v[138:141], v[212:215], v[32:35]
	v_mfma_f32_16x16x32_bf16 v[24:27], v[146:149], v[212:215], v[24:27]
	v_mfma_f32_16x16x32_bf16 v[16:19], v[138:141], v[220:223], v[16:19]
	v_mfma_f32_16x16x32_bf16 v[8:11], v[146:149], v[220:223], v[8:11]
	v_mfma_f32_16x16x32_bf16 v[60:63], v[142:145], v[186:189], v[60:63]
	v_mfma_f32_16x16x32_bf16 v[56:59], v[150:153], v[186:189], v[56:59]
	v_mfma_f32_16x16x32_bf16 v[48:51], v[142:145], v[208:211], v[48:51]
	v_mfma_f32_16x16x32_bf16 v[40:43], v[150:153], v[208:211], v[40:43]
	v_mfma_f32_16x16x32_bf16 v[32:35], v[142:145], v[216:219], v[32:35]
	v_mfma_f32_16x16x32_bf16 v[24:27], v[150:153], v[216:219], v[24:27]
	v_mfma_f32_16x16x32_bf16 v[16:19], v[142:145], v[224:227], v[16:19]
	v_mfma_f32_16x16x32_bf16 v[8:11], v[150:153], v[224:227], v[8:11]
	v_mfma_f32_16x16x32_bf16 v[52:55], v[154:157], v[182:185], v[52:55]
	v_mfma_f32_16x16x32_bf16 v[44:47], v[172:175], v[182:185], v[44:47]
	v_mfma_f32_16x16x32_bf16 v[36:39], v[154:157], v[190:193], v[36:39]
	v_mfma_f32_16x16x32_bf16 v[28:31], v[172:175], v[190:193], v[28:31]
	v_mfma_f32_16x16x32_bf16 v[20:23], v[154:157], v[212:215], v[20:23]
	v_mfma_f32_16x16x32_bf16 v[12:15], v[172:175], v[212:215], v[12:15]
	v_mfma_f32_16x16x32_bf16 v[4:7], v[154:157], v[220:223], v[4:7]
	v_mfma_f32_16x16x32_bf16 v[0:3], v[172:175], v[220:223], v[0:3]
	v_mfma_f32_16x16x32_bf16 v[52:55], v[168:171], v[186:189], v[52:55]
	v_mfma_f32_16x16x32_bf16 v[44:47], v[178:181], v[186:189], v[44:47]
	v_mfma_f32_16x16x32_bf16 v[36:39], v[168:171], v[208:211], v[36:39]
	v_mfma_f32_16x16x32_bf16 v[28:31], v[178:181], v[208:211], v[28:31]
	v_mfma_f32_16x16x32_bf16 v[20:23], v[168:171], v[216:219], v[20:23]
	v_mfma_f32_16x16x32_bf16 v[12:15], v[178:181], v[216:219], v[12:15]
	v_mfma_f32_16x16x32_bf16 v[4:7], v[168:171], v[224:227], v[4:7]
	v_mfma_f32_16x16x32_bf16 v[0:3], v[178:181], v[224:227], v[0:3]
	s_barrier
	s_setprio 0
	s_add_i32 s65, 0, 0x18000
	s_add_i32 s68, 0, 0x1c000
	v_add_u32_e32 v150, s65, v163
	v_add_u32_e32 v160, s68, v163
	ds_read_b128 v[138:141], v150
	ds_read_b128 v[142:145], v150 offset:1024
	ds_read_b128 v[146:149], v150 offset:2048
	ds_read_b128 v[150:153], v150 offset:3072
	ds_read_b128 v[154:157], v160
	ds_read_b128 v[168:171], v160 offset:1024
	ds_read_b128 v[172:175], v160 offset:2048
	ds_read_b128 v[178:181], v160 offset:3072
	s_mov_b32 m0, s47
	ds_read_b128 v[182:185], v167 offset:32768
	ds_read_b128 v[186:189], v167 offset:33792
	ds_read_b128 v[190:193], v167 offset:34816
	ds_read_b128 v[208:211], v167 offset:35840
	ds_read_b128 v[212:215], v167 offset:36864
	ds_read_b128 v[216:219], v167 offset:37888
	ds_read_b128 v[220:223], v167 offset:38912
	ds_read_b128 v[224:227], v167 offset:39936
	global_load_lds_dwordx4 v132, s[34:35]
	s_mov_b32 m0, s48
	s_nop 0
	global_load_lds_dwordx4 v130, s[34:35]
	s_waitcnt vmcnt(8)
	s_waitcnt lgkmcnt(0)
	s_setprio 1
	s_barrier
	v_mfma_f32_16x16x32_bf16 v[124:127], v[138:141], v[182:185], v[124:127]
	v_mfma_f32_16x16x32_bf16 v[120:123], v[146:149], v[182:185], v[120:123]
	v_mfma_f32_16x16x32_bf16 v[108:111], v[138:141], v[190:193], v[108:111]
	v_mfma_f32_16x16x32_bf16 v[104:107], v[146:149], v[190:193], v[104:107]
	v_mfma_f32_16x16x32_bf16 v[92:95], v[138:141], v[212:215], v[92:95]
	v_mfma_f32_16x16x32_bf16 v[88:91], v[146:149], v[212:215], v[88:91]
	v_mfma_f32_16x16x32_bf16 v[76:79], v[138:141], v[220:223], v[76:79]
	v_mfma_f32_16x16x32_bf16 v[72:75], v[146:149], v[220:223], v[72:75]
	v_mfma_f32_16x16x32_bf16 v[124:127], v[142:145], v[186:189], v[124:127]
	v_mfma_f32_16x16x32_bf16 v[120:123], v[150:153], v[186:189], v[120:123]
	v_mfma_f32_16x16x32_bf16 v[108:111], v[142:145], v[208:211], v[108:111]
	v_mfma_f32_16x16x32_bf16 v[104:107], v[150:153], v[208:211], v[104:107]
	v_mfma_f32_16x16x32_bf16 v[92:95], v[142:145], v[216:219], v[92:95]
	v_mfma_f32_16x16x32_bf16 v[88:91], v[150:153], v[216:219], v[88:91]
	v_mfma_f32_16x16x32_bf16 v[76:79], v[142:145], v[224:227], v[76:79]
	v_mfma_f32_16x16x32_bf16 v[72:75], v[150:153], v[224:227], v[72:75]
	v_mfma_f32_16x16x32_bf16 v[116:119], v[154:157], v[182:185], v[116:119]
	v_mfma_f32_16x16x32_bf16 v[112:115], v[172:175], v[182:185], v[112:115]
	v_mfma_f32_16x16x32_bf16 v[100:103], v[154:157], v[190:193], v[100:103]
	v_mfma_f32_16x16x32_bf16 v[96:99], v[172:175], v[190:193], v[96:99]
	v_mfma_f32_16x16x32_bf16 v[84:87], v[154:157], v[212:215], v[84:87]
	v_mfma_f32_16x16x32_bf16 v[80:83], v[172:175], v[212:215], v[80:83]
	v_mfma_f32_16x16x32_bf16 v[68:71], v[154:157], v[220:223], v[68:71]
	v_mfma_f32_16x16x32_bf16 v[64:67], v[172:175], v[220:223], v[64:67]
	v_mfma_f32_16x16x32_bf16 v[116:119], v[168:171], v[186:189], v[116:119]
	v_mfma_f32_16x16x32_bf16 v[112:115], v[178:181], v[186:189], v[112:115]
	v_mfma_f32_16x16x32_bf16 v[100:103], v[168:171], v[208:211], v[100:103]
	v_mfma_f32_16x16x32_bf16 v[96:99], v[178:181], v[208:211], v[96:99]
	v_mfma_f32_16x16x32_bf16 v[84:87], v[168:171], v[216:219], v[84:87]
	v_mfma_f32_16x16x32_bf16 v[80:83], v[178:181], v[216:219], v[80:83]
	v_mfma_f32_16x16x32_bf16 v[68:71], v[168:171], v[224:227], v[68:71]
	v_mfma_f32_16x16x32_bf16 v[64:67], v[178:181], v[224:227], v[64:67]
	s_barrier
; #define PG8_STAGE(bufoff, gbase, voff) do { _Pragma("unroll") for (int _i = 0; _i < 2; ++_i) \
;         __builtin_amdgcn_global_load_lds((const unsigned*)((const char*)(gbase) + (voff)[_i]), (LAS unsigned*)(lds + (bufoff) + ldsw + _i * 8192), 16, 0, 0); } while (0)
; #define PG8_LDA(dst, b, h) do { _Pragma("unroll") for (int m = 0; m < 4; ++m) _Pragma("unroll") for (int k = 0; k < 2; ++k) dst[m][k] = *(const LAS bf16x8*)(lds + PG8_SA(b, h) + aoff + m * 2048 + k * 1024); } while (0)
; #define PG8_WAIT_V(n) asm volatile("s_waitcnt vmcnt(" #n ")" ::: "memory")
; #define PG8_WAIT_L(n) asm volatile("s_waitcnt lgkmcnt(" #n ")" ::: "memory")
; #define PG8_BAR __builtin_amdgcn_s_barrier()
; #define PG8_SCHED __builtin_amdgcn_sched_barrier(0)
; template <bool F16, class Sched, class Epi>
; __device__ __forceinline__ void gemm_phase(LAS unsigned char* lds, const Gemm g, const Sched& S, const Epi& E, int wave_s) {
;     ...
;             PG8_LDA(At, 1, 1); PG8_STAGE(PG8_SB(1, 0), b3, voffB); PG8_STAGE(PG8_SB(1, 1), b3 + hstepB, voffB); PG8_STAGE(PG8_SA(1, 0), a3, voffA);
;             PG8_WAIT_V(8); PG8_WAIT_L(0); PG8_BAR; PG8_MMA(1, 0, At, B0); PG8_MMA(1, 1, At, B1); PG8_BAR; PG8_SCHED;
;         }
	s_setprio 0
	s_add_i32 s34, s65, s42
	v_lshl_add_u64 v[158:159], v[158:159], 0, s[54:55]
	s_mov_b32 m0, s34
	ds_read_b128 v[182:185], v167 offset:49152
	ds_read_b128 v[186:189], v167 offset:50176
	ds_read_b128 v[190:193], v167 offset:51200
	ds_read_b128 v[208:211], v167 offset:52224
	ds_read_b128 v[212:215], v167 offset:53248
	ds_read_b128 v[216:219], v167 offset:54272
	ds_read_b128 v[220:223], v167 offset:55296
	ds_read_b128 v[224:227], v167 offset:56320
	global_load_lds_dwordx4 v[158:159], off
	s_add_i32 m0, s34, 0x2000
	s_add_u32 s30, s30, 0x80080
	v_lshl_add_u64 v[158:159], v[194:195], 0, s[54:55]
	s_addc_u32 s31, s31, 0
	s_add_i32 s34, s68, s42
	global_load_lds_dwordx4 v[158:159], off
	v_lshl_add_u64 v[158:159], s[30:31], 0, v[176:177]
	s_mov_b32 m0, s34
	s_nop 0
	global_load_lds_dwordx4 v[158:159], off
	v_lshl_add_u64 v[158:159], s[30:31], 0, v[128:129]
	s_add_i32 m0, s34, 0x2000
	s_nop 0
	global_load_lds_dwordx4 v[158:159], off
	v_lshl_add_u64 v[158:159], v[198:199], 0, s[54:55]
	s_mov_b32 m0, s49
	s_nop 0
	global_load_lds_dwordx4 v[158:159], off
	v_lshl_add_u64 v[158:159], v[200:201], 0, s[54:55]
	s_mov_b32 m0, s52
	s_nop 0
	global_load_lds_dwordx4 v[158:159], off
	s_waitcnt vmcnt(8)
	s_waitcnt lgkmcnt(0)
	s_setprio 1
	s_barrier
	v_mfma_f32_16x16x32_bf16 v[60:63], v[138:141], v[182:185], v[60:63]
	v_mfma_f32_16x16x32_bf16 v[56:59], v[146:149], v[182:185], v[56:59]
	v_mfma_f32_16x16x32_bf16 v[48:51], v[138:141], v[190:193], v[48:51]
	v_mfma_f32_16x16x32_bf16 v[40:43], v[146:149], v[190:193], v[40:43]
	v_mfma_f32_16x16x32_bf16 v[32:35], v[138:141], v[212:215], v[32:35]
	v_mfma_f32_16x16x32_bf16 v[24:27], v[146:149], v[212:215], v[24:27]
	v_mfma_f32_16x16x32_bf16 v[16:19], v[138:141], v[220:223], v[16:19]
	v_mfma_f32_16x16x32_bf16 v[8:11], v[146:149], v[220:223], v[8:11]
	v_mfma_f32_16x16x32_bf16 v[60:63], v[142:145], v[186:189], v[60:63]
	v_mfma_f32_16x16x32_bf16 v[56:59], v[150:153], v[186:189], v[56:59]
	v_mfma_f32_16x16x32_bf16 v[48:51], v[142:145], v[208:211], v[48:51]
	v_mfma_f32_16x16x32_bf16 v[40:43], v[150:153], v[208:211], v[40:43]
	v_mfma_f32_16x16x32_bf16 v[32:35], v[142:145], v[216:219], v[32:35]
	v_mfma_f32_16x16x32_bf16 v[24:27], v[150:153], v[216:219], v[24:27]
	v_mfma_f32_16x16x32_bf16 v[16:19], v[142:145], v[224:227], v[16:19]
	v_mfma_f32_16x16x32_bf16 v[8:11], v[150:153], v[224:227], v[8:11]
	v_mfma_f32_16x16x32_bf16 v[52:55], v[154:157], v[182:185], v[52:55]
	v_mfma_f32_16x16x32_bf16 v[44:47], v[172:175], v[182:185], v[44:47]
	v_mfma_f32_16x16x32_bf16 v[36:39], v[154:157], v[190:193], v[36:39]
	v_mfma_f32_16x16x32_bf16 v[28:31], v[172:175], v[190:193], v[28:31]
	v_mfma_f32_16x16x32_bf16 v[20:23], v[154:157], v[212:215], v[20:23]
	v_mfma_f32_16x16x32_bf16 v[12:15], v[172:175], v[212:215], v[12:15]
	v_mfma_f32_16x16x32_bf16 v[4:7], v[154:157], v[220:223], v[4:7]
	v_mfma_f32_16x16x32_bf16 v[0:3], v[172:175], v[220:223], v[0:3]
	v_mfma_f32_16x16x32_bf16 v[52:55], v[168:171], v[186:189], v[52:55]
	v_mfma_f32_16x16x32_bf16 v[44:47], v[178:181], v[186:189], v[44:47]
	v_mfma_f32_16x16x32_bf16 v[36:39], v[168:171], v[208:211], v[36:39]
	v_mfma_f32_16x16x32_bf16 v[28:31], v[178:181], v[208:211], v[28:31]
	v_mfma_f32_16x16x32_bf16 v[20:23], v[168:171], v[216:219], v[20:23]
	v_mfma_f32_16x16x32_bf16 v[12:15], v[178:181], v[216:219], v[12:15]
	v_mfma_f32_16x16x32_bf16 v[4:7], v[168:171], v[224:227], v[4:7]
	v_mfma_f32_16x16x32_bf16 v[0:3], v[178:181], v[224:227], v[0:3]
	s_barrier
	s_setprio 0
	s_add_i32 s64, s64, 2
	s_add_u32 s2, s2, 0x100
	s_addc_u32 s3, s3, 0
	s_add_u32 s62, s62, 0x100
	s_addc_u32 s63, s63, 0
	s_cmp_gt_u32 s64, 29
	s_cbranch_scc0 .LBB0_358
	s_and_b64 vcc, exec, s[26:27]
	s_cbranch_vccz .LBB0_361
	s_barrier

; #define PG8_STAGE(bufoff, gbase, voff) do { _Pragma("unroll") for (int _i = 0; _i < 2; ++_i) \
;         __builtin_amdgcn_global_load_lds((const unsigned*)((const char*)(gbase) + (voff)[_i]), (LAS unsigned*)(lds + (bufoff) + ldsw + _i * 8192), 16, 0, 0); } while (0)
; #define PG8_LDA(dst, b, h) do { _Pragma("unroll") for (int m = 0; m < 4; ++m) _Pragma("unroll") for (int k = 0; k < 2; ++k) dst[m][k] = *(const LAS bf16x8*)(lds + PG8_SA(b, h) + aoff + m * 2048 + k * 1024); } while (0)
; #define PG8_LDB(dst, b, h) do { _Pragma("unroll") for (int n = 0; n < 2; ++n) _Pragma("unroll") for (int k = 0; k < 2; ++k) dst[n][k] = *(const LAS bf16x8*)(lds + PG8_SB(b, h) + boff + n * 2048 + k * 1024); } while (0)
; #define PG8_WAIT_V(n) asm volatile("s_waitcnt vmcnt(" #n ")" ::: "memory")
; #define PG8_WAIT_L(n) asm volatile("s_waitcnt lgkmcnt(" #n ")" ::: "memory")
; #define PG8_BAR __builtin_amdgcn_s_barrier()
; #define PG8_SCHED __builtin_amdgcn_sched_barrier(0)
; template <bool F16, class Sched, class Epi>
; __device__ __forceinline__ void gemm_phase(LAS unsigned char* lds, const Gemm g, const Sched& S, const Epi& E, int wave_s) {
;     ...
;         for (int t = 0; t < nt; t += 2) {
;             const bool last = (t == nt - 2);
;             const char* a1 = cA + (size_t)(t + 1) * kstep;
;             const char* a2 = last ? nA : cA + (size_t)(t + 2) * kstep; const char* b2 = last ? nB : cB + (size_t)(t + 2) * kstep;
;             const char* a3 = a2 + kstep; const char* b3 = b2 + kstep;
;             PG8_LDB(B0, 0, 0); PG8_LDB(B1, 0, 1); PG8_SCHED; PG8_LDA(At, 0, 0); PG8_STAGE(PG8_SA(1, 1), a1 + hstepA, voffA);
;             PG8_WAIT_V(8); PG8_WAIT_L(0); PG8_BAR; PG8_MMA(0, 0, At, B0); PG8_MMA(0, 1, At, B1); PG8_BAR; PG8_SCHED;
;             PG8_LDA(At, 0, 1); PG8_STAGE(PG8_SB(0, 0), b2, voffB); PG8_STAGE(PG8_SB(0, 1), b2 + hstepB, voffB); PG8_STAGE(PG8_SA(0, 0), a2, voffA);
;             PG8_WAIT_V(8); PG8_WAIT_L(0); PG8_BAR; PG8_MMA(1, 0, At, B0); PG8_MMA(1, 1, At, B1); PG8_BAR; PG8_SCHED;
.LBB0_598:
	s_add_i32 s61, 0, 0x10000
	s_add_i32 s64, 0, 0x14000
	v_add_u32_e32 v150, s61, v163
	v_add_u32_e32 v170, s64, v163
	ds_read_b128 v[138:141], v150
	ds_read_b128 v[142:145], v150 offset:1024
	ds_read_b128 v[146:149], v150 offset:2048
	ds_read_b128 v[150:153], v150 offset:3072
	ds_read_b128 v[154:157], v170
	ds_read_b128 v[158:161], v170 offset:1024
	ds_read_b128 v[166:169], v170 offset:2048
	ds_read_b128 v[170:173], v170 offset:3072
	s_add_i32 m0, s43, 0xc000
	ds_read_b128 v[178:181], v165
	ds_read_b128 v[182:185], v165 offset:1024
	ds_read_b128 v[186:189], v165 offset:2048
	ds_read_b128 v[190:193], v165 offset:3072
	ds_read_b128 v[208:211], v165 offset:4096
	ds_read_b128 v[212:215], v165 offset:5120
	ds_read_b128 v[216:219], v165 offset:6144
	ds_read_b128 v[220:223], v165 offset:7168
	global_load_lds_dwordx4 v134, s[26:27]
	s_add_i32 m0, s43, 0xe000
	s_nop 0
	global_load_lds_dwordx4 v136, s[26:27]
	s_waitcnt vmcnt(8)
	s_waitcnt lgkmcnt(0)
	s_setprio 1
	s_barrier
	v_mfma_f32_16x16x32_bf16 v[124:127], v[138:141], v[178:181], v[124:127]
	v_mfma_f32_16x16x32_bf16 v[120:123], v[146:149], v[178:181], v[120:123]
	v_mfma_f32_16x16x32_bf16 v[108:111], v[138:141], v[186:189], v[108:111]
	v_mfma_f32_16x16x32_bf16 v[104:107], v[146:149], v[186:189], v[104:107]
	v_mfma_f32_16x16x32_bf16 v[96:99], v[138:141], v[208:211], v[96:99]
	v_mfma_f32_16x16x32_bf16 v[92:95], v[146:149], v[208:211], v[92:95]
	v_mfma_f32_16x16x32_bf16 v[84:87], v[138:141], v[216:219], v[84:87]
	v_mfma_f32_16x16x32_bf16 v[76:79], v[146:149], v[216:219], v[76:79]
	v_mfma_f32_16x16x32_bf16 v[124:127], v[142:145], v[182:185], v[124:127]
	v_mfma_f32_16x16x32_bf16 v[120:123], v[150:153], v[182:185], v[120:123]
	v_mfma_f32_16x16x32_bf16 v[108:111], v[142:145], v[190:193], v[108:111]
	v_mfma_f32_16x16x32_bf16 v[104:107], v[150:153], v[190:193], v[104:107]
	v_mfma_f32_16x16x32_bf16 v[96:99], v[142:145], v[212:215], v[96:99]
	v_mfma_f32_16x16x32_bf16 v[92:95], v[150:153], v[212:215], v[92:95]
	v_mfma_f32_16x16x32_bf16 v[84:87], v[142:145], v[220:223], v[84:87]
	v_mfma_f32_16x16x32_bf16 v[76:79], v[150:153], v[220:223], v[76:79]
	v_mfma_f32_16x16x32_bf16 v[116:119], v[154:157], v[178:181], v[116:119]
	v_mfma_f32_16x16x32_bf16 v[112:115], v[166:169], v[178:181], v[112:115]
	v_mfma_f32_16x16x32_bf16 v[100:103], v[154:157], v[186:189], v[100:103]
	v_mfma_f32_16x16x32_bf16 v[88:91], v[166:169], v[186:189], v[88:91]
	v_mfma_f32_16x16x32_bf16 v[80:83], v[154:157], v[208:211], v[80:83]
	v_mfma_f32_16x16x32_bf16 v[72:75], v[166:169], v[208:211], v[72:75]
	v_mfma_f32_16x16x32_bf16 v[68:71], v[154:157], v[216:219], v[68:71]
	v_mfma_f32_16x16x32_bf16 v[64:67], v[166:169], v[216:219], v[64:67]
	v_mfma_f32_16x16x32_bf16 v[116:119], v[158:161], v[182:185], v[116:119]
	v_mfma_f32_16x16x32_bf16 v[112:115], v[170:173], v[182:185], v[112:115]
	v_mfma_f32_16x16x32_bf16 v[100:103], v[158:161], v[190:193], v[100:103]
	v_mfma_f32_16x16x32_bf16 v[88:91], v[170:173], v[190:193], v[88:91]
	v_mfma_f32_16x16x32_bf16 v[80:83], v[158:161], v[212:215], v[80:83]
	v_mfma_f32_16x16x32_bf16 v[72:75], v[170:173], v[212:215], v[72:75]
	v_mfma_f32_16x16x32_bf16 v[68:71], v[158:161], v[220:223], v[68:71]
	v_mfma_f32_16x16x32_bf16 v[64:67], v[170:173], v[220:223], v[64:67]
	s_barrier
	s_setprio 0
	s_add_u32 s28, s26, 0xfff80080
	s_addc_u32 s29, s27, -1
	s_cmp_eq_u32 s60, 28
	s_cselect_b32 s31, s49, s29
	s_cselect_b32 s30, s50, s28
	s_cselect_b32 s29, s52, s59
	s_cselect_b32 s28, s53, s58
	s_add_i32 s61, s61, s39
	v_lshl_add_u64 v[174:175], s[28:29], 0, v[176:177]
	s_mov_b32 m0, s61
	ds_read_b128 v[178:181], v165 offset:16384
	ds_read_b128 v[182:185], v165 offset:17408
	ds_read_b128 v[186:189], v165 offset:18432
	ds_read_b128 v[190:193], v165 offset:19456
	ds_read_b128 v[208:211], v165 offset:20480
	ds_read_b128 v[212:215], v165 offset:21504
	ds_read_b128 v[216:219], v165 offset:22528
	ds_read_b128 v[220:223], v165 offset:23552
	global_load_lds_dwordx4 v[174:175], off
	s_add_i32 m0, s61, 0x2000
	s_add_u32 s62, s28, 0x80000
	v_lshl_add_u64 v[194:195], s[28:29], 0, v[128:129]
	s_addc_u32 s63, s29, 0
	s_add_i32 s61, s64, s39
	global_load_lds_dwordx4 v[194:195], off
	v_lshl_add_u64 v[198:199], s[62:63], 0, v[176:177]
	s_mov_b32 m0, s61
	v_lshl_add_u64 v[200:201], s[30:31], 0, v[130:131]
	global_load_lds_dwordx4 v[198:199], off
	v_lshl_add_u64 v[198:199], s[62:63], 0, v[128:129]
	s_add_i32 m0, s61, 0x2000
	s_nop 0
	global_load_lds_dwordx4 v[198:199], off
	v_lshl_add_u64 v[198:199], s[30:31], 0, v[132:133]
	s_mov_b32 m0, s43
	s_nop 0
	global_load_lds_dwordx4 v[198:199], off
	s_mov_b32 m0, s44
	s_nop 0
	global_load_lds_dwordx4 v[200:201], off
	s_add_u32 s30, s30, 0x80000
	s_addc_u32 s31, s31, 0
	s_waitcnt vmcnt(8)
	s_waitcnt lgkmcnt(0)
	s_setprio 1
	s_barrier
; #define PG8_STAGE(bufoff, gbase, voff) do { _Pragma("unroll") for (int _i = 0; _i < 2; ++_i) \
;         __builtin_amdgcn_global_load_lds((const unsigned*)((const char*)(gbase) + (voff)[_i]), (LAS unsigned*)(lds + (bufoff) + ldsw + _i * 8192), 16, 0, 0); } while (0)
; #define PG8_LDA(dst, b, h) do { _Pragma("unroll") for (int m = 0; m < 4; ++m) _Pragma("unroll") for (int k = 0; k < 2; ++k) dst[m][k] = *(const LAS bf16x8*)(lds + PG8_SA(b, h) + aoff + m * 2048 + k * 1024); } while (0)
; #define PG8_LDB(dst, b, h) do { _Pragma("unroll") for (int n = 0; n < 2; ++n) _Pragma("unroll") for (int k = 0; k < 2; ++k) dst[n][k] = *(const LAS bf16x8*)(lds + PG8_SB(b, h) + boff + n * 2048 + k * 1024); } while (0)
; #define PG8_WAIT_V(n) asm volatile("s_waitcnt vmcnt(" #n ")" ::: "memory")
; #define PG8_WAIT_L(n) asm volatile("s_waitcnt lgkmcnt(" #n ")" ::: "memory")
; #define PG8_BAR __builtin_amdgcn_s_barrier()
; #define PG8_SCHED __builtin_amdgcn_sched_barrier(0)
; template <bool F16, class Sched, class Epi>
; __device__ __forceinline__ void gemm_phase(LAS unsigned char* lds, const Gemm g, const Sched& S, const Epi& E, int wave_s) {
;     ...
;             PG8_WAIT_V(8); PG8_WAIT_L(0); PG8_BAR; PG8_MMA(1, 0, At, B0); PG8_MMA(1, 1, At, B1); PG8_BAR; PG8_SCHED;
;             PG8_LDB(B0, 1, 0); PG8_LDB(B1, 1, 1); PG8_SCHED; PG8_LDA(At, 1, 0); PG8_STAGE(PG8_SA(0, 1), a2 + hstepA, voffA);
;             PG8_WAIT_V(8); PG8_WAIT_L(0); PG8_BAR; PG8_MMA(0, 0, At, B0); PG8_MMA(0, 1, At, B1); PG8_BAR; PG8_SCHED;
	v_mfma_f32_16x16x32_bf16 v[60:63], v[138:141], v[178:181], v[60:63]
	v_mfma_f32_16x16x32_bf16 v[56:59], v[146:149], v[178:181], v[56:59]
	v_mfma_f32_16x16x32_bf16 v[52:55], v[138:141], v[186:189], v[52:55]
	v_mfma_f32_16x16x32_bf16 v[44:47], v[146:149], v[186:189], v[44:47]
	v_mfma_f32_16x16x32_bf16 v[36:39], v[138:141], v[208:211], v[36:39]
	v_mfma_f32_16x16x32_bf16 v[28:31], v[146:149], v[208:211], v[28:31]
	v_mfma_f32_16x16x32_bf16 v[20:23], v[138:141], v[216:219], v[20:23]
	v_mfma_f32_16x16x32_bf16 v[12:15], v[146:149], v[216:219], v[12:15]
	v_mfma_f32_16x16x32_bf16 v[60:63], v[142:145], v[182:185], v[60:63]
	v_mfma_f32_16x16x32_bf16 v[56:59], v[150:153], v[182:185], v[56:59]
	v_mfma_f32_16x16x32_bf16 v[52:55], v[142:145], v[190:193], v[52:55]
	v_mfma_f32_16x16x32_bf16 v[44:47], v[150:153], v[190:193], v[44:47]
	v_mfma_f32_16x16x32_bf16 v[36:39], v[142:145], v[212:215], v[36:39]
	v_mfma_f32_16x16x32_bf16 v[28:31], v[150:153], v[212:215], v[28:31]
	v_mfma_f32_16x16x32_bf16 v[20:23], v[142:145], v[220:223], v[20:23]
	v_mfma_f32_16x16x32_bf16 v[12:15], v[150:153], v[220:223], v[12:15]
	v_mfma_f32_16x16x32_bf16 v[48:51], v[154:157], v[178:181], v[48:51]
	v_mfma_f32_16x16x32_bf16 v[40:43], v[166:169], v[178:181], v[40:43]
	v_mfma_f32_16x16x32_bf16 v[32:35], v[154:157], v[186:189], v[32:35]
	v_mfma_f32_16x16x32_bf16 v[24:27], v[166:169], v[186:189], v[24:27]
	v_mfma_f32_16x16x32_bf16 v[16:19], v[154:157], v[208:211], v[16:19]
	v_mfma_f32_16x16x32_bf16 v[8:11], v[166:169], v[208:211], v[8:11]
	v_mfma_f32_16x16x32_bf16 v[4:7], v[154:157], v[216:219], v[4:7]
	v_mfma_f32_16x16x32_bf16 v[0:3], v[166:169], v[216:219], v[0:3]
	v_mfma_f32_16x16x32_bf16 v[48:51], v[158:161], v[182:185], v[48:51]
	v_mfma_f32_16x16x32_bf16 v[40:43], v[170:173], v[182:185], v[40:43]
	v_mfma_f32_16x16x32_bf16 v[32:35], v[158:161], v[190:193], v[32:35]
	v_mfma_f32_16x16x32_bf16 v[24:27], v[170:173], v[190:193], v[24:27]
	v_mfma_f32_16x16x32_bf16 v[16:19], v[158:161], v[212:215], v[16:19]
	v_mfma_f32_16x16x32_bf16 v[8:11], v[170:173], v[212:215], v[8:11]
	v_mfma_f32_16x16x32_bf16 v[4:7], v[158:161], v[220:223], v[4:7]
	v_mfma_f32_16x16x32_bf16 v[0:3], v[170:173], v[220:223], v[0:3]
	s_barrier
	s_setprio 0
	s_add_i32 s61, 0, 0x18000
	s_add_i32 s62, 0, 0x1c000
	v_add_u32_e32 v150, s61, v163
	v_add_u32_e32 v170, s62, v163
	ds_read_b128 v[138:141], v150
	ds_read_b128 v[142:145], v150 offset:1024
	ds_read_b128 v[146:149], v150 offset:2048
	ds_read_b128 v[150:153], v150 offset:3072
	ds_read_b128 v[154:157], v170
	ds_read_b128 v[158:161], v170 offset:1024
	ds_read_b128 v[166:169], v170 offset:2048
	ds_read_b128 v[170:173], v170 offset:3072
	s_mov_b32 m0, s45
	ds_read_b128 v[178:181], v165 offset:32768
	ds_read_b128 v[182:185], v165 offset:33792
	ds_read_b128 v[186:189], v165 offset:34816
	ds_read_b128 v[190:193], v165 offset:35840
	ds_read_b128 v[208:211], v165 offset:36864
	ds_read_b128 v[212:215], v165 offset:37888
	ds_read_b128 v[216:219], v165 offset:38912
	ds_read_b128 v[220:223], v165 offset:39936
	global_load_lds_dwordx4 v132, s[30:31]
	s_mov_b32 m0, s46
	s_nop 0
	global_load_lds_dwordx4 v130, s[30:31]
	s_waitcnt vmcnt(8)
	s_waitcnt lgkmcnt(0)
	s_setprio 1
	s_barrier
	v_mfma_f32_16x16x32_bf16 v[124:127], v[138:141], v[178:181], v[124:127]
	v_mfma_f32_16x16x32_bf16 v[120:123], v[146:149], v[178:181], v[120:123]
	v_mfma_f32_16x16x32_bf16 v[108:111], v[138:141], v[186:189], v[108:111]
	v_mfma_f32_16x16x32_bf16 v[104:107], v[146:149], v[186:189], v[104:107]
	v_mfma_f32_16x16x32_bf16 v[96:99], v[138:141], v[208:211], v[96:99]
	v_mfma_f32_16x16x32_bf16 v[92:95], v[146:149], v[208:211], v[92:95]
	v_mfma_f32_16x16x32_bf16 v[84:87], v[138:141], v[216:219], v[84:87]
	v_mfma_f32_16x16x32_bf16 v[76:79], v[146:149], v[216:219], v[76:79]
	v_mfma_f32_16x16x32_bf16 v[124:127], v[142:145], v[182:185], v[124:127]
	v_mfma_f32_16x16x32_bf16 v[120:123], v[150:153], v[182:185], v[120:123]
	v_mfma_f32_16x16x32_bf16 v[108:111], v[142:145], v[190:193], v[108:111]
	v_mfma_f32_16x16x32_bf16 v[104:107], v[150:153], v[190:193], v[104:107]
	v_mfma_f32_16x16x32_bf16 v[96:99], v[142:145], v[212:215], v[96:99]
	v_mfma_f32_16x16x32_bf16 v[92:95], v[150:153], v[212:215], v[92:95]
	v_mfma_f32_16x16x32_bf16 v[84:87], v[142:145], v[220:223], v[84:87]
	v_mfma_f32_16x16x32_bf16 v[76:79], v[150:153], v[220:223], v[76:79]
	v_mfma_f32_16x16x32_bf16 v[116:119], v[154:157], v[178:181], v[116:119]
	v_mfma_f32_16x16x32_bf16 v[112:115], v[166:169], v[178:181], v[112:115]
	v_mfma_f32_16x16x32_bf16 v[100:103], v[154:157], v[186:189], v[100:103]
	v_mfma_f32_16x16x32_bf16 v[88:91], v[166:169], v[186:189], v[88:91]
	v_mfma_f32_16x16x32_bf16 v[80:83], v[154:157], v[208:211], v[80:83]
	v_mfma_f32_16x16x32_bf16 v[72:75], v[166:169], v[208:211], v[72:75]
	v_mfma_f32_16x16x32_bf16 v[68:71], v[154:157], v[216:219], v[68:71]
	v_mfma_f32_16x16x32_bf16 v[64:67], v[166:169], v[216:219], v[64:67]
	v_mfma_f32_16x16x32_bf16 v[116:119], v[158:161], v[182:185], v[116:119]
	v_mfma_f32_16x16x32_bf16 v[112:115], v[170:173], v[182:185], v[112:115]
	v_mfma_f32_16x16x32_bf16 v[100:103], v[158:161], v[190:193], v[100:103]
	v_mfma_f32_16x16x32_bf16 v[88:91], v[170:173], v[190:193], v[88:91]
	v_mfma_f32_16x16x32_bf16 v[80:83], v[158:161], v[212:215], v[80:83]
	v_mfma_f32_16x16x32_bf16 v[72:75], v[170:173], v[212:215], v[72:75]
	v_mfma_f32_16x16x32_bf16 v[68:71], v[158:161], v[220:223], v[68:71]
	v_mfma_f32_16x16x32_bf16 v[64:67], v[170:173], v[220:223], v[64:67]
	s_barrier
; #define PG8_STAGE(bufoff, gbase, voff) do { _Pragma("unroll") for (int _i = 0; _i < 2; ++_i) \
;         __builtin_amdgcn_global_load_lds((const unsigned*)((const char*)(gbase) + (voff)[_i]), (LAS unsigned*)(lds + (bufoff) + ldsw + _i * 8192), 16, 0, 0); } while (0)
; #define PG8_LDA(dst, b, h) do { _Pragma("unroll") for (int m = 0; m < 4; ++m) _Pragma("unroll") for (int k = 0; k < 2; ++k) dst[m][k] = *(const LAS bf16x8*)(lds + PG8_SA(b, h) + aoff + m * 2048 + k * 1024); } while (0)
; #define PG8_WAIT_V(n) asm volatile("s_waitcnt vmcnt(" #n ")" ::: "memory")
; #define PG8_WAIT_L(n) asm volatile("s_waitcnt lgkmcnt(" #n ")" ::: "memory")
; #define PG8_BAR __builtin_amdgcn_s_barrier()
; #define PG8_SCHED __builtin_amdgcn_sched_barrier(0)
; template <bool F16, class Sched, class Epi>
; __device__ __forceinline__ void gemm_phase(LAS unsigned char* lds, const Gemm g, const Sched& S, const Epi& E, int wave_s) {
;     ...
;             PG8_LDA(At, 1, 1); PG8_STAGE(PG8_SB(1, 0), b3, voffB); PG8_STAGE(PG8_SB(1, 1), b3 + hstepB, voffB); PG8_STAGE(PG8_SA(1, 0), a3, voffA);
;             PG8_WAIT_V(8); PG8_WAIT_L(0); PG8_BAR; PG8_MMA(1, 0, At, B0); PG8_MMA(1, 1, At, B1); PG8_BAR; PG8_SCHED;
;         }
	s_setprio 0
	s_add_i32 s30, s61, s39
	v_lshl_add_u64 v[174:175], v[174:175], 0, s[54:55]
	s_mov_b32 m0, s30
	ds_read_b128 v[178:181], v165 offset:49152
	ds_read_b128 v[182:185], v165 offset:50176
	ds_read_b128 v[186:189], v165 offset:51200
	ds_read_b128 v[190:193], v165 offset:52224
	ds_read_b128 v[208:211], v165 offset:53248
	ds_read_b128 v[212:215], v165 offset:54272
	ds_read_b128 v[216:219], v165 offset:55296
	ds_read_b128 v[220:223], v165 offset:56320
	global_load_lds_dwordx4 v[174:175], off
	s_add_i32 m0, s30, 0x2000
	s_add_u32 s28, s28, 0x80080
	v_lshl_add_u64 v[174:175], v[194:195], 0, s[54:55]
	s_addc_u32 s29, s29, 0
	s_add_i32 s30, s62, s39
	global_load_lds_dwordx4 v[174:175], off
	v_lshl_add_u64 v[174:175], s[28:29], 0, v[176:177]
	s_mov_b32 m0, s30
	s_nop 0
	global_load_lds_dwordx4 v[174:175], off
	v_lshl_add_u64 v[174:175], s[28:29], 0, v[128:129]
	s_add_i32 m0, s30, 0x2000
	s_nop 0
	global_load_lds_dwordx4 v[174:175], off
	v_lshl_add_u64 v[174:175], v[198:199], 0, s[54:55]
	s_mov_b32 m0, s19
	s_nop 0
	global_load_lds_dwordx4 v[174:175], off
	v_lshl_add_u64 v[174:175], v[200:201], 0, s[54:55]
	s_mov_b32 m0, s47
	s_nop 0
	global_load_lds_dwordx4 v[174:175], off
	s_waitcnt vmcnt(8)
	s_waitcnt lgkmcnt(0)
	s_setprio 1
	s_barrier
	v_mfma_f32_16x16x32_bf16 v[60:63], v[138:141], v[178:181], v[60:63]
	v_mfma_f32_16x16x32_bf16 v[56:59], v[146:149], v[178:181], v[56:59]
	v_mfma_f32_16x16x32_bf16 v[52:55], v[138:141], v[186:189], v[52:55]
	v_mfma_f32_16x16x32_bf16 v[44:47], v[146:149], v[186:189], v[44:47]
	v_mfma_f32_16x16x32_bf16 v[36:39], v[138:141], v[208:211], v[36:39]
	v_mfma_f32_16x16x32_bf16 v[28:31], v[146:149], v[208:211], v[28:31]
	v_mfma_f32_16x16x32_bf16 v[20:23], v[138:141], v[216:219], v[20:23]
	v_mfma_f32_16x16x32_bf16 v[12:15], v[146:149], v[216:219], v[12:15]
	v_mfma_f32_16x16x32_bf16 v[60:63], v[142:145], v[182:185], v[60:63]
	v_mfma_f32_16x16x32_bf16 v[56:59], v[150:153], v[182:185], v[56:59]
	v_mfma_f32_16x16x32_bf16 v[52:55], v[142:145], v[190:193], v[52:55]
	v_mfma_f32_16x16x32_bf16 v[44:47], v[150:153], v[190:193], v[44:47]
	v_mfma_f32_16x16x32_bf16 v[36:39], v[142:145], v[212:215], v[36:39]
	v_mfma_f32_16x16x32_bf16 v[28:31], v[150:153], v[212:215], v[28:31]
	v_mfma_f32_16x16x32_bf16 v[20:23], v[142:145], v[220:223], v[20:23]
	v_mfma_f32_16x16x32_bf16 v[12:15], v[150:153], v[220:223], v[12:15]
	v_mfma_f32_16x16x32_bf16 v[48:51], v[154:157], v[178:181], v[48:51]
	v_mfma_f32_16x16x32_bf16 v[40:43], v[166:169], v[178:181], v[40:43]
	v_mfma_f32_16x16x32_bf16 v[32:35], v[154:157], v[186:189], v[32:35]
	v_mfma_f32_16x16x32_bf16 v[24:27], v[166:169], v[186:189], v[24:27]
	v_mfma_f32_16x16x32_bf16 v[16:19], v[154:157], v[208:211], v[16:19]
	v_mfma_f32_16x16x32_bf16 v[8:11], v[166:169], v[208:211], v[8:11]
	v_mfma_f32_16x16x32_bf16 v[4:7], v[154:157], v[216:219], v[4:7]
	v_mfma_f32_16x16x32_bf16 v[0:3], v[166:169], v[216:219], v[0:3]
	v_mfma_f32_16x16x32_bf16 v[48:51], v[158:161], v[182:185], v[48:51]
	v_mfma_f32_16x16x32_bf16 v[40:43], v[170:173], v[182:185], v[40:43]
	v_mfma_f32_16x16x32_bf16 v[32:35], v[158:161], v[190:193], v[32:35]
	v_mfma_f32_16x16x32_bf16 v[24:27], v[170:173], v[190:193], v[24:27]
	v_mfma_f32_16x16x32_bf16 v[16:19], v[158:161], v[212:215], v[16:19]
	v_mfma_f32_16x16x32_bf16 v[8:11], v[170:173], v[212:215], v[8:11]
	v_mfma_f32_16x16x32_bf16 v[4:7], v[158:161], v[220:223], v[4:7]
	v_mfma_f32_16x16x32_bf16 v[0:3], v[170:173], v[220:223], v[0:3]
	s_barrier
	s_setprio 0
	s_add_i32 s60, s60, 2
	s_add_u32 s26, s26, 0x100
	s_addc_u32 s27, s27, 0
	s_add_u32 s58, s58, 0x100
	s_addc_u32 s59, s59, 0
	s_cmp_gt_u32 s60, 29
	s_cbranch_scc0 .LBB0_598
	s_and_b64 vcc, exec, s[14:15]
	s_cbranch_vccz .LBB0_601
	s_barrier

; #define PG8_STAGE(bufoff, gbase, voff) do { _Pragma("unroll") for (int _i = 0; _i < 2; ++_i) \
;         __builtin_amdgcn_global_load_lds((const unsigned*)((const char*)(gbase) + (voff)[_i]), (LAS unsigned*)(lds + (bufoff) + ldsw + _i * 8192), 16, 0, 0); } while (0)
; #define PG8_LDA(dst, b, h) do { _Pragma("unroll") for (int m = 0; m < 4; ++m) _Pragma("unroll") for (int k = 0; k < 2; ++k) dst[m][k] = *(const LAS bf16x8*)(lds + PG8_SA(b, h) + aoff + m * 2048 + k * 1024); } while (0)
; #define PG8_LDB(dst, b, h) do { _Pragma("unroll") for (int n = 0; n < 2; ++n) _Pragma("unroll") for (int k = 0; k < 2; ++k) dst[n][k] = *(const LAS bf16x8*)(lds + PG8_SB(b, h) + boff + n * 2048 + k * 1024); } while (0)
; #define PG8_WAIT_V(n) asm volatile("s_waitcnt vmcnt(" #n ")" ::: "memory")
; #define PG8_WAIT_L(n) asm volatile("s_waitcnt lgkmcnt(" #n ")" ::: "memory")
; #define PG8_BAR __builtin_amdgcn_s_barrier()
; #define PG8_SCHED __builtin_amdgcn_sched_barrier(0)
; template <bool F16, class Sched, class Epi>
; __device__ __forceinline__ void gemm_phase(LAS unsigned char* lds, const Gemm g, const Sched& S, const Epi& E, int wave_s) {
;     ...
;         for (int t = 0; t < nt; t += 2) {
;             const bool last = (t == nt - 2);
;             const char* a1 = cA + (size_t)(t + 1) * kstep;
;             const char* a2 = last ? nA : cA + (size_t)(t + 2) * kstep; const char* b2 = last ? nB : cB + (size_t)(t + 2) * kstep;
;             const char* a3 = a2 + kstep; const char* b3 = b2 + kstep;
;             PG8_LDB(B0, 0, 0); PG8_LDB(B1, 0, 1); PG8_SCHED; PG8_LDA(At, 0, 0); PG8_STAGE(PG8_SA(1, 1), a1 + hstepA, voffA);
;             PG8_WAIT_V(8); PG8_WAIT_L(0); PG8_BAR; PG8_MMA(0, 0, At, B0); PG8_MMA(0, 1, At, B1); PG8_BAR; PG8_SCHED;
;             PG8_LDA(At, 0, 1); PG8_STAGE(PG8_SB(0, 0), b2, voffB); PG8_STAGE(PG8_SB(0, 1), b2 + hstepB, voffB); PG8_STAGE(PG8_SA(0, 0), a2, voffA);
;             PG8_WAIT_V(8); PG8_WAIT_L(0); PG8_BAR; PG8_MMA(1, 0, At, B0); PG8_MMA(1, 1, At, B1); PG8_BAR; PG8_SCHED;
.LBB0_681:
	s_add_i32 s61, 0, 0x10000
	v_add_u32_e32 v146, s61, v149
	s_add_i32 s64, 0, 0x14000
	ds_read_b128 v[138:141], v146
	ds_read_b128 v[142:145], v146 offset:1024
	ds_read_b128 v[154:157], v146 offset:2048
	ds_read_b128 v[158:161], v146 offset:3072
	v_add_u32_e32 v146, s64, v149
	ds_read_b128 v[162:165], v146
	ds_read_b128 v[166:169], v146 offset:1024
	ds_read_b128 v[170:173], v146 offset:2048
	ds_read_b128 v[178:181], v146 offset:3072
	s_add_i32 m0, s39, 0xc000
	ds_read_b128 v[182:185], v152
	ds_read_b128 v[186:189], v152 offset:1024
	ds_read_b128 v[190:193], v152 offset:2048
	ds_read_b128 v[208:211], v152 offset:3072
	ds_read_b128 v[212:215], v152 offset:4096
	ds_read_b128 v[216:219], v152 offset:5120
	ds_read_b128 v[220:223], v152 offset:6144
	ds_read_b128 v[224:227], v152 offset:7168
	global_load_lds_dwordx4 v134, s[24:25]
	s_add_i32 m0, s39, 0xe000
	s_nop 0
	global_load_lds_dwordx4 v136, s[24:25]
	s_waitcnt vmcnt(8)
	s_waitcnt lgkmcnt(0)
	s_setprio 1
	s_barrier
	v_mfma_f32_16x16x32_bf16 v[124:127], v[138:141], v[182:185], v[124:127]
	v_mfma_f32_16x16x32_bf16 v[116:119], v[154:157], v[182:185], v[116:119]
	v_mfma_f32_16x16x32_bf16 v[108:111], v[138:141], v[190:193], v[108:111]
	v_mfma_f32_16x16x32_bf16 v[100:103], v[154:157], v[190:193], v[100:103]
	v_mfma_f32_16x16x32_bf16 v[92:95], v[138:141], v[212:215], v[92:95]
	v_mfma_f32_16x16x32_bf16 v[84:87], v[154:157], v[212:215], v[84:87]
	v_mfma_f32_16x16x32_bf16 v[76:79], v[138:141], v[220:223], v[76:79]
	v_mfma_f32_16x16x32_bf16 v[68:71], v[154:157], v[220:223], v[68:71]
	v_mfma_f32_16x16x32_bf16 v[124:127], v[142:145], v[186:189], v[124:127]
	v_mfma_f32_16x16x32_bf16 v[116:119], v[158:161], v[186:189], v[116:119]
	v_mfma_f32_16x16x32_bf16 v[108:111], v[142:145], v[208:211], v[108:111]
	v_mfma_f32_16x16x32_bf16 v[100:103], v[158:161], v[208:211], v[100:103]
	v_mfma_f32_16x16x32_bf16 v[92:95], v[142:145], v[216:219], v[92:95]
	v_mfma_f32_16x16x32_bf16 v[84:87], v[158:161], v[216:219], v[84:87]
	v_mfma_f32_16x16x32_bf16 v[76:79], v[142:145], v[224:227], v[76:79]
	v_mfma_f32_16x16x32_bf16 v[68:71], v[158:161], v[224:227], v[68:71]
	v_mfma_f32_16x16x32_bf16 v[120:123], v[162:165], v[182:185], v[120:123]
	v_mfma_f32_16x16x32_bf16 v[112:115], v[170:173], v[182:185], v[112:115]
	v_mfma_f32_16x16x32_bf16 v[104:107], v[162:165], v[190:193], v[104:107]
	v_mfma_f32_16x16x32_bf16 v[96:99], v[170:173], v[190:193], v[96:99]
	v_mfma_f32_16x16x32_bf16 v[88:91], v[162:165], v[212:215], v[88:91]
	v_mfma_f32_16x16x32_bf16 v[80:83], v[170:173], v[212:215], v[80:83]
	v_mfma_f32_16x16x32_bf16 v[72:75], v[162:165], v[220:223], v[72:75]
	v_mfma_f32_16x16x32_bf16 v[64:67], v[170:173], v[220:223], v[64:67]
	v_mfma_f32_16x16x32_bf16 v[120:123], v[166:169], v[186:189], v[120:123]
	v_mfma_f32_16x16x32_bf16 v[112:115], v[178:181], v[186:189], v[112:115]
	v_mfma_f32_16x16x32_bf16 v[104:107], v[166:169], v[208:211], v[104:107]
	v_mfma_f32_16x16x32_bf16 v[96:99], v[178:181], v[208:211], v[96:99]
	v_mfma_f32_16x16x32_bf16 v[88:91], v[166:169], v[216:219], v[88:91]
	v_mfma_f32_16x16x32_bf16 v[80:83], v[178:181], v[216:219], v[80:83]
	v_mfma_f32_16x16x32_bf16 v[72:75], v[166:169], v[224:227], v[72:75]
	v_mfma_f32_16x16x32_bf16 v[64:67], v[178:181], v[224:227], v[64:67]
	s_barrier
	s_setprio 0
	s_add_u32 s26, s24, 0xfff80080
	s_addc_u32 s27, s25, -1
	s_cmp_eq_u32 s60, 28
	s_cselect_b32 s29, s49, s27
	s_cselect_b32 s28, s50, s26
	s_cselect_b32 s27, s52, s59
	s_cselect_b32 s26, s53, s58
	s_add_i32 s61, s61, s38
	v_lshl_add_u64 v[146:147], s[26:27], 0, v[176:177]
	s_mov_b32 m0, s61
	ds_read_b128 v[182:185], v152 offset:16384
	ds_read_b128 v[186:189], v152 offset:17408
	ds_read_b128 v[190:193], v152 offset:18432
	ds_read_b128 v[208:211], v152 offset:19456
	ds_read_b128 v[212:215], v152 offset:20480
	ds_read_b128 v[216:219], v152 offset:21504
	ds_read_b128 v[220:223], v152 offset:22528
	ds_read_b128 v[224:227], v152 offset:23552
	global_load_lds_dwordx4 v[146:147], off
	s_add_i32 m0, s61, 0x2000
	s_add_u32 s62, s26, 0x80000
	v_lshl_add_u64 v[174:175], s[26:27], 0, v[128:129]
	s_addc_u32 s63, s27, 0
	s_add_i32 s61, s64, s38
	global_load_lds_dwordx4 v[174:175], off
	v_lshl_add_u64 v[194:195], s[62:63], 0, v[176:177]
	s_mov_b32 m0, s61
	v_lshl_add_u64 v[198:199], s[28:29], 0, v[130:131]
	global_load_lds_dwordx4 v[194:195], off
	v_lshl_add_u64 v[194:195], s[62:63], 0, v[128:129]
	s_add_i32 m0, s61, 0x2000
	s_nop 0
	global_load_lds_dwordx4 v[194:195], off
	v_lshl_add_u64 v[194:195], s[28:29], 0, v[132:133]
	s_mov_b32 m0, s39
	s_nop 0
	global_load_lds_dwordx4 v[194:195], off
	s_mov_b32 m0, s43
	s_nop 0
	global_load_lds_dwordx4 v[198:199], off
	s_add_u32 s28, s28, 0x80000
	s_addc_u32 s29, s29, 0
	s_waitcnt vmcnt(8)
	s_waitcnt lgkmcnt(0)
	s_setprio 1
	s_barrier
; #define PG8_STAGE(bufoff, gbase, voff) do { _Pragma("unroll") for (int _i = 0; _i < 2; ++_i) \
;         __builtin_amdgcn_global_load_lds((const unsigned*)((const char*)(gbase) + (voff)[_i]), (LAS unsigned*)(lds + (bufoff) + ldsw + _i * 8192), 16, 0, 0); } while (0)
; #define PG8_LDA(dst, b, h) do { _Pragma("unroll") for (int m = 0; m < 4; ++m) _Pragma("unroll") for (int k = 0; k < 2; ++k) dst[m][k] = *(const LAS bf16x8*)(lds + PG8_SA(b, h) + aoff + m * 2048 + k * 1024); } while (0)
; #define PG8_LDB(dst, b, h) do { _Pragma("unroll") for (int n = 0; n < 2; ++n) _Pragma("unroll") for (int k = 0; k < 2; ++k) dst[n][k] = *(const LAS bf16x8*)(lds + PG8_SB(b, h) + boff + n * 2048 + k * 1024); } while (0)
; #define PG8_WAIT_V(n) asm volatile("s_waitcnt vmcnt(" #n ")" ::: "memory")
; #define PG8_WAIT_L(n) asm volatile("s_waitcnt lgkmcnt(" #n ")" ::: "memory")
; #define PG8_BAR __builtin_amdgcn_s_barrier()
; #define PG8_SCHED __builtin_amdgcn_sched_barrier(0)
; template <bool F16, class Sched, class Epi>
; __device__ __forceinline__ void gemm_phase(LAS unsigned char* lds, const Gemm g, const Sched& S, const Epi& E, int wave_s) {
;     ...
;             PG8_WAIT_V(8); PG8_WAIT_L(0); PG8_BAR; PG8_MMA(1, 0, At, B0); PG8_MMA(1, 1, At, B1); PG8_BAR; PG8_SCHED;
;             PG8_LDB(B0, 1, 0); PG8_LDB(B1, 1, 1); PG8_SCHED; PG8_LDA(At, 1, 0); PG8_STAGE(PG8_SA(0, 1), a2 + hstepA, voffA);
;             PG8_WAIT_V(8); PG8_WAIT_L(0); PG8_BAR; PG8_MMA(0, 0, At, B0); PG8_MMA(0, 1, At, B1); PG8_BAR; PG8_SCHED;
	v_mfma_f32_16x16x32_bf16 v[60:63], v[138:141], v[182:185], v[60:63]
	v_mfma_f32_16x16x32_bf16 v[52:55], v[154:157], v[182:185], v[52:55]
	v_mfma_f32_16x16x32_bf16 v[44:47], v[138:141], v[190:193], v[44:47]
	v_mfma_f32_16x16x32_bf16 v[36:39], v[154:157], v[190:193], v[36:39]
	v_mfma_f32_16x16x32_bf16 v[28:31], v[138:141], v[212:215], v[28:31]
	v_mfma_f32_16x16x32_bf16 v[20:23], v[154:157], v[212:215], v[20:23]
	v_mfma_f32_16x16x32_bf16 v[12:15], v[138:141], v[220:223], v[12:15]
	v_mfma_f32_16x16x32_bf16 v[4:7], v[154:157], v[220:223], v[4:7]
	v_mfma_f32_16x16x32_bf16 v[60:63], v[142:145], v[186:189], v[60:63]
	v_mfma_f32_16x16x32_bf16 v[52:55], v[158:161], v[186:189], v[52:55]
	v_mfma_f32_16x16x32_bf16 v[44:47], v[142:145], v[208:211], v[44:47]
	v_mfma_f32_16x16x32_bf16 v[36:39], v[158:161], v[208:211], v[36:39]
	v_mfma_f32_16x16x32_bf16 v[28:31], v[142:145], v[216:219], v[28:31]
	v_mfma_f32_16x16x32_bf16 v[20:23], v[158:161], v[216:219], v[20:23]
	v_mfma_f32_16x16x32_bf16 v[12:15], v[142:145], v[224:227], v[12:15]
	v_mfma_f32_16x16x32_bf16 v[4:7], v[158:161], v[224:227], v[4:7]
	v_mfma_f32_16x16x32_bf16 v[56:59], v[162:165], v[182:185], v[56:59]
	v_mfma_f32_16x16x32_bf16 v[48:51], v[170:173], v[182:185], v[48:51]
	v_mfma_f32_16x16x32_bf16 v[40:43], v[162:165], v[190:193], v[40:43]
	v_mfma_f32_16x16x32_bf16 v[32:35], v[170:173], v[190:193], v[32:35]
	v_mfma_f32_16x16x32_bf16 v[24:27], v[162:165], v[212:215], v[24:27]
	v_mfma_f32_16x16x32_bf16 v[16:19], v[170:173], v[212:215], v[16:19]
	v_mfma_f32_16x16x32_bf16 v[8:11], v[162:165], v[220:223], v[8:11]
	v_mfma_f32_16x16x32_bf16 v[0:3], v[170:173], v[220:223], v[0:3]
	v_mfma_f32_16x16x32_bf16 v[56:59], v[166:169], v[186:189], v[56:59]
	v_mfma_f32_16x16x32_bf16 v[48:51], v[178:181], v[186:189], v[48:51]
	v_mfma_f32_16x16x32_bf16 v[40:43], v[166:169], v[208:211], v[40:43]
	v_mfma_f32_16x16x32_bf16 v[32:35], v[178:181], v[208:211], v[32:35]
	v_mfma_f32_16x16x32_bf16 v[24:27], v[166:169], v[216:219], v[24:27]
	v_mfma_f32_16x16x32_bf16 v[16:19], v[178:181], v[216:219], v[16:19]
	v_mfma_f32_16x16x32_bf16 v[8:11], v[166:169], v[224:227], v[8:11]
	v_mfma_f32_16x16x32_bf16 v[0:3], v[178:181], v[224:227], v[0:3]
	s_barrier
	s_setprio 0
	s_add_i32 s61, 0, 0x18000
	v_add_u32_e32 v153, s61, v149
	s_add_i32 s62, 0, 0x1c000
	ds_read_b128 v[138:141], v153
	ds_read_b128 v[142:145], v153 offset:1024
	ds_read_b128 v[154:157], v153 offset:2048
	ds_read_b128 v[158:161], v153 offset:3072
	v_add_u32_e32 v153, s62, v149
	ds_read_b128 v[162:165], v153
	ds_read_b128 v[166:169], v153 offset:1024
	ds_read_b128 v[170:173], v153 offset:2048
	ds_read_b128 v[178:181], v153 offset:3072
	s_mov_b32 m0, s44
	ds_read_b128 v[182:185], v152 offset:32768
	ds_read_b128 v[186:189], v152 offset:33792
	ds_read_b128 v[190:193], v152 offset:34816
	ds_read_b128 v[208:211], v152 offset:35840
	ds_read_b128 v[212:215], v152 offset:36864
	ds_read_b128 v[216:219], v152 offset:37888
	ds_read_b128 v[220:223], v152 offset:38912
	ds_read_b128 v[224:227], v152 offset:39936
	global_load_lds_dwordx4 v132, s[28:29]
	s_mov_b32 m0, s45
	s_nop 0
	global_load_lds_dwordx4 v130, s[28:29]
	s_waitcnt vmcnt(8)
	s_waitcnt lgkmcnt(0)
	s_setprio 1
	s_barrier
	v_mfma_f32_16x16x32_bf16 v[124:127], v[138:141], v[182:185], v[124:127]
	v_mfma_f32_16x16x32_bf16 v[116:119], v[154:157], v[182:185], v[116:119]
	v_mfma_f32_16x16x32_bf16 v[108:111], v[138:141], v[190:193], v[108:111]
	v_mfma_f32_16x16x32_bf16 v[100:103], v[154:157], v[190:193], v[100:103]
	v_mfma_f32_16x16x32_bf16 v[92:95], v[138:141], v[212:215], v[92:95]
	v_mfma_f32_16x16x32_bf16 v[84:87], v[154:157], v[212:215], v[84:87]
	v_mfma_f32_16x16x32_bf16 v[76:79], v[138:141], v[220:223], v[76:79]
	v_mfma_f32_16x16x32_bf16 v[68:71], v[154:157], v[220:223], v[68:71]
	v_mfma_f32_16x16x32_bf16 v[124:127], v[142:145], v[186:189], v[124:127]
	v_mfma_f32_16x16x32_bf16 v[116:119], v[158:161], v[186:189], v[116:119]
	v_mfma_f32_16x16x32_bf16 v[108:111], v[142:145], v[208:211], v[108:111]
	v_mfma_f32_16x16x32_bf16 v[100:103], v[158:161], v[208:211], v[100:103]
	v_mfma_f32_16x16x32_bf16 v[92:95], v[142:145], v[216:219], v[92:95]
	v_mfma_f32_16x16x32_bf16 v[84:87], v[158:161], v[216:219], v[84:87]
	v_mfma_f32_16x16x32_bf16 v[76:79], v[142:145], v[224:227], v[76:79]
	v_mfma_f32_16x16x32_bf16 v[68:71], v[158:161], v[224:227], v[68:71]
	v_mfma_f32_16x16x32_bf16 v[120:123], v[162:165], v[182:185], v[120:123]
	v_mfma_f32_16x16x32_bf16 v[112:115], v[170:173], v[182:185], v[112:115]
	v_mfma_f32_16x16x32_bf16 v[104:107], v[162:165], v[190:193], v[104:107]
	v_mfma_f32_16x16x32_bf16 v[96:99], v[170:173], v[190:193], v[96:99]
	v_mfma_f32_16x16x32_bf16 v[88:91], v[162:165], v[212:215], v[88:91]
	v_mfma_f32_16x16x32_bf16 v[80:83], v[170:173], v[212:215], v[80:83]
	v_mfma_f32_16x16x32_bf16 v[72:75], v[162:165], v[220:223], v[72:75]
	v_mfma_f32_16x16x32_bf16 v[64:67], v[170:173], v[220:223], v[64:67]
	v_mfma_f32_16x16x32_bf16 v[120:123], v[166:169], v[186:189], v[120:123]
	v_mfma_f32_16x16x32_bf16 v[112:115], v[178:181], v[186:189], v[112:115]
	v_mfma_f32_16x16x32_bf16 v[104:107], v[166:169], v[208:211], v[104:107]
	v_mfma_f32_16x16x32_bf16 v[96:99], v[178:181], v[208:211], v[96:99]
	v_mfma_f32_16x16x32_bf16 v[88:91], v[166:169], v[216:219], v[88:91]
	v_mfma_f32_16x16x32_bf16 v[80:83], v[178:181], v[216:219], v[80:83]
	v_mfma_f32_16x16x32_bf16 v[72:75], v[166:169], v[224:227], v[72:75]
	v_mfma_f32_16x16x32_bf16 v[64:67], v[178:181], v[224:227], v[64:67]
	s_barrier
; #define PG8_STAGE(bufoff, gbase, voff) do { _Pragma("unroll") for (int _i = 0; _i < 2; ++_i) \
;         __builtin_amdgcn_global_load_lds((const unsigned*)((const char*)(gbase) + (voff)[_i]), (LAS unsigned*)(lds + (bufoff) + ldsw + _i * 8192), 16, 0, 0); } while (0)
; #define PG8_LDA(dst, b, h) do { _Pragma("unroll") for (int m = 0; m < 4; ++m) _Pragma("unroll") for (int k = 0; k < 2; ++k) dst[m][k] = *(const LAS bf16x8*)(lds + PG8_SA(b, h) + aoff + m * 2048 + k * 1024); } while (0)
; #define PG8_WAIT_V(n) asm volatile("s_waitcnt vmcnt(" #n ")" ::: "memory")
; #define PG8_WAIT_L(n) asm volatile("s_waitcnt lgkmcnt(" #n ")" ::: "memory")
; #define PG8_BAR __builtin_amdgcn_s_barrier()
; #define PG8_SCHED __builtin_amdgcn_sched_barrier(0)
; template <bool F16, class Sched, class Epi>
; __device__ __forceinline__ void gemm_phase(LAS unsigned char* lds, const Gemm g, const Sched& S, const Epi& E, int wave_s) {
;     ...
;             PG8_LDA(At, 1, 1); PG8_STAGE(PG8_SB(1, 0), b3, voffB); PG8_STAGE(PG8_SB(1, 1), b3 + hstepB, voffB); PG8_STAGE(PG8_SA(1, 0), a3, voffA);
;             PG8_WAIT_V(8); PG8_WAIT_L(0); PG8_BAR; PG8_MMA(1, 0, At, B0); PG8_MMA(1, 1, At, B1); PG8_BAR; PG8_SCHED;
;         }
	s_setprio 0
	s_add_i32 s28, s61, s38
	v_lshl_add_u64 v[146:147], v[146:147], 0, s[54:55]
	s_mov_b32 m0, s28
	ds_read_b128 v[182:185], v152 offset:49152
	ds_read_b128 v[186:189], v152 offset:50176
	ds_read_b128 v[190:193], v152 offset:51200
	ds_read_b128 v[208:211], v152 offset:52224
	ds_read_b128 v[212:215], v152 offset:53248
	ds_read_b128 v[216:219], v152 offset:54272
	ds_read_b128 v[220:223], v152 offset:55296
	ds_read_b128 v[224:227], v152 offset:56320
	global_load_lds_dwordx4 v[146:147], off
	s_add_i32 m0, s28, 0x2000
	s_add_u32 s26, s26, 0x80080
	v_lshl_add_u64 v[146:147], v[174:175], 0, s[54:55]
	s_addc_u32 s27, s27, 0
	s_add_i32 s28, s62, s38
	global_load_lds_dwordx4 v[146:147], off
	v_lshl_add_u64 v[146:147], s[26:27], 0, v[176:177]
	s_mov_b32 m0, s28
	s_nop 0
	global_load_lds_dwordx4 v[146:147], off
	v_lshl_add_u64 v[146:147], s[26:27], 0, v[128:129]
	s_add_i32 m0, s28, 0x2000
	s_nop 0
	global_load_lds_dwordx4 v[146:147], off
	v_lshl_add_u64 v[146:147], v[194:195], 0, s[54:55]
	s_mov_b32 m0, s46
	s_nop 0
	global_load_lds_dwordx4 v[146:147], off
	v_lshl_add_u64 v[146:147], v[198:199], 0, s[54:55]
	s_mov_b32 m0, s47
	s_nop 0
	global_load_lds_dwordx4 v[146:147], off
	s_waitcnt vmcnt(8)
	s_waitcnt lgkmcnt(0)
	s_setprio 1
	s_barrier
	v_mfma_f32_16x16x32_bf16 v[60:63], v[138:141], v[182:185], v[60:63]
	v_mfma_f32_16x16x32_bf16 v[52:55], v[154:157], v[182:185], v[52:55]
	v_mfma_f32_16x16x32_bf16 v[44:47], v[138:141], v[190:193], v[44:47]
	v_mfma_f32_16x16x32_bf16 v[36:39], v[154:157], v[190:193], v[36:39]
	v_mfma_f32_16x16x32_bf16 v[28:31], v[138:141], v[212:215], v[28:31]
	v_mfma_f32_16x16x32_bf16 v[20:23], v[154:157], v[212:215], v[20:23]
	v_mfma_f32_16x16x32_bf16 v[12:15], v[138:141], v[220:223], v[12:15]
	v_mfma_f32_16x16x32_bf16 v[4:7], v[154:157], v[220:223], v[4:7]
	v_mfma_f32_16x16x32_bf16 v[60:63], v[142:145], v[186:189], v[60:63]
	v_mfma_f32_16x16x32_bf16 v[52:55], v[158:161], v[186:189], v[52:55]
	v_mfma_f32_16x16x32_bf16 v[44:47], v[142:145], v[208:211], v[44:47]
	v_mfma_f32_16x16x32_bf16 v[36:39], v[158:161], v[208:211], v[36:39]
	v_mfma_f32_16x16x32_bf16 v[28:31], v[142:145], v[216:219], v[28:31]
	v_mfma_f32_16x16x32_bf16 v[20:23], v[158:161], v[216:219], v[20:23]
	v_mfma_f32_16x16x32_bf16 v[12:15], v[142:145], v[224:227], v[12:15]
	v_mfma_f32_16x16x32_bf16 v[4:7], v[158:161], v[224:227], v[4:7]
	v_mfma_f32_16x16x32_bf16 v[56:59], v[162:165], v[182:185], v[56:59]
	v_mfma_f32_16x16x32_bf16 v[48:51], v[170:173], v[182:185], v[48:51]
	v_mfma_f32_16x16x32_bf16 v[40:43], v[162:165], v[190:193], v[40:43]
	v_mfma_f32_16x16x32_bf16 v[32:35], v[170:173], v[190:193], v[32:35]
	v_mfma_f32_16x16x32_bf16 v[24:27], v[162:165], v[212:215], v[24:27]
	v_mfma_f32_16x16x32_bf16 v[16:19], v[170:173], v[212:215], v[16:19]
	v_mfma_f32_16x16x32_bf16 v[8:11], v[162:165], v[220:223], v[8:11]
	v_mfma_f32_16x16x32_bf16 v[0:3], v[170:173], v[220:223], v[0:3]
	v_mfma_f32_16x16x32_bf16 v[56:59], v[166:169], v[186:189], v[56:59]
	v_mfma_f32_16x16x32_bf16 v[48:51], v[178:181], v[186:189], v[48:51]
	v_mfma_f32_16x16x32_bf16 v[40:43], v[166:169], v[208:211], v[40:43]
	v_mfma_f32_16x16x32_bf16 v[32:35], v[178:181], v[208:211], v[32:35]
	v_mfma_f32_16x16x32_bf16 v[24:27], v[166:169], v[216:219], v[24:27]
	v_mfma_f32_16x16x32_bf16 v[16:19], v[178:181], v[216:219], v[16:19]
	v_mfma_f32_16x16x32_bf16 v[8:11], v[166:169], v[224:227], v[8:11]
	v_mfma_f32_16x16x32_bf16 v[0:3], v[178:181], v[224:227], v[0:3]
	s_barrier
	s_setprio 0
	s_add_i32 s60, s60, 2
	s_add_u32 s24, s24, 0x100
	s_addc_u32 s25, s25, 0
	s_add_u32 s58, s58, 0x100
	s_addc_u32 s59, s59, 0
	s_cmp_gt_u32 s60, 29
	s_cbranch_scc0 .LBB0_681
	s_and_b64 vcc, exec, s[12:13]
	s_cbranch_vccz .LBB0_684
	s_barrier

; #define PG8_STAGE(bufoff, gbase, voff) do { _Pragma("unroll") for (int _i = 0; _i < 2; ++_i) \
;         __builtin_amdgcn_global_load_lds((const unsigned*)((const char*)(gbase) + (voff)[_i]), (LAS unsigned*)(lds + (bufoff) + ldsw + _i * 8192), 16, 0, 0); } while (0)
; #define PG8_LDA(dst, b, h) do { _Pragma("unroll") for (int m = 0; m < 4; ++m) _Pragma("unroll") for (int k = 0; k < 2; ++k) dst[m][k] = *(const LAS bf16x8*)(lds + PG8_SA(b, h) + aoff + m * 2048 + k * 1024); } while (0)
; #define PG8_LDB(dst, b, h) do { _Pragma("unroll") for (int n = 0; n < 2; ++n) _Pragma("unroll") for (int k = 0; k < 2; ++k) dst[n][k] = *(const LAS bf16x8*)(lds + PG8_SB(b, h) + boff + n * 2048 + k * 1024); } while (0)
; #define PG8_WAIT_V(n) asm volatile("s_waitcnt vmcnt(" #n ")" ::: "memory")
; #define PG8_WAIT_L(n) asm volatile("s_waitcnt lgkmcnt(" #n ")" ::: "memory")
; #define PG8_BAR __builtin_amdgcn_s_barrier()
; #define PG8_SCHED __builtin_amdgcn_sched_barrier(0)
; template <bool F16, class Sched, class Epi>
; __device__ __forceinline__ void gemm_phase(LAS unsigned char* lds, const Gemm g, const Sched& S, const Epi& E, int wave_s) {
;     ...
;         for (int t = 0; t < nt; t += 2) {
;             const bool last = (t == nt - 2);
;             const char* a1 = cA + (size_t)(t + 1) * kstep;
;             const char* a2 = last ? nA : cA + (size_t)(t + 2) * kstep; const char* b2 = last ? nB : cB + (size_t)(t + 2) * kstep;
;             const char* a3 = a2 + kstep; const char* b3 = b2 + kstep;
;             PG8_LDB(B0, 0, 0); PG8_LDB(B1, 0, 1); PG8_SCHED; PG8_LDA(At, 0, 0); PG8_STAGE(PG8_SA(1, 1), a1 + hstepA, voffA);
;             PG8_WAIT_V(8); PG8_WAIT_L(0); PG8_BAR; PG8_MMA(0, 0, At, B0); PG8_MMA(0, 1, At, B1); PG8_BAR; PG8_SCHED;
;             PG8_LDA(At, 0, 1); PG8_STAGE(PG8_SB(0, 0), b2, voffB); PG8_STAGE(PG8_SB(0, 1), b2 + hstepB, voffB); PG8_STAGE(PG8_SA(0, 0), a2, voffA);
;             PG8_WAIT_V(8); PG8_WAIT_L(0); PG8_BAR; PG8_MMA(1, 0, At, B0); PG8_MMA(1, 1, At, B1); PG8_BAR; PG8_SCHED;
.LBB0_795:
	s_add_i32 s64, 0, 0x10000
	s_add_i32 s65, 0, 0x14000
	v_add_u32_e32 v150, s64, v163
	v_add_u32_e32 v170, s65, v163
	ds_read_b128 v[138:141], v150
	ds_read_b128 v[142:145], v150 offset:1024
	ds_read_b128 v[146:149], v150 offset:2048
	ds_read_b128 v[150:153], v150 offset:3072
	ds_read_b128 v[154:157], v170
	ds_read_b128 v[158:161], v170 offset:1024
	ds_read_b128 v[166:169], v170 offset:2048
	ds_read_b128 v[170:173], v170 offset:3072
	v_lshl_add_u64 v[174:175], s[28:29], 0, v[134:135]
	s_add_i32 m0, s46, 0xc000
	ds_read_b128 v[178:181], v165
	ds_read_b128 v[182:185], v165 offset:1024
	ds_read_b128 v[186:189], v165 offset:2048
	ds_read_b128 v[190:193], v165 offset:3072
	ds_read_b128 v[198:201], v165 offset:4096
	ds_read_b128 v[208:211], v165 offset:5120
	ds_read_b128 v[212:215], v165 offset:6144
	ds_read_b128 v[216:219], v165 offset:7168
	global_load_lds_dwordx4 v[174:175], off
	v_lshl_add_u64 v[174:175], s[28:29], 0, v[136:137]
	s_add_i32 m0, s46, 0xe000
	s_nop 0
	global_load_lds_dwordx4 v[174:175], off
	s_waitcnt vmcnt(8)
	s_waitcnt lgkmcnt(0)
	s_setprio 1
	s_barrier
	v_mfma_f32_16x16x32_bf16 v[124:127], v[138:141], v[178:181], v[124:127]
	v_mfma_f32_16x16x32_bf16 v[120:123], v[146:149], v[178:181], v[120:123]
	v_mfma_f32_16x16x32_bf16 v[108:111], v[138:141], v[186:189], v[108:111]
	v_mfma_f32_16x16x32_bf16 v[104:107], v[146:149], v[186:189], v[104:107]
	v_mfma_f32_16x16x32_bf16 v[96:99], v[138:141], v[198:201], v[96:99]
	v_mfma_f32_16x16x32_bf16 v[92:95], v[146:149], v[198:201], v[92:95]
	v_mfma_f32_16x16x32_bf16 v[84:87], v[138:141], v[212:215], v[84:87]
	v_mfma_f32_16x16x32_bf16 v[76:79], v[146:149], v[212:215], v[76:79]
	v_mfma_f32_16x16x32_bf16 v[124:127], v[142:145], v[182:185], v[124:127]
	v_mfma_f32_16x16x32_bf16 v[120:123], v[150:153], v[182:185], v[120:123]
	v_mfma_f32_16x16x32_bf16 v[108:111], v[142:145], v[190:193], v[108:111]
	v_mfma_f32_16x16x32_bf16 v[104:107], v[150:153], v[190:193], v[104:107]
	v_mfma_f32_16x16x32_bf16 v[96:99], v[142:145], v[208:211], v[96:99]
	v_mfma_f32_16x16x32_bf16 v[92:95], v[150:153], v[208:211], v[92:95]
	v_mfma_f32_16x16x32_bf16 v[84:87], v[142:145], v[216:219], v[84:87]
	v_mfma_f32_16x16x32_bf16 v[76:79], v[150:153], v[216:219], v[76:79]
	v_mfma_f32_16x16x32_bf16 v[116:119], v[154:157], v[178:181], v[116:119]
	v_mfma_f32_16x16x32_bf16 v[112:115], v[166:169], v[178:181], v[112:115]
	v_mfma_f32_16x16x32_bf16 v[100:103], v[154:157], v[186:189], v[100:103]
	v_mfma_f32_16x16x32_bf16 v[88:91], v[166:169], v[186:189], v[88:91]
	v_mfma_f32_16x16x32_bf16 v[80:83], v[154:157], v[198:201], v[80:83]
	v_mfma_f32_16x16x32_bf16 v[72:75], v[166:169], v[198:201], v[72:75]
	v_mfma_f32_16x16x32_bf16 v[68:71], v[154:157], v[212:215], v[68:71]
	v_mfma_f32_16x16x32_bf16 v[64:67], v[166:169], v[212:215], v[64:67]
	v_mfma_f32_16x16x32_bf16 v[116:119], v[158:161], v[182:185], v[116:119]
	v_mfma_f32_16x16x32_bf16 v[112:115], v[170:173], v[182:185], v[112:115]
	v_mfma_f32_16x16x32_bf16 v[100:103], v[158:161], v[190:193], v[100:103]
	v_mfma_f32_16x16x32_bf16 v[88:91], v[170:173], v[190:193], v[88:91]
	v_mfma_f32_16x16x32_bf16 v[80:83], v[158:161], v[208:211], v[80:83]
	v_mfma_f32_16x16x32_bf16 v[72:75], v[170:173], v[208:211], v[72:75]
	v_mfma_f32_16x16x32_bf16 v[68:71], v[158:161], v[216:219], v[68:71]
	v_mfma_f32_16x16x32_bf16 v[64:67], v[170:173], v[216:219], v[64:67]
	s_barrier
	s_setprio 0
	s_add_u32 s30, s28, 0x100
	s_addc_u32 s31, s29, 0
	s_cmpk_eq_i32 s63, 0x54
	s_cselect_b32 s37, s15, s31
	s_cselect_b32 s36, s14, s30
	s_cselect_b32 s35, s27, s1
	s_cselect_b32 s34, s26, s0
	s_add_i32 s28, s64, s45
	v_lshl_add_u64 v[174:175], s[34:35], 0, v[176:177]
	s_mov_b32 m0, s28
	ds_read_b128 v[178:181], v165 offset:16384
	ds_read_b128 v[182:185], v165 offset:17408
	ds_read_b128 v[186:189], v165 offset:18432
	ds_read_b128 v[190:193], v165 offset:19456
	ds_read_b128 v[198:201], v165 offset:20480
	ds_read_b128 v[208:211], v165 offset:21504
	ds_read_b128 v[212:215], v165 offset:22528
	ds_read_b128 v[216:219], v165 offset:23552
	global_load_lds_dwordx4 v[174:175], off
	s_add_i32 m0, s28, 0x2000
	s_add_u32 s28, s34, 0x160000
	v_lshl_add_u64 v[194:195], s[34:35], 0, v[128:129]
	s_addc_u32 s29, s35, 0
	s_add_i32 s64, s65, s45
	global_load_lds_dwordx4 v[194:195], off
	v_lshl_add_u64 v[202:203], s[28:29], 0, v[176:177]
	s_mov_b32 m0, s64
	v_lshl_add_u64 v[220:221], s[36:37], 0, v[130:131]
	global_load_lds_dwordx4 v[202:203], off
	v_lshl_add_u64 v[202:203], s[28:29], 0, v[128:129]
	s_add_i32 m0, s64, 0x2000
	s_nop 0
	global_load_lds_dwordx4 v[202:203], off
	v_lshl_add_u64 v[202:203], s[36:37], 0, v[132:133]
	s_mov_b32 m0, s46
	s_nop 0
	global_load_lds_dwordx4 v[202:203], off
	s_mov_b32 m0, s47
	s_nop 0
	global_load_lds_dwordx4 v[220:221], off
	s_add_u32 s28, s36, 0x160000
	s_addc_u32 s29, s37, 0
	s_waitcnt vmcnt(8)
	s_waitcnt lgkmcnt(0)
	s_setprio 1
	s_barrier
; #define PG8_STAGE(bufoff, gbase, voff) do { _Pragma("unroll") for (int _i = 0; _i < 2; ++_i) \
;         __builtin_amdgcn_global_load_lds((const unsigned*)((const char*)(gbase) + (voff)[_i]), (LAS unsigned*)(lds + (bufoff) + ldsw + _i * 8192), 16, 0, 0); } while (0)
; #define PG8_LDA(dst, b, h) do { _Pragma("unroll") for (int m = 0; m < 4; ++m) _Pragma("unroll") for (int k = 0; k < 2; ++k) dst[m][k] = *(const LAS bf16x8*)(lds + PG8_SA(b, h) + aoff + m * 2048 + k * 1024); } while (0)
; #define PG8_LDB(dst, b, h) do { _Pragma("unroll") for (int n = 0; n < 2; ++n) _Pragma("unroll") for (int k = 0; k < 2; ++k) dst[n][k] = *(const LAS bf16x8*)(lds + PG8_SB(b, h) + boff + n * 2048 + k * 1024); } while (0)
; #define PG8_WAIT_V(n) asm volatile("s_waitcnt vmcnt(" #n ")" ::: "memory")
; #define PG8_WAIT_L(n) asm volatile("s_waitcnt lgkmcnt(" #n ")" ::: "memory")
; #define PG8_BAR __builtin_amdgcn_s_barrier()
; #define PG8_SCHED __builtin_amdgcn_sched_barrier(0)
; template <bool F16, class Sched, class Epi>
; __device__ __forceinline__ void gemm_phase(LAS unsigned char* lds, const Gemm g, const Sched& S, const Epi& E, int wave_s) {
;     ...
;             PG8_WAIT_V(8); PG8_WAIT_L(0); PG8_BAR; PG8_MMA(1, 0, At, B0); PG8_MMA(1, 1, At, B1); PG8_BAR; PG8_SCHED;
;             PG8_LDB(B0, 1, 0); PG8_LDB(B1, 1, 1); PG8_SCHED; PG8_LDA(At, 1, 0); PG8_STAGE(PG8_SA(0, 1), a2 + hstepA, voffA);
;             PG8_WAIT_V(8); PG8_WAIT_L(0); PG8_BAR; PG8_MMA(0, 0, At, B0); PG8_MMA(0, 1, At, B1); PG8_BAR; PG8_SCHED;
	v_mfma_f32_16x16x32_bf16 v[60:63], v[138:141], v[178:181], v[60:63]
	v_mfma_f32_16x16x32_bf16 v[56:59], v[146:149], v[178:181], v[56:59]
	v_mfma_f32_16x16x32_bf16 v[52:55], v[138:141], v[186:189], v[52:55]
	v_mfma_f32_16x16x32_bf16 v[44:47], v[146:149], v[186:189], v[44:47]
	v_mfma_f32_16x16x32_bf16 v[36:39], v[138:141], v[198:201], v[36:39]
	v_mfma_f32_16x16x32_bf16 v[28:31], v[146:149], v[198:201], v[28:31]
	v_mfma_f32_16x16x32_bf16 v[20:23], v[138:141], v[212:215], v[20:23]
	v_mfma_f32_16x16x32_bf16 v[12:15], v[146:149], v[212:215], v[12:15]
	v_mfma_f32_16x16x32_bf16 v[60:63], v[142:145], v[182:185], v[60:63]
	v_mfma_f32_16x16x32_bf16 v[56:59], v[150:153], v[182:185], v[56:59]
	v_mfma_f32_16x16x32_bf16 v[52:55], v[142:145], v[190:193], v[52:55]
	v_mfma_f32_16x16x32_bf16 v[44:47], v[150:153], v[190:193], v[44:47]
	v_mfma_f32_16x16x32_bf16 v[36:39], v[142:145], v[208:211], v[36:39]
	v_mfma_f32_16x16x32_bf16 v[28:31], v[150:153], v[208:211], v[28:31]
	v_mfma_f32_16x16x32_bf16 v[20:23], v[142:145], v[216:219], v[20:23]
	v_mfma_f32_16x16x32_bf16 v[12:15], v[150:153], v[216:219], v[12:15]
	v_mfma_f32_16x16x32_bf16 v[48:51], v[154:157], v[178:181], v[48:51]
	v_mfma_f32_16x16x32_bf16 v[40:43], v[166:169], v[178:181], v[40:43]
	v_mfma_f32_16x16x32_bf16 v[32:35], v[154:157], v[186:189], v[32:35]
	v_mfma_f32_16x16x32_bf16 v[24:27], v[166:169], v[186:189], v[24:27]
	v_mfma_f32_16x16x32_bf16 v[16:19], v[154:157], v[198:201], v[16:19]
	v_mfma_f32_16x16x32_bf16 v[8:11], v[166:169], v[198:201], v[8:11]
	v_mfma_f32_16x16x32_bf16 v[4:7], v[154:157], v[212:215], v[4:7]
	v_mfma_f32_16x16x32_bf16 v[0:3], v[166:169], v[212:215], v[0:3]
	v_mfma_f32_16x16x32_bf16 v[48:51], v[158:161], v[182:185], v[48:51]
	v_mfma_f32_16x16x32_bf16 v[40:43], v[170:173], v[182:185], v[40:43]
	v_mfma_f32_16x16x32_bf16 v[32:35], v[158:161], v[190:193], v[32:35]
	v_mfma_f32_16x16x32_bf16 v[24:27], v[170:173], v[190:193], v[24:27]
	v_mfma_f32_16x16x32_bf16 v[16:19], v[158:161], v[208:211], v[16:19]
	v_mfma_f32_16x16x32_bf16 v[8:11], v[170:173], v[208:211], v[8:11]
	v_mfma_f32_16x16x32_bf16 v[4:7], v[158:161], v[216:219], v[4:7]
	v_mfma_f32_16x16x32_bf16 v[0:3], v[170:173], v[216:219], v[0:3]
	s_barrier
	s_setprio 0
	s_add_i32 s64, 0, 0x18000
	s_add_i32 s65, 0, 0x1c000
	v_add_u32_e32 v150, s64, v163
	v_add_u32_e32 v170, s65, v163
	ds_read_b128 v[138:141], v150
	ds_read_b128 v[142:145], v150 offset:1024
	ds_read_b128 v[146:149], v150 offset:2048
	ds_read_b128 v[150:153], v150 offset:3072
	ds_read_b128 v[154:157], v170
	ds_read_b128 v[158:161], v170 offset:1024
	ds_read_b128 v[166:169], v170 offset:2048
	ds_read_b128 v[170:173], v170 offset:3072
	s_mov_b32 m0, s48
	ds_read_b128 v[178:181], v165 offset:32768
	ds_read_b128 v[182:185], v165 offset:33792
	ds_read_b128 v[186:189], v165 offset:34816
	ds_read_b128 v[190:193], v165 offset:35840
	ds_read_b128 v[198:201], v165 offset:36864
	ds_read_b128 v[208:211], v165 offset:37888
	ds_read_b128 v[212:215], v165 offset:38912
	ds_read_b128 v[216:219], v165 offset:39936
	global_load_lds_dwordx4 v132, s[28:29]
	s_mov_b32 m0, s49
	s_nop 0
	global_load_lds_dwordx4 v130, s[28:29]
	s_waitcnt vmcnt(8)
	s_waitcnt lgkmcnt(0)
	s_setprio 1
	s_barrier
	v_mfma_f32_16x16x32_bf16 v[124:127], v[138:141], v[178:181], v[124:127]
	v_mfma_f32_16x16x32_bf16 v[120:123], v[146:149], v[178:181], v[120:123]
	v_mfma_f32_16x16x32_bf16 v[108:111], v[138:141], v[186:189], v[108:111]
	v_mfma_f32_16x16x32_bf16 v[104:107], v[146:149], v[186:189], v[104:107]
	v_mfma_f32_16x16x32_bf16 v[96:99], v[138:141], v[198:201], v[96:99]
	v_mfma_f32_16x16x32_bf16 v[92:95], v[146:149], v[198:201], v[92:95]
	v_mfma_f32_16x16x32_bf16 v[84:87], v[138:141], v[212:215], v[84:87]
	v_mfma_f32_16x16x32_bf16 v[76:79], v[146:149], v[212:215], v[76:79]
	v_mfma_f32_16x16x32_bf16 v[124:127], v[142:145], v[182:185], v[124:127]
	v_mfma_f32_16x16x32_bf16 v[120:123], v[150:153], v[182:185], v[120:123]
	v_mfma_f32_16x16x32_bf16 v[108:111], v[142:145], v[190:193], v[108:111]
	v_mfma_f32_16x16x32_bf16 v[104:107], v[150:153], v[190:193], v[104:107]
	v_mfma_f32_16x16x32_bf16 v[96:99], v[142:145], v[208:211], v[96:99]
	v_mfma_f32_16x16x32_bf16 v[92:95], v[150:153], v[208:211], v[92:95]
	v_mfma_f32_16x16x32_bf16 v[84:87], v[142:145], v[216:219], v[84:87]
	v_mfma_f32_16x16x32_bf16 v[76:79], v[150:153], v[216:219], v[76:79]
	v_mfma_f32_16x16x32_bf16 v[116:119], v[154:157], v[178:181], v[116:119]
	v_mfma_f32_16x16x32_bf16 v[112:115], v[166:169], v[178:181], v[112:115]
	v_mfma_f32_16x16x32_bf16 v[100:103], v[154:157], v[186:189], v[100:103]
	v_mfma_f32_16x16x32_bf16 v[88:91], v[166:169], v[186:189], v[88:91]
	v_mfma_f32_16x16x32_bf16 v[80:83], v[154:157], v[198:201], v[80:83]
	v_mfma_f32_16x16x32_bf16 v[72:75], v[166:169], v[198:201], v[72:75]
	v_mfma_f32_16x16x32_bf16 v[68:71], v[154:157], v[212:215], v[68:71]
	v_mfma_f32_16x16x32_bf16 v[64:67], v[166:169], v[212:215], v[64:67]
	v_mfma_f32_16x16x32_bf16 v[116:119], v[158:161], v[182:185], v[116:119]
	v_mfma_f32_16x16x32_bf16 v[112:115], v[170:173], v[182:185], v[112:115]
	v_mfma_f32_16x16x32_bf16 v[100:103], v[158:161], v[190:193], v[100:103]
	v_mfma_f32_16x16x32_bf16 v[88:91], v[170:173], v[190:193], v[88:91]
	v_mfma_f32_16x16x32_bf16 v[80:83], v[158:161], v[208:211], v[80:83]
	v_mfma_f32_16x16x32_bf16 v[72:75], v[170:173], v[208:211], v[72:75]
	v_mfma_f32_16x16x32_bf16 v[68:71], v[158:161], v[216:219], v[68:71]
	v_mfma_f32_16x16x32_bf16 v[64:67], v[170:173], v[216:219], v[64:67]
	s_barrier
; #define PG8_STAGE(bufoff, gbase, voff) do { _Pragma("unroll") for (int _i = 0; _i < 2; ++_i) \
;         __builtin_amdgcn_global_load_lds((const unsigned*)((const char*)(gbase) + (voff)[_i]), (LAS unsigned*)(lds + (bufoff) + ldsw + _i * 8192), 16, 0, 0); } while (0)
; #define PG8_LDA(dst, b, h) do { _Pragma("unroll") for (int m = 0; m < 4; ++m) _Pragma("unroll") for (int k = 0; k < 2; ++k) dst[m][k] = *(const LAS bf16x8*)(lds + PG8_SA(b, h) + aoff + m * 2048 + k * 1024); } while (0)
; #define PG8_WAIT_V(n) asm volatile("s_waitcnt vmcnt(" #n ")" ::: "memory")
; #define PG8_WAIT_L(n) asm volatile("s_waitcnt lgkmcnt(" #n ")" ::: "memory")
; #define PG8_BAR __builtin_amdgcn_s_barrier()
; #define PG8_SCHED __builtin_amdgcn_sched_barrier(0)
; template <bool F16, class Sched, class Epi>
; __device__ __forceinline__ void gemm_phase(LAS unsigned char* lds, const Gemm g, const Sched& S, const Epi& E, int wave_s) {
;     ...
;             PG8_LDA(At, 1, 1); PG8_STAGE(PG8_SB(1, 0), b3, voffB); PG8_STAGE(PG8_SB(1, 1), b3 + hstepB, voffB); PG8_STAGE(PG8_SA(1, 0), a3, voffA);
;             PG8_WAIT_V(8); PG8_WAIT_L(0); PG8_BAR; PG8_MMA(1, 0, At, B0); PG8_MMA(1, 1, At, B1); PG8_BAR; PG8_SCHED;
;         }
	s_setprio 0
	s_add_i32 s28, s64, s45
	v_lshl_add_u64 v[174:175], v[174:175], 0, s[54:55]
	s_mov_b32 m0, s28
	ds_read_b128 v[178:181], v165 offset:49152
	ds_read_b128 v[182:185], v165 offset:50176
	ds_read_b128 v[186:189], v165 offset:51200
	ds_read_b128 v[190:193], v165 offset:52224
	ds_read_b128 v[198:201], v165 offset:53248
	ds_read_b128 v[208:211], v165 offset:54272
	ds_read_b128 v[212:215], v165 offset:55296
	ds_read_b128 v[216:219], v165 offset:56320
	global_load_lds_dwordx4 v[174:175], off
	s_add_i32 m0, s28, 0x2000
	s_add_u32 s28, s34, 0x160080
	v_lshl_add_u64 v[174:175], v[194:195], 0, s[54:55]
	s_addc_u32 s29, s35, 0
	s_add_i32 s34, s65, s45
	global_load_lds_dwordx4 v[174:175], off
	v_lshl_add_u64 v[174:175], s[28:29], 0, v[176:177]
	s_mov_b32 m0, s34
	s_nop 0
	global_load_lds_dwordx4 v[174:175], off
	v_lshl_add_u64 v[174:175], s[28:29], 0, v[128:129]
	s_add_i32 m0, s34, 0x2000
	s_nop 0
	global_load_lds_dwordx4 v[174:175], off
	v_lshl_add_u64 v[174:175], v[202:203], 0, s[54:55]
	s_mov_b32 m0, s52
	s_nop 0
	global_load_lds_dwordx4 v[174:175], off
	v_lshl_add_u64 v[174:175], v[220:221], 0, s[54:55]
	s_mov_b32 m0, s53
	s_nop 0
	global_load_lds_dwordx4 v[174:175], off
	s_waitcnt vmcnt(8)
	s_waitcnt lgkmcnt(0)
	s_setprio 1
	s_barrier
	v_mfma_f32_16x16x32_bf16 v[60:63], v[138:141], v[178:181], v[60:63]
	v_mfma_f32_16x16x32_bf16 v[56:59], v[146:149], v[178:181], v[56:59]
	v_mfma_f32_16x16x32_bf16 v[52:55], v[138:141], v[186:189], v[52:55]
	v_mfma_f32_16x16x32_bf16 v[44:47], v[146:149], v[186:189], v[44:47]
	v_mfma_f32_16x16x32_bf16 v[36:39], v[138:141], v[198:201], v[36:39]
	v_mfma_f32_16x16x32_bf16 v[28:31], v[146:149], v[198:201], v[28:31]
	v_mfma_f32_16x16x32_bf16 v[20:23], v[138:141], v[212:215], v[20:23]
	v_mfma_f32_16x16x32_bf16 v[12:15], v[146:149], v[212:215], v[12:15]
	v_mfma_f32_16x16x32_bf16 v[60:63], v[142:145], v[182:185], v[60:63]
	v_mfma_f32_16x16x32_bf16 v[56:59], v[150:153], v[182:185], v[56:59]
	v_mfma_f32_16x16x32_bf16 v[52:55], v[142:145], v[190:193], v[52:55]
	v_mfma_f32_16x16x32_bf16 v[44:47], v[150:153], v[190:193], v[44:47]
	v_mfma_f32_16x16x32_bf16 v[36:39], v[142:145], v[208:211], v[36:39]
	v_mfma_f32_16x16x32_bf16 v[28:31], v[150:153], v[208:211], v[28:31]
	v_mfma_f32_16x16x32_bf16 v[20:23], v[142:145], v[216:219], v[20:23]
	v_mfma_f32_16x16x32_bf16 v[12:15], v[150:153], v[216:219], v[12:15]
	v_mfma_f32_16x16x32_bf16 v[48:51], v[154:157], v[178:181], v[48:51]
	v_mfma_f32_16x16x32_bf16 v[40:43], v[166:169], v[178:181], v[40:43]
	v_mfma_f32_16x16x32_bf16 v[32:35], v[154:157], v[186:189], v[32:35]
	v_mfma_f32_16x16x32_bf16 v[24:27], v[166:169], v[186:189], v[24:27]
	v_mfma_f32_16x16x32_bf16 v[16:19], v[154:157], v[198:201], v[16:19]
	v_mfma_f32_16x16x32_bf16 v[8:11], v[166:169], v[198:201], v[8:11]
	v_mfma_f32_16x16x32_bf16 v[4:7], v[154:157], v[212:215], v[4:7]
	v_mfma_f32_16x16x32_bf16 v[0:3], v[166:169], v[212:215], v[0:3]
	v_mfma_f32_16x16x32_bf16 v[48:51], v[158:161], v[182:185], v[48:51]
	v_mfma_f32_16x16x32_bf16 v[40:43], v[170:173], v[182:185], v[40:43]
	v_mfma_f32_16x16x32_bf16 v[32:35], v[158:161], v[190:193], v[32:35]
	v_mfma_f32_16x16x32_bf16 v[24:27], v[170:173], v[190:193], v[24:27]
	v_mfma_f32_16x16x32_bf16 v[16:19], v[158:161], v[208:211], v[16:19]
	v_mfma_f32_16x16x32_bf16 v[8:11], v[170:173], v[208:211], v[8:11]
	v_mfma_f32_16x16x32_bf16 v[4:7], v[158:161], v[216:219], v[4:7]
	v_mfma_f32_16x16x32_bf16 v[0:3], v[170:173], v[216:219], v[0:3]
	s_barrier
	s_setprio 0
	s_add_i32 s63, s63, 2
	s_add_u32 s0, s0, 0x100
	s_addc_u32 s1, s1, 0
	s_cmpk_gt_u32 s63, 0x55
	s_mov_b64 s[28:29], s[30:31]
	s_cbranch_scc0 .LBB0_795
	s_and_b64 vcc, exec, s[12:13]
	s_cbranch_vccz .LBB0_798
	s_barrier

; #define PG8_STAGE(bufoff, gbase, voff) do { _Pragma("unroll") for (int _i = 0; _i < 2; ++_i) \
;         __builtin_amdgcn_global_load_lds((const unsigned*)((const char*)(gbase) + (voff)[_i]), (LAS unsigned*)(lds + (bufoff) + ldsw + _i * 8192), 16, 0, 0); } while (0)
; #define PG8_LDA(dst, b, h) do { _Pragma("unroll") for (int m = 0; m < 4; ++m) _Pragma("unroll") for (int k = 0; k < 2; ++k) dst[m][k] = *(const LAS bf16x8*)(lds + PG8_SA(b, h) + aoff + m * 2048 + k * 1024); } while (0)
; #define PG8_LDB(dst, b, h) do { _Pragma("unroll") for (int n = 0; n < 2; ++n) _Pragma("unroll") for (int k = 0; k < 2; ++k) dst[n][k] = *(const LAS bf16x8*)(lds + PG8_SB(b, h) + boff + n * 2048 + k * 1024); } while (0)
; #define PG8_WAIT_V(n) asm volatile("s_waitcnt vmcnt(" #n ")" ::: "memory")
; #define PG8_WAIT_L(n) asm volatile("s_waitcnt lgkmcnt(" #n ")" ::: "memory")
; #define PG8_BAR __builtin_amdgcn_s_barrier()
; #define PG8_SCHED __builtin_amdgcn_sched_barrier(0)
; template <bool F16, class Sched, class Epi>
; __device__ __forceinline__ void gemm_phase(LAS unsigned char* lds, const Gemm g, const Sched& S, const Epi& E, int wave_s) {
;     ...
;         for (int t = 0; t < nt; t += 2) {
;             const bool last = (t == nt - 2);
;             const char* a1 = cA + (size_t)(t + 1) * kstep;
;             const char* a2 = last ? nA : cA + (size_t)(t + 2) * kstep; const char* b2 = last ? nB : cB + (size_t)(t + 2) * kstep;
;             const char* a3 = a2 + kstep; const char* b3 = b2 + kstep;
;             PG8_LDB(B0, 0, 0); PG8_LDB(B1, 0, 1); PG8_SCHED; PG8_LDA(At, 0, 0); PG8_STAGE(PG8_SA(1, 1), a1 + hstepA, voffA);
;             PG8_WAIT_V(8); PG8_WAIT_L(0); PG8_BAR; PG8_MMA(0, 0, At, B0); PG8_MMA(0, 1, At, B1); PG8_BAR; PG8_SCHED;
;             PG8_LDA(At, 0, 1); PG8_STAGE(PG8_SB(0, 0), b2, voffB); PG8_STAGE(PG8_SB(0, 1), b2 + hstepB, voffB); PG8_STAGE(PG8_SA(0, 0), a2, voffA);
;             PG8_WAIT_V(8); PG8_WAIT_L(0); PG8_BAR; PG8_MMA(1, 0, At, B0); PG8_MMA(1, 1, At, B1); PG8_BAR; PG8_SCHED;
.LBB0_869:
	s_add_i32 s64, 0, 0x10000
	s_add_i32 s68, 0, 0x14000
	v_add_u32_e32 v44, s64, v208
	v_add_u32_e32 v156, s68, v208
	ds_read_b128 v[32:35], v44
	ds_read_b128 v[36:39], v44 offset:1024
	ds_read_b128 v[40:43], v44 offset:2048
	ds_read_b128 v[44:47], v44 offset:3072
	ds_read_b128 v[144:147], v156
	ds_read_b128 v[148:151], v156 offset:1024
	ds_read_b128 v[152:155], v156 offset:2048
	ds_read_b128 v[156:159], v156 offset:3072
	s_add_i32 m0, s44, 0xc000
	ds_read_b128 v[160:163], v210
	ds_read_b128 v[164:167], v210 offset:1024
	ds_read_b128 v[168:171], v210 offset:2048
	ds_read_b128 v[172:175], v210 offset:3072
	ds_read_b128 v[188:191], v210 offset:4096
	ds_read_b128 v[192:195], v210 offset:5120
	ds_read_b128 v[198:201], v210 offset:6144
	ds_read_b128 v[212:215], v210 offset:7168
	global_load_lds_dwordx4 v184, s[4:5]
	s_add_i32 m0, s44, 0xe000
	s_nop 0
	global_load_lds_dwordx4 v186, s[4:5]
	s_waitcnt vmcnt(8)
	s_waitcnt lgkmcnt(0)
	s_setprio 1
	s_barrier
	v_mfma_f32_16x16x32_bf16 v[140:143], v[32:35], v[160:163], v[140:143]
	v_mfma_f32_16x16x32_bf16 v[136:139], v[40:43], v[160:163], v[136:139]
	v_mfma_f32_16x16x32_bf16 v[124:127], v[32:35], v[168:171], v[124:127]
	v_mfma_f32_16x16x32_bf16 v[120:123], v[40:43], v[168:171], v[120:123]
	v_mfma_f32_16x16x32_bf16 v[108:111], v[32:35], v[188:191], v[108:111]
	v_mfma_f32_16x16x32_bf16 v[104:107], v[40:43], v[188:191], v[104:107]
	v_mfma_f32_16x16x32_bf16 v[92:95], v[32:35], v[198:201], v[92:95]
	v_mfma_f32_16x16x32_bf16 v[88:91], v[40:43], v[198:201], v[88:91]
	v_mfma_f32_16x16x32_bf16 v[140:143], v[36:39], v[164:167], v[140:143]
	v_mfma_f32_16x16x32_bf16 v[136:139], v[44:47], v[164:167], v[136:139]
	v_mfma_f32_16x16x32_bf16 v[124:127], v[36:39], v[172:175], v[124:127]
	v_mfma_f32_16x16x32_bf16 v[120:123], v[44:47], v[172:175], v[120:123]
	v_mfma_f32_16x16x32_bf16 v[108:111], v[36:39], v[192:195], v[108:111]
	v_mfma_f32_16x16x32_bf16 v[104:107], v[44:47], v[192:195], v[104:107]
	v_mfma_f32_16x16x32_bf16 v[92:95], v[36:39], v[212:215], v[92:95]
	v_mfma_f32_16x16x32_bf16 v[88:91], v[44:47], v[212:215], v[88:91]
	v_mfma_f32_16x16x32_bf16 v[132:135], v[144:147], v[160:163], v[132:135]
	v_mfma_f32_16x16x32_bf16 v[128:131], v[152:155], v[160:163], v[128:131]
	v_mfma_f32_16x16x32_bf16 v[116:119], v[144:147], v[168:171], v[116:119]
	v_mfma_f32_16x16x32_bf16 v[112:115], v[152:155], v[168:171], v[112:115]
	v_mfma_f32_16x16x32_bf16 v[100:103], v[144:147], v[188:191], v[100:103]
	v_mfma_f32_16x16x32_bf16 v[96:99], v[152:155], v[188:191], v[96:99]
	v_mfma_f32_16x16x32_bf16 v[84:87], v[144:147], v[198:201], v[84:87]
	v_mfma_f32_16x16x32_bf16 v[80:83], v[152:155], v[198:201], v[80:83]
	v_mfma_f32_16x16x32_bf16 v[132:135], v[148:151], v[164:167], v[132:135]
	v_mfma_f32_16x16x32_bf16 v[128:131], v[156:159], v[164:167], v[128:131]
	v_mfma_f32_16x16x32_bf16 v[116:119], v[148:151], v[172:175], v[116:119]
	v_mfma_f32_16x16x32_bf16 v[112:115], v[156:159], v[172:175], v[112:115]
	v_mfma_f32_16x16x32_bf16 v[100:103], v[148:151], v[192:195], v[100:103]
	v_mfma_f32_16x16x32_bf16 v[96:99], v[156:159], v[192:195], v[96:99]
	v_mfma_f32_16x16x32_bf16 v[84:87], v[148:151], v[212:215], v[84:87]
	v_mfma_f32_16x16x32_bf16 v[80:83], v[156:159], v[212:215], v[80:83]
	s_barrier
	s_setprio 0
	s_add_u32 s30, s4, 0xfff80080
	s_addc_u32 s31, s5, -1
	s_cmp_eq_u32 s63, 28
	s_cselect_b32 s35, s53, s31
	s_cselect_b32 s34, s58, s30
	s_cselect_b32 s31, s59, s62
	s_cselect_b32 s30, s60, s61
	s_add_i32 s64, s64, s41
	v_lshl_add_u64 v[202:203], s[30:31], 0, v[176:177]
	s_mov_b32 m0, s64
	ds_read_b128 v[160:163], v210 offset:16384
	ds_read_b128 v[164:167], v210 offset:17408
	ds_read_b128 v[168:171], v210 offset:18432
	ds_read_b128 v[172:175], v210 offset:19456
	ds_read_b128 v[188:191], v210 offset:20480
	ds_read_b128 v[192:195], v210 offset:21504
	ds_read_b128 v[198:201], v210 offset:22528
	ds_read_b128 v[212:215], v210 offset:23552
	global_load_lds_dwordx4 v[202:203], off
	s_add_i32 m0, s64, 0x2000
	s_add_u32 s64, s30, 0x80000
	v_lshl_add_u64 v[216:217], s[30:31], 0, v[178:179]
	s_addc_u32 s65, s31, 0
	s_add_i32 s68, s68, s41
	global_load_lds_dwordx4 v[216:217], off
	v_lshl_add_u64 v[218:219], s[64:65], 0, v[176:177]
	s_mov_b32 m0, s68
	v_lshl_add_u64 v[220:221], s[34:35], 0, v[180:181]
	global_load_lds_dwordx4 v[218:219], off
	v_lshl_add_u64 v[218:219], s[64:65], 0, v[178:179]
	s_add_i32 m0, s68, 0x2000
	s_nop 0
	global_load_lds_dwordx4 v[218:219], off
	v_lshl_add_u64 v[218:219], s[34:35], 0, v[182:183]
	s_mov_b32 m0, s44
	s_nop 0
	global_load_lds_dwordx4 v[218:219], off
	s_mov_b32 m0, s45
	s_nop 0
	global_load_lds_dwordx4 v[220:221], off
	s_add_u32 s34, s34, 0x80000
	s_addc_u32 s35, s35, 0
	s_waitcnt vmcnt(8)
	s_waitcnt lgkmcnt(0)
	s_setprio 1
	s_barrier
; #define PG8_STAGE(bufoff, gbase, voff) do { _Pragma("unroll") for (int _i = 0; _i < 2; ++_i) \
;         __builtin_amdgcn_global_load_lds((const unsigned*)((const char*)(gbase) + (voff)[_i]), (LAS unsigned*)(lds + (bufoff) + ldsw + _i * 8192), 16, 0, 0); } while (0)
; #define PG8_LDA(dst, b, h) do { _Pragma("unroll") for (int m = 0; m < 4; ++m) _Pragma("unroll") for (int k = 0; k < 2; ++k) dst[m][k] = *(const LAS bf16x8*)(lds + PG8_SA(b, h) + aoff + m * 2048 + k * 1024); } while (0)
; #define PG8_LDB(dst, b, h) do { _Pragma("unroll") for (int n = 0; n < 2; ++n) _Pragma("unroll") for (int k = 0; k < 2; ++k) dst[n][k] = *(const LAS bf16x8*)(lds + PG8_SB(b, h) + boff + n * 2048 + k * 1024); } while (0)
; #define PG8_WAIT_V(n) asm volatile("s_waitcnt vmcnt(" #n ")" ::: "memory")
; #define PG8_WAIT_L(n) asm volatile("s_waitcnt lgkmcnt(" #n ")" ::: "memory")
; #define PG8_BAR __builtin_amdgcn_s_barrier()
; #define PG8_SCHED __builtin_amdgcn_sched_barrier(0)
; template <bool F16, class Sched, class Epi>
; __device__ __forceinline__ void gemm_phase(LAS unsigned char* lds, const Gemm g, const Sched& S, const Epi& E, int wave_s) {
;     ...
;             PG8_WAIT_V(8); PG8_WAIT_L(0); PG8_BAR; PG8_MMA(1, 0, At, B0); PG8_MMA(1, 1, At, B1); PG8_BAR; PG8_SCHED;
;             PG8_LDB(B0, 1, 0); PG8_LDB(B1, 1, 1); PG8_SCHED; PG8_LDA(At, 1, 0); PG8_STAGE(PG8_SA(0, 1), a2 + hstepA, voffA);
;             PG8_WAIT_V(8); PG8_WAIT_L(0); PG8_BAR; PG8_MMA(0, 0, At, B0); PG8_MMA(0, 1, At, B1); PG8_BAR; PG8_SCHED;
	v_mfma_f32_16x16x32_bf16 v[76:79], v[32:35], v[160:163], v[76:79]
	v_mfma_f32_16x16x32_bf16 v[72:75], v[40:43], v[160:163], v[72:75]
	v_mfma_f32_16x16x32_bf16 v[60:63], v[32:35], v[168:171], v[60:63]
	v_mfma_f32_16x16x32_bf16 v[56:59], v[40:43], v[168:171], v[56:59]
	v_mfma_f32_16x16x32_bf16 v[28:31], v[32:35], v[188:191], v[28:31]
	v_mfma_f32_16x16x32_bf16 v[24:27], v[40:43], v[188:191], v[24:27]
	v_mfma_f32_16x16x32_bf16 v[12:15], v[32:35], v[198:201], v[12:15]
	v_mfma_f32_16x16x32_bf16 v[8:11], v[40:43], v[198:201], v[8:11]
	v_mfma_f32_16x16x32_bf16 v[76:79], v[36:39], v[164:167], v[76:79]
	v_mfma_f32_16x16x32_bf16 v[72:75], v[44:47], v[164:167], v[72:75]
	v_mfma_f32_16x16x32_bf16 v[60:63], v[36:39], v[172:175], v[60:63]
	v_mfma_f32_16x16x32_bf16 v[56:59], v[44:47], v[172:175], v[56:59]
	v_mfma_f32_16x16x32_bf16 v[28:31], v[36:39], v[192:195], v[28:31]
	v_mfma_f32_16x16x32_bf16 v[24:27], v[44:47], v[192:195], v[24:27]
	v_mfma_f32_16x16x32_bf16 v[12:15], v[36:39], v[212:215], v[12:15]
	v_mfma_f32_16x16x32_bf16 v[8:11], v[44:47], v[212:215], v[8:11]
	v_mfma_f32_16x16x32_bf16 v[20:23], v[144:147], v[188:191], v[20:23]
	v_mfma_f32_16x16x32_bf16 v[16:19], v[152:155], v[188:191], v[16:19]
	v_mfma_f32_16x16x32_bf16 v[4:7], v[144:147], v[198:201], v[4:7]
	v_mfma_f32_16x16x32_bf16 v[0:3], v[152:155], v[198:201], v[0:3]
	v_mfma_f32_16x16x32_bf16 v[32:35], v[144:147], v[160:163], v[68:71]
	v_mfma_f32_16x16x32_bf16 v[36:39], v[152:155], v[160:163], v[64:67]
	v_mfma_f32_16x16x32_bf16 v[40:43], v[144:147], v[168:171], v[52:55]
	v_mfma_f32_16x16x32_bf16 v[44:47], v[152:155], v[168:171], v[48:51]
	v_mfma_f32_16x16x32_bf16 v[20:23], v[148:151], v[192:195], v[20:23]
	v_mfma_f32_16x16x32_bf16 v[16:19], v[156:159], v[192:195], v[16:19]
	v_mfma_f32_16x16x32_bf16 v[4:7], v[148:151], v[212:215], v[4:7]
	v_mfma_f32_16x16x32_bf16 v[0:3], v[156:159], v[212:215], v[0:3]
	v_mfma_f32_16x16x32_bf16 v[32:35], v[148:151], v[164:167], v[32:35]
	v_mfma_f32_16x16x32_bf16 v[36:39], v[156:159], v[164:167], v[36:39]
	v_mfma_f32_16x16x32_bf16 v[40:43], v[148:151], v[172:175], v[40:43]
	v_mfma_f32_16x16x32_bf16 v[44:47], v[156:159], v[172:175], v[44:47]
	s_barrier
	s_setprio 0
	s_add_i32 s64, 0, 0x18000
	s_add_i32 s65, 0, 0x1c000
	v_add_u32_e32 v68, s64, v208
	v_add_u32_e32 v156, s65, v208
	ds_read_b128 v[48:51], v68
	ds_read_b128 v[52:55], v68 offset:1024
	ds_read_b128 v[64:67], v68 offset:2048
	ds_read_b128 v[68:71], v68 offset:3072
	ds_read_b128 v[144:147], v156
	ds_read_b128 v[148:151], v156 offset:1024
	ds_read_b128 v[152:155], v156 offset:2048
	ds_read_b128 v[156:159], v156 offset:3072
	s_mov_b32 m0, s46
	ds_read_b128 v[160:163], v210 offset:32768
	ds_read_b128 v[164:167], v210 offset:33792
	ds_read_b128 v[168:171], v210 offset:34816
	ds_read_b128 v[172:175], v210 offset:35840
	ds_read_b128 v[188:191], v210 offset:36864
	ds_read_b128 v[192:195], v210 offset:37888
	ds_read_b128 v[198:201], v210 offset:38912
	ds_read_b128 v[212:215], v210 offset:39936
	global_load_lds_dwordx4 v182, s[34:35]
	s_mov_b32 m0, s47
	s_nop 0
	global_load_lds_dwordx4 v180, s[34:35]
	s_waitcnt vmcnt(8)
	s_waitcnt lgkmcnt(0)
	s_setprio 1
	s_barrier
	v_mfma_f32_16x16x32_bf16 v[140:143], v[48:51], v[160:163], v[140:143]
	v_mfma_f32_16x16x32_bf16 v[136:139], v[64:67], v[160:163], v[136:139]
	v_mfma_f32_16x16x32_bf16 v[124:127], v[48:51], v[168:171], v[124:127]
	v_mfma_f32_16x16x32_bf16 v[120:123], v[64:67], v[168:171], v[120:123]
	v_mfma_f32_16x16x32_bf16 v[108:111], v[48:51], v[188:191], v[108:111]
	v_mfma_f32_16x16x32_bf16 v[104:107], v[64:67], v[188:191], v[104:107]
	v_mfma_f32_16x16x32_bf16 v[92:95], v[48:51], v[198:201], v[92:95]
	v_mfma_f32_16x16x32_bf16 v[88:91], v[64:67], v[198:201], v[88:91]
	v_mfma_f32_16x16x32_bf16 v[140:143], v[52:55], v[164:167], v[140:143]
	v_mfma_f32_16x16x32_bf16 v[136:139], v[68:71], v[164:167], v[136:139]
	v_mfma_f32_16x16x32_bf16 v[124:127], v[52:55], v[172:175], v[124:127]
	v_mfma_f32_16x16x32_bf16 v[120:123], v[68:71], v[172:175], v[120:123]
	v_mfma_f32_16x16x32_bf16 v[108:111], v[52:55], v[192:195], v[108:111]
	v_mfma_f32_16x16x32_bf16 v[104:107], v[68:71], v[192:195], v[104:107]
	v_mfma_f32_16x16x32_bf16 v[92:95], v[52:55], v[212:215], v[92:95]
	v_mfma_f32_16x16x32_bf16 v[88:91], v[68:71], v[212:215], v[88:91]
	v_mfma_f32_16x16x32_bf16 v[132:135], v[144:147], v[160:163], v[132:135]
	v_mfma_f32_16x16x32_bf16 v[128:131], v[152:155], v[160:163], v[128:131]
	v_mfma_f32_16x16x32_bf16 v[116:119], v[144:147], v[168:171], v[116:119]
	v_mfma_f32_16x16x32_bf16 v[112:115], v[152:155], v[168:171], v[112:115]
	v_mfma_f32_16x16x32_bf16 v[100:103], v[144:147], v[188:191], v[100:103]
	v_mfma_f32_16x16x32_bf16 v[96:99], v[152:155], v[188:191], v[96:99]
	v_mfma_f32_16x16x32_bf16 v[84:87], v[144:147], v[198:201], v[84:87]
	v_mfma_f32_16x16x32_bf16 v[80:83], v[152:155], v[198:201], v[80:83]
	v_mfma_f32_16x16x32_bf16 v[132:135], v[148:151], v[164:167], v[132:135]
	v_mfma_f32_16x16x32_bf16 v[128:131], v[156:159], v[164:167], v[128:131]
	v_mfma_f32_16x16x32_bf16 v[116:119], v[148:151], v[172:175], v[116:119]
	v_mfma_f32_16x16x32_bf16 v[112:115], v[156:159], v[172:175], v[112:115]
	v_mfma_f32_16x16x32_bf16 v[100:103], v[148:151], v[192:195], v[100:103]
	v_mfma_f32_16x16x32_bf16 v[96:99], v[156:159], v[192:195], v[96:99]
	v_mfma_f32_16x16x32_bf16 v[84:87], v[148:151], v[212:215], v[84:87]
	v_mfma_f32_16x16x32_bf16 v[80:83], v[156:159], v[212:215], v[80:83]
	s_barrier
; #define PG8_STAGE(bufoff, gbase, voff) do { _Pragma("unroll") for (int _i = 0; _i < 2; ++_i) \
;         __builtin_amdgcn_global_load_lds((const unsigned*)((const char*)(gbase) + (voff)[_i]), (LAS unsigned*)(lds + (bufoff) + ldsw + _i * 8192), 16, 0, 0); } while (0)
; #define PG8_LDA(dst, b, h) do { _Pragma("unroll") for (int m = 0; m < 4; ++m) _Pragma("unroll") for (int k = 0; k < 2; ++k) dst[m][k] = *(const LAS bf16x8*)(lds + PG8_SA(b, h) + aoff + m * 2048 + k * 1024); } while (0)
; #define PG8_WAIT_V(n) asm volatile("s_waitcnt vmcnt(" #n ")" ::: "memory")
; #define PG8_WAIT_L(n) asm volatile("s_waitcnt lgkmcnt(" #n ")" ::: "memory")
; #define PG8_BAR __builtin_amdgcn_s_barrier()
; #define PG8_SCHED __builtin_amdgcn_sched_barrier(0)
; template <bool F16, class Sched, class Epi>
; __device__ __forceinline__ void gemm_phase(LAS unsigned char* lds, const Gemm g, const Sched& S, const Epi& E, int wave_s) {
;     ...
;             PG8_LDA(At, 1, 1); PG8_STAGE(PG8_SB(1, 0), b3, voffB); PG8_STAGE(PG8_SB(1, 1), b3 + hstepB, voffB); PG8_STAGE(PG8_SA(1, 0), a3, voffA);
;             PG8_WAIT_V(8); PG8_WAIT_L(0); PG8_BAR; PG8_MMA(1, 0, At, B0); PG8_MMA(1, 1, At, B1); PG8_BAR; PG8_SCHED;
;         }
	s_setprio 0
	s_add_i32 s34, s64, s41
	v_lshl_add_u64 v[202:203], v[202:203], 0, s[54:55]
	s_mov_b32 m0, s34
	ds_read_b128 v[160:163], v210 offset:49152
	ds_read_b128 v[164:167], v210 offset:50176
	ds_read_b128 v[168:171], v210 offset:51200
	ds_read_b128 v[172:175], v210 offset:52224
	ds_read_b128 v[188:191], v210 offset:53248
	ds_read_b128 v[192:195], v210 offset:54272
	ds_read_b128 v[198:201], v210 offset:55296
	ds_read_b128 v[212:215], v210 offset:56320
	global_load_lds_dwordx4 v[202:203], off
	s_add_i32 m0, s34, 0x2000
	s_add_u32 s30, s30, 0x80080
	v_lshl_add_u64 v[202:203], v[216:217], 0, s[54:55]
	s_addc_u32 s31, s31, 0
	s_add_i32 s34, s65, s41
	global_load_lds_dwordx4 v[202:203], off
	v_lshl_add_u64 v[202:203], s[30:31], 0, v[176:177]
	s_mov_b32 m0, s34
	s_nop 0
	global_load_lds_dwordx4 v[202:203], off
	v_lshl_add_u64 v[202:203], s[30:31], 0, v[178:179]
	s_add_i32 m0, s34, 0x2000
	s_nop 0
	global_load_lds_dwordx4 v[202:203], off
	v_lshl_add_u64 v[202:203], v[218:219], 0, s[54:55]
	s_mov_b32 m0, s49
	s_nop 0
	global_load_lds_dwordx4 v[202:203], off
	v_lshl_add_u64 v[202:203], v[220:221], 0, s[54:55]
	s_mov_b32 m0, s52
	s_nop 0
	global_load_lds_dwordx4 v[202:203], off
	s_waitcnt vmcnt(8)
	s_waitcnt lgkmcnt(0)
	s_setprio 1
	s_barrier
	v_mfma_f32_16x16x32_bf16 v[76:79], v[48:51], v[160:163], v[76:79]
	v_mfma_f32_16x16x32_bf16 v[72:75], v[64:67], v[160:163], v[72:75]
	v_mfma_f32_16x16x32_bf16 v[60:63], v[48:51], v[168:171], v[60:63]
	v_mfma_f32_16x16x32_bf16 v[56:59], v[64:67], v[168:171], v[56:59]
	v_mfma_f32_16x16x32_bf16 v[28:31], v[48:51], v[188:191], v[28:31]
	v_mfma_f32_16x16x32_bf16 v[24:27], v[64:67], v[188:191], v[24:27]
	v_mfma_f32_16x16x32_bf16 v[12:15], v[48:51], v[198:201], v[12:15]
	v_mfma_f32_16x16x32_bf16 v[8:11], v[64:67], v[198:201], v[8:11]
	v_mfma_f32_16x16x32_bf16 v[76:79], v[52:55], v[164:167], v[76:79]
	v_mfma_f32_16x16x32_bf16 v[72:75], v[68:71], v[164:167], v[72:75]
	v_mfma_f32_16x16x32_bf16 v[60:63], v[52:55], v[172:175], v[60:63]
	v_mfma_f32_16x16x32_bf16 v[56:59], v[68:71], v[172:175], v[56:59]
	v_mfma_f32_16x16x32_bf16 v[28:31], v[52:55], v[192:195], v[28:31]
	v_mfma_f32_16x16x32_bf16 v[24:27], v[68:71], v[192:195], v[24:27]
	v_mfma_f32_16x16x32_bf16 v[12:15], v[52:55], v[212:215], v[12:15]
	v_mfma_f32_16x16x32_bf16 v[8:11], v[68:71], v[212:215], v[8:11]
	v_mfma_f32_16x16x32_bf16 v[32:35], v[144:147], v[160:163], v[32:35]
	v_mfma_f32_16x16x32_bf16 v[68:71], v[148:151], v[164:167], v[32:35]
	v_mfma_f32_16x16x32_bf16 v[32:35], v[152:155], v[160:163], v[36:39]
	v_mfma_f32_16x16x32_bf16 v[64:67], v[156:159], v[164:167], v[32:35]
	v_mfma_f32_16x16x32_bf16 v[32:35], v[144:147], v[168:171], v[40:43]
	v_mfma_f32_16x16x32_bf16 v[52:55], v[148:151], v[172:175], v[32:35]
	v_mfma_f32_16x16x32_bf16 v[32:35], v[152:155], v[168:171], v[44:47]
	v_mfma_f32_16x16x32_bf16 v[20:23], v[144:147], v[188:191], v[20:23]
	v_mfma_f32_16x16x32_bf16 v[16:19], v[152:155], v[188:191], v[16:19]
	v_mfma_f32_16x16x32_bf16 v[4:7], v[144:147], v[198:201], v[4:7]
	v_mfma_f32_16x16x32_bf16 v[0:3], v[152:155], v[198:201], v[0:3]
	v_mfma_f32_16x16x32_bf16 v[48:51], v[156:159], v[172:175], v[32:35]
	v_mfma_f32_16x16x32_bf16 v[20:23], v[148:151], v[192:195], v[20:23]
	v_mfma_f32_16x16x32_bf16 v[16:19], v[156:159], v[192:195], v[16:19]
	v_mfma_f32_16x16x32_bf16 v[4:7], v[148:151], v[212:215], v[4:7]
	v_mfma_f32_16x16x32_bf16 v[0:3], v[156:159], v[212:215], v[0:3]
	s_barrier
	s_setprio 0
	s_add_i32 s63, s63, 2
	s_add_u32 s4, s4, 0x100
	s_addc_u32 s5, s5, 0
	s_add_u32 s61, s61, 0x100
	s_addc_u32 s62, s62, 0
	s_cmp_gt_u32 s63, 29
	s_cbranch_scc0 .LBB0_869
	s_and_b64 vcc, exec, s[26:27]
	s_cbranch_vccz .LBB0_872
	s_barrier

; #define PG8_STAGE(bufoff, gbase, voff) do { _Pragma("unroll") for (int _i = 0; _i < 2; ++_i) \
;         __builtin_amdgcn_global_load_lds((const unsigned*)((const char*)(gbase) + (voff)[_i]), (LAS unsigned*)(lds + (bufoff) + ldsw + _i * 8192), 16, 0, 0); } while (0)
; #define PG8_LDA(dst, b, h) do { _Pragma("unroll") for (int m = 0; m < 4; ++m) _Pragma("unroll") for (int k = 0; k < 2; ++k) dst[m][k] = *(const LAS bf16x8*)(lds + PG8_SA(b, h) + aoff + m * 2048 + k * 1024); } while (0)
; #define PG8_LDB(dst, b, h) do { _Pragma("unroll") for (int n = 0; n < 2; ++n) _Pragma("unroll") for (int k = 0; k < 2; ++k) dst[n][k] = *(const LAS bf16x8*)(lds + PG8_SB(b, h) + boff + n * 2048 + k * 1024); } while (0)
; #define PG8_WAIT_V(n) asm volatile("s_waitcnt vmcnt(" #n ")" ::: "memory")
; #define PG8_WAIT_L(n) asm volatile("s_waitcnt lgkmcnt(" #n ")" ::: "memory")
; #define PG8_BAR __builtin_amdgcn_s_barrier()
; #define PG8_SCHED __builtin_amdgcn_sched_barrier(0)
; template <bool F16, class Sched, class Epi>
; __device__ __forceinline__ void gemm_phase(LAS unsigned char* lds, const Gemm g, const Sched& S, const Epi& E, int wave_s) {
;     ...
;         for (int t = 0; t < nt; t += 2) {
;             const bool last = (t == nt - 2);
;             const char* a1 = cA + (size_t)(t + 1) * kstep;
;             const char* a2 = last ? nA : cA + (size_t)(t + 2) * kstep; const char* b2 = last ? nB : cB + (size_t)(t + 2) * kstep;
;             const char* a3 = a2 + kstep; const char* b3 = b2 + kstep;
;             PG8_LDB(B0, 0, 0); PG8_LDB(B1, 0, 1); PG8_SCHED; PG8_LDA(At, 0, 0); PG8_STAGE(PG8_SA(1, 1), a1 + hstepA, voffA);
;             PG8_WAIT_V(8); PG8_WAIT_L(0); PG8_BAR; PG8_MMA(0, 0, At, B0); PG8_MMA(0, 1, At, B1); PG8_BAR; PG8_SCHED;
;             PG8_LDA(At, 0, 1); PG8_STAGE(PG8_SB(0, 0), b2, voffB); PG8_STAGE(PG8_SB(0, 1), b2 + hstepB, voffB); PG8_STAGE(PG8_SA(0, 0), a2, voffA);
;             PG8_WAIT_V(8); PG8_WAIT_L(0); PG8_BAR; PG8_MMA(1, 0, At, B0); PG8_MMA(1, 1, At, B1); PG8_BAR; PG8_SCHED;
.LBB0_993:
	s_add_i32 s43, 0, 0x10000
	s_add_i32 s26, 0, 0x14000
	v_add_u32_e32 v68, s43, v208
	v_add_u32_e32 v156, s26, v208
	ds_read_b128 v[56:59], v68
	ds_read_b128 v[60:63], v68 offset:1024
	ds_read_b128 v[64:67], v68 offset:2048
	ds_read_b128 v[68:71], v68 offset:3072
	ds_read_b128 v[144:147], v156
	ds_read_b128 v[148:151], v156 offset:1024
	ds_read_b128 v[152:155], v156 offset:2048
	ds_read_b128 v[156:159], v156 offset:3072
	s_add_i32 m0, s18, 0xc000
	ds_read_b128 v[160:163], v210
	ds_read_b128 v[164:167], v210 offset:1024
	ds_read_b128 v[168:171], v210 offset:2048
	ds_read_b128 v[172:175], v210 offset:3072
	ds_read_b128 v[188:191], v210 offset:4096
	ds_read_b128 v[192:195], v210 offset:5120
	ds_read_b128 v[198:201], v210 offset:6144
	ds_read_b128 v[212:215], v210 offset:7168
	global_load_lds_dwordx4 v184, s[38:39]
	s_add_i32 m0, s18, 0xe000
	s_nop 0
	global_load_lds_dwordx4 v186, s[38:39]
	s_waitcnt vmcnt(8)
	s_waitcnt lgkmcnt(0)
	s_setprio 1
	s_barrier
	v_mfma_f32_16x16x32_bf16 v[140:143], v[56:59], v[160:163], v[140:143]
	v_mfma_f32_16x16x32_bf16 v[136:139], v[64:67], v[160:163], v[136:139]
	v_mfma_f32_16x16x32_bf16 v[124:127], v[56:59], v[168:171], v[124:127]
	v_mfma_f32_16x16x32_bf16 v[120:123], v[64:67], v[168:171], v[120:123]
	v_mfma_f32_16x16x32_bf16 v[108:111], v[56:59], v[188:191], v[108:111]
	v_mfma_f32_16x16x32_bf16 v[104:107], v[64:67], v[188:191], v[104:107]
	v_mfma_f32_16x16x32_bf16 v[92:95], v[56:59], v[198:201], v[92:95]
	v_mfma_f32_16x16x32_bf16 v[88:91], v[64:67], v[198:201], v[88:91]
	v_mfma_f32_16x16x32_bf16 v[140:143], v[60:63], v[164:167], v[140:143]
	v_mfma_f32_16x16x32_bf16 v[136:139], v[68:71], v[164:167], v[136:139]
	v_mfma_f32_16x16x32_bf16 v[124:127], v[60:63], v[172:175], v[124:127]
	v_mfma_f32_16x16x32_bf16 v[120:123], v[68:71], v[172:175], v[120:123]
	v_mfma_f32_16x16x32_bf16 v[108:111], v[60:63], v[192:195], v[108:111]
	v_mfma_f32_16x16x32_bf16 v[104:107], v[68:71], v[192:195], v[104:107]
	v_mfma_f32_16x16x32_bf16 v[92:95], v[60:63], v[212:215], v[92:95]
	v_mfma_f32_16x16x32_bf16 v[88:91], v[68:71], v[212:215], v[88:91]
	v_mfma_f32_16x16x32_bf16 v[132:135], v[144:147], v[160:163], v[132:135]
	v_mfma_f32_16x16x32_bf16 v[128:131], v[152:155], v[160:163], v[128:131]
	v_mfma_f32_16x16x32_bf16 v[116:119], v[144:147], v[168:171], v[116:119]
	v_mfma_f32_16x16x32_bf16 v[112:115], v[152:155], v[168:171], v[112:115]
	v_mfma_f32_16x16x32_bf16 v[100:103], v[144:147], v[188:191], v[100:103]
	v_mfma_f32_16x16x32_bf16 v[96:99], v[152:155], v[188:191], v[96:99]
	v_mfma_f32_16x16x32_bf16 v[84:87], v[144:147], v[198:201], v[84:87]
	v_mfma_f32_16x16x32_bf16 v[80:83], v[152:155], v[198:201], v[80:83]
	v_mfma_f32_16x16x32_bf16 v[132:135], v[148:151], v[164:167], v[132:135]
	v_mfma_f32_16x16x32_bf16 v[128:131], v[156:159], v[164:167], v[128:131]
	v_mfma_f32_16x16x32_bf16 v[116:119], v[148:151], v[172:175], v[116:119]
	v_mfma_f32_16x16x32_bf16 v[112:115], v[156:159], v[172:175], v[112:115]
	v_mfma_f32_16x16x32_bf16 v[100:103], v[148:151], v[192:195], v[100:103]
	v_mfma_f32_16x16x32_bf16 v[96:99], v[156:159], v[192:195], v[96:99]
	v_mfma_f32_16x16x32_bf16 v[84:87], v[148:151], v[212:215], v[84:87]
	v_mfma_f32_16x16x32_bf16 v[80:83], v[156:159], v[212:215], v[80:83]
	s_barrier
	s_setprio 0
	s_add_u32 s24, s38, 0xfff80080
	s_addc_u32 s25, s39, -1
	s_cmp_eq_u32 s42, 28
	s_cselect_b32 s65, s4, s25
	s_cselect_b32 s64, s5, s24
	s_cselect_b32 vcc_hi, s6, s9
	s_cselect_b32 vcc_lo, s7, s8
	s_add_i32 s24, s43, s15
	v_lshl_add_u64 v[202:203], vcc, 0, v[176:177]
	s_mov_b32 m0, s24
	ds_read_b128 v[160:163], v210 offset:16384
	ds_read_b128 v[164:167], v210 offset:17408
	ds_read_b128 v[168:171], v210 offset:18432
	ds_read_b128 v[172:175], v210 offset:19456
	ds_read_b128 v[188:191], v210 offset:20480
	ds_read_b128 v[192:195], v210 offset:21504
	ds_read_b128 v[198:201], v210 offset:22528
	ds_read_b128 v[212:215], v210 offset:23552
	global_load_lds_dwordx4 v[202:203], off
	s_add_i32 m0, s24, 0x2000
	s_add_u32 s24, vcc_lo, 0x80000
	v_lshl_add_u64 v[216:217], vcc, 0, v[178:179]
	s_addc_u32 s25, vcc_hi, 0
	s_add_i32 s26, s26, s15
	global_load_lds_dwordx4 v[216:217], off
	v_lshl_add_u64 v[218:219], s[24:25], 0, v[176:177]
	s_mov_b32 m0, s26
	v_lshl_add_u64 v[220:221], s[64:65], 0, v[180:181]
	global_load_lds_dwordx4 v[218:219], off
	v_lshl_add_u64 v[218:219], s[24:25], 0, v[178:179]
	s_add_i32 m0, s26, 0x2000
	s_nop 0
	global_load_lds_dwordx4 v[218:219], off
	v_lshl_add_u64 v[218:219], s[64:65], 0, v[182:183]
	s_mov_b32 m0, s18
	s_nop 0
	global_load_lds_dwordx4 v[218:219], off
	s_mov_b32 m0, s19
	s_nop 0
	global_load_lds_dwordx4 v[220:221], off
	s_add_u32 s24, s64, 0x80000
	s_addc_u32 s25, s65, 0
	s_waitcnt vmcnt(8)
	s_waitcnt lgkmcnt(0)
	s_setprio 1
	s_barrier
; #define PG8_STAGE(bufoff, gbase, voff) do { _Pragma("unroll") for (int _i = 0; _i < 2; ++_i) \
;         __builtin_amdgcn_global_load_lds((const unsigned*)((const char*)(gbase) + (voff)[_i]), (LAS unsigned*)(lds + (bufoff) + ldsw + _i * 8192), 16, 0, 0); } while (0)
; #define PG8_LDA(dst, b, h) do { _Pragma("unroll") for (int m = 0; m < 4; ++m) _Pragma("unroll") for (int k = 0; k < 2; ++k) dst[m][k] = *(const LAS bf16x8*)(lds + PG8_SA(b, h) + aoff + m * 2048 + k * 1024); } while (0)
; #define PG8_LDB(dst, b, h) do { _Pragma("unroll") for (int n = 0; n < 2; ++n) _Pragma("unroll") for (int k = 0; k < 2; ++k) dst[n][k] = *(const LAS bf16x8*)(lds + PG8_SB(b, h) + boff + n * 2048 + k * 1024); } while (0)
; #define PG8_WAIT_V(n) asm volatile("s_waitcnt vmcnt(" #n ")" ::: "memory")
; #define PG8_WAIT_L(n) asm volatile("s_waitcnt lgkmcnt(" #n ")" ::: "memory")
; #define PG8_BAR __builtin_amdgcn_s_barrier()
; #define PG8_SCHED __builtin_amdgcn_sched_barrier(0)
; template <bool F16, class Sched, class Epi>
; __device__ __forceinline__ void gemm_phase(LAS unsigned char* lds, const Gemm g, const Sched& S, const Epi& E, int wave_s) {
;     ...
;             PG8_WAIT_V(8); PG8_WAIT_L(0); PG8_BAR; PG8_MMA(1, 0, At, B0); PG8_MMA(1, 1, At, B1); PG8_BAR; PG8_SCHED;
;             PG8_LDB(B0, 1, 0); PG8_LDB(B1, 1, 1); PG8_SCHED; PG8_LDA(At, 1, 0); PG8_STAGE(PG8_SA(0, 1), a2 + hstepA, voffA);
;             PG8_WAIT_V(8); PG8_WAIT_L(0); PG8_BAR; PG8_MMA(0, 0, At, B0); PG8_MMA(0, 1, At, B1); PG8_BAR; PG8_SCHED;
	v_mfma_f32_16x16x32_bf16 v[76:79], v[56:59], v[160:163], v[76:79]
	v_mfma_f32_16x16x32_bf16 v[72:75], v[64:67], v[160:163], v[72:75]
	v_mfma_f32_16x16x32_bf16 v[44:47], v[56:59], v[168:171], v[44:47]
	v_mfma_f32_16x16x32_bf16 v[40:43], v[64:67], v[168:171], v[40:43]
	v_mfma_f32_16x16x32_bf16 v[28:31], v[56:59], v[188:191], v[28:31]
	v_mfma_f32_16x16x32_bf16 v[24:27], v[64:67], v[188:191], v[24:27]
	v_mfma_f32_16x16x32_bf16 v[12:15], v[56:59], v[198:201], v[12:15]
	v_mfma_f32_16x16x32_bf16 v[8:11], v[64:67], v[198:201], v[8:11]
	v_mfma_f32_16x16x32_bf16 v[76:79], v[60:63], v[164:167], v[76:79]
	v_mfma_f32_16x16x32_bf16 v[72:75], v[68:71], v[164:167], v[72:75]
	v_mfma_f32_16x16x32_bf16 v[44:47], v[60:63], v[172:175], v[44:47]
	v_mfma_f32_16x16x32_bf16 v[40:43], v[68:71], v[172:175], v[40:43]
	v_mfma_f32_16x16x32_bf16 v[28:31], v[60:63], v[192:195], v[28:31]
	v_mfma_f32_16x16x32_bf16 v[24:27], v[68:71], v[192:195], v[24:27]
	v_mfma_f32_16x16x32_bf16 v[12:15], v[60:63], v[212:215], v[12:15]
	v_mfma_f32_16x16x32_bf16 v[8:11], v[68:71], v[212:215], v[8:11]
	v_mfma_f32_16x16x32_bf16 v[52:55], v[144:147], v[160:163], v[52:55]
	v_mfma_f32_16x16x32_bf16 v[48:51], v[152:155], v[160:163], v[48:51]
	v_mfma_f32_16x16x32_bf16 v[36:39], v[144:147], v[168:171], v[36:39]
	v_mfma_f32_16x16x32_bf16 v[32:35], v[152:155], v[168:171], v[32:35]
	v_mfma_f32_16x16x32_bf16 v[20:23], v[144:147], v[188:191], v[20:23]
	v_mfma_f32_16x16x32_bf16 v[16:19], v[152:155], v[188:191], v[16:19]
	v_mfma_f32_16x16x32_bf16 v[4:7], v[144:147], v[198:201], v[4:7]
	v_mfma_f32_16x16x32_bf16 v[0:3], v[152:155], v[198:201], v[0:3]
	v_mfma_f32_16x16x32_bf16 v[52:55], v[148:151], v[164:167], v[52:55]
	v_mfma_f32_16x16x32_bf16 v[48:51], v[156:159], v[164:167], v[48:51]
	v_mfma_f32_16x16x32_bf16 v[36:39], v[148:151], v[172:175], v[36:39]
	v_mfma_f32_16x16x32_bf16 v[32:35], v[156:159], v[172:175], v[32:35]
	v_mfma_f32_16x16x32_bf16 v[20:23], v[148:151], v[192:195], v[20:23]
	v_mfma_f32_16x16x32_bf16 v[16:19], v[156:159], v[192:195], v[16:19]
	v_mfma_f32_16x16x32_bf16 v[4:7], v[148:151], v[212:215], v[4:7]
	v_mfma_f32_16x16x32_bf16 v[0:3], v[156:159], v[212:215], v[0:3]
	s_barrier
	s_setprio 0
	s_add_i32 s26, 0, 0x18000
	s_add_i32 s27, 0, 0x1c000
	v_add_u32_e32 v68, s26, v208
	v_add_u32_e32 v156, s27, v208
	ds_read_b128 v[56:59], v68
	ds_read_b128 v[60:63], v68 offset:1024
	ds_read_b128 v[64:67], v68 offset:2048
	ds_read_b128 v[68:71], v68 offset:3072
	ds_read_b128 v[144:147], v156
	ds_read_b128 v[148:151], v156 offset:1024
	ds_read_b128 v[152:155], v156 offset:2048
	ds_read_b128 v[156:159], v156 offset:3072
	s_mov_b32 m0, s20
	ds_read_b128 v[160:163], v210 offset:32768
	ds_read_b128 v[164:167], v210 offset:33792
	ds_read_b128 v[168:171], v210 offset:34816
	ds_read_b128 v[172:175], v210 offset:35840
	ds_read_b128 v[188:191], v210 offset:36864
	ds_read_b128 v[192:195], v210 offset:37888
	ds_read_b128 v[198:201], v210 offset:38912
	ds_read_b128 v[212:215], v210 offset:39936
	global_load_lds_dwordx4 v182, s[24:25]
	s_mov_b32 m0, s21
	s_nop 0
	global_load_lds_dwordx4 v180, s[24:25]
	s_waitcnt vmcnt(8)
	s_waitcnt lgkmcnt(0)
	s_setprio 1
	s_barrier
	v_mfma_f32_16x16x32_bf16 v[140:143], v[56:59], v[160:163], v[140:143]
	v_mfma_f32_16x16x32_bf16 v[136:139], v[64:67], v[160:163], v[136:139]
	v_mfma_f32_16x16x32_bf16 v[124:127], v[56:59], v[168:171], v[124:127]
	v_mfma_f32_16x16x32_bf16 v[120:123], v[64:67], v[168:171], v[120:123]
	v_mfma_f32_16x16x32_bf16 v[108:111], v[56:59], v[188:191], v[108:111]
	v_mfma_f32_16x16x32_bf16 v[104:107], v[64:67], v[188:191], v[104:107]
	v_mfma_f32_16x16x32_bf16 v[92:95], v[56:59], v[198:201], v[92:95]
	v_mfma_f32_16x16x32_bf16 v[88:91], v[64:67], v[198:201], v[88:91]
	v_mfma_f32_16x16x32_bf16 v[140:143], v[60:63], v[164:167], v[140:143]
	v_mfma_f32_16x16x32_bf16 v[136:139], v[68:71], v[164:167], v[136:139]
	v_mfma_f32_16x16x32_bf16 v[124:127], v[60:63], v[172:175], v[124:127]
	v_mfma_f32_16x16x32_bf16 v[120:123], v[68:71], v[172:175], v[120:123]
	v_mfma_f32_16x16x32_bf16 v[108:111], v[60:63], v[192:195], v[108:111]
	v_mfma_f32_16x16x32_bf16 v[104:107], v[68:71], v[192:195], v[104:107]
	v_mfma_f32_16x16x32_bf16 v[92:95], v[60:63], v[212:215], v[92:95]
	v_mfma_f32_16x16x32_bf16 v[88:91], v[68:71], v[212:215], v[88:91]
	v_mfma_f32_16x16x32_bf16 v[132:135], v[144:147], v[160:163], v[132:135]
	v_mfma_f32_16x16x32_bf16 v[128:131], v[152:155], v[160:163], v[128:131]
	v_mfma_f32_16x16x32_bf16 v[116:119], v[144:147], v[168:171], v[116:119]
	v_mfma_f32_16x16x32_bf16 v[112:115], v[152:155], v[168:171], v[112:115]
	v_mfma_f32_16x16x32_bf16 v[100:103], v[144:147], v[188:191], v[100:103]
	v_mfma_f32_16x16x32_bf16 v[96:99], v[152:155], v[188:191], v[96:99]
	v_mfma_f32_16x16x32_bf16 v[84:87], v[144:147], v[198:201], v[84:87]
	v_mfma_f32_16x16x32_bf16 v[80:83], v[152:155], v[198:201], v[80:83]
	v_mfma_f32_16x16x32_bf16 v[132:135], v[148:151], v[164:167], v[132:135]
	v_mfma_f32_16x16x32_bf16 v[128:131], v[156:159], v[164:167], v[128:131]
	v_mfma_f32_16x16x32_bf16 v[116:119], v[148:151], v[172:175], v[116:119]
	v_mfma_f32_16x16x32_bf16 v[112:115], v[156:159], v[172:175], v[112:115]
	v_mfma_f32_16x16x32_bf16 v[100:103], v[148:151], v[192:195], v[100:103]
	v_mfma_f32_16x16x32_bf16 v[96:99], v[156:159], v[192:195], v[96:99]
	v_mfma_f32_16x16x32_bf16 v[84:87], v[148:151], v[212:215], v[84:87]
	v_mfma_f32_16x16x32_bf16 v[80:83], v[156:159], v[212:215], v[80:83]
	s_barrier
; #define PG8_STAGE(bufoff, gbase, voff) do { _Pragma("unroll") for (int _i = 0; _i < 2; ++_i) \
;         __builtin_amdgcn_global_load_lds((const unsigned*)((const char*)(gbase) + (voff)[_i]), (LAS unsigned*)(lds + (bufoff) + ldsw + _i * 8192), 16, 0, 0); } while (0)
; #define PG8_LDA(dst, b, h) do { _Pragma("unroll") for (int m = 0; m < 4; ++m) _Pragma("unroll") for (int k = 0; k < 2; ++k) dst[m][k] = *(const LAS bf16x8*)(lds + PG8_SA(b, h) + aoff + m * 2048 + k * 1024); } while (0)
; #define PG8_WAIT_V(n) asm volatile("s_waitcnt vmcnt(" #n ")" ::: "memory")
; #define PG8_WAIT_L(n) asm volatile("s_waitcnt lgkmcnt(" #n ")" ::: "memory")
; #define PG8_BAR __builtin_amdgcn_s_barrier()
; #define PG8_SCHED __builtin_amdgcn_sched_barrier(0)
; template <bool F16, class Sched, class Epi>
; __device__ __forceinline__ void gemm_phase(LAS unsigned char* lds, const Gemm g, const Sched& S, const Epi& E, int wave_s) {
;     ...
;             PG8_LDA(At, 1, 1); PG8_STAGE(PG8_SB(1, 0), b3, voffB); PG8_STAGE(PG8_SB(1, 1), b3 + hstepB, voffB); PG8_STAGE(PG8_SA(1, 0), a3, voffA);
;             PG8_WAIT_V(8); PG8_WAIT_L(0); PG8_BAR; PG8_MMA(1, 0, At, B0); PG8_MMA(1, 1, At, B1); PG8_BAR; PG8_SCHED;
;         }
	s_setprio 0
	s_add_i32 s24, s26, s15
	v_lshl_add_u64 v[202:203], v[202:203], 0, s[54:55]
	s_mov_b32 m0, s24
	ds_read_b128 v[160:163], v210 offset:49152
	ds_read_b128 v[164:167], v210 offset:50176
	ds_read_b128 v[168:171], v210 offset:51200
	ds_read_b128 v[172:175], v210 offset:52224
	ds_read_b128 v[188:191], v210 offset:53248
	ds_read_b128 v[192:195], v210 offset:54272
	ds_read_b128 v[198:201], v210 offset:55296
	ds_read_b128 v[212:215], v210 offset:56320
	global_load_lds_dwordx4 v[202:203], off
	s_add_i32 m0, s24, 0x2000
	s_add_u32 s24, vcc_lo, 0x80080
	v_lshl_add_u64 v[202:203], v[216:217], 0, s[54:55]
	s_addc_u32 s25, vcc_hi, 0
	s_add_i32 s26, s27, s15
	global_load_lds_dwordx4 v[202:203], off
	v_lshl_add_u64 v[202:203], s[24:25], 0, v[176:177]
	s_mov_b32 m0, s26
	s_nop 0
	global_load_lds_dwordx4 v[202:203], off
	v_lshl_add_u64 v[202:203], s[24:25], 0, v[178:179]
	s_add_i32 m0, s26, 0x2000
	s_nop 0
	global_load_lds_dwordx4 v[202:203], off
	v_lshl_add_u64 v[202:203], v[218:219], 0, s[54:55]
	s_mov_b32 m0, s50
	s_nop 0
	global_load_lds_dwordx4 v[202:203], off
	v_lshl_add_u64 v[202:203], v[220:221], 0, s[54:55]
	s_mov_b32 m0, s22
	s_nop 0
	global_load_lds_dwordx4 v[202:203], off
	s_waitcnt vmcnt(8)
	s_waitcnt lgkmcnt(0)
	s_setprio 1
	s_barrier
	v_mfma_f32_16x16x32_bf16 v[76:79], v[56:59], v[160:163], v[76:79]
	v_mfma_f32_16x16x32_bf16 v[72:75], v[64:67], v[160:163], v[72:75]
	v_mfma_f32_16x16x32_bf16 v[44:47], v[56:59], v[168:171], v[44:47]
	v_mfma_f32_16x16x32_bf16 v[40:43], v[64:67], v[168:171], v[40:43]
	v_mfma_f32_16x16x32_bf16 v[28:31], v[56:59], v[188:191], v[28:31]
	v_mfma_f32_16x16x32_bf16 v[24:27], v[64:67], v[188:191], v[24:27]
	v_mfma_f32_16x16x32_bf16 v[12:15], v[56:59], v[198:201], v[12:15]
	v_mfma_f32_16x16x32_bf16 v[8:11], v[64:67], v[198:201], v[8:11]
	v_mfma_f32_16x16x32_bf16 v[76:79], v[60:63], v[164:167], v[76:79]
	v_mfma_f32_16x16x32_bf16 v[72:75], v[68:71], v[164:167], v[72:75]
	v_mfma_f32_16x16x32_bf16 v[44:47], v[60:63], v[172:175], v[44:47]
	v_mfma_f32_16x16x32_bf16 v[40:43], v[68:71], v[172:175], v[40:43]
	v_mfma_f32_16x16x32_bf16 v[28:31], v[60:63], v[192:195], v[28:31]
	v_mfma_f32_16x16x32_bf16 v[24:27], v[68:71], v[192:195], v[24:27]
	v_mfma_f32_16x16x32_bf16 v[12:15], v[60:63], v[212:215], v[12:15]
	v_mfma_f32_16x16x32_bf16 v[8:11], v[68:71], v[212:215], v[8:11]
	v_mfma_f32_16x16x32_bf16 v[52:55], v[144:147], v[160:163], v[52:55]
	v_mfma_f32_16x16x32_bf16 v[48:51], v[152:155], v[160:163], v[48:51]
	v_mfma_f32_16x16x32_bf16 v[36:39], v[144:147], v[168:171], v[36:39]
	v_mfma_f32_16x16x32_bf16 v[32:35], v[152:155], v[168:171], v[32:35]
	v_mfma_f32_16x16x32_bf16 v[20:23], v[144:147], v[188:191], v[20:23]
	v_mfma_f32_16x16x32_bf16 v[16:19], v[152:155], v[188:191], v[16:19]
	v_mfma_f32_16x16x32_bf16 v[4:7], v[144:147], v[198:201], v[4:7]
	v_mfma_f32_16x16x32_bf16 v[0:3], v[152:155], v[198:201], v[0:3]
	v_mfma_f32_16x16x32_bf16 v[52:55], v[148:151], v[164:167], v[52:55]
	v_mfma_f32_16x16x32_bf16 v[48:51], v[156:159], v[164:167], v[48:51]
	v_mfma_f32_16x16x32_bf16 v[36:39], v[148:151], v[172:175], v[36:39]
	v_mfma_f32_16x16x32_bf16 v[32:35], v[156:159], v[172:175], v[32:35]
	v_mfma_f32_16x16x32_bf16 v[20:23], v[148:151], v[192:195], v[20:23]
	v_mfma_f32_16x16x32_bf16 v[16:19], v[156:159], v[192:195], v[16:19]
	v_mfma_f32_16x16x32_bf16 v[4:7], v[148:151], v[212:215], v[4:7]
	v_mfma_f32_16x16x32_bf16 v[0:3], v[156:159], v[212:215], v[0:3]
	s_barrier
	s_setprio 0
	s_add_i32 s42, s42, 2
	s_add_u32 s38, s38, 0x100
	s_addc_u32 s39, s39, 0
	s_add_u32 s8, s8, 0x100
	s_addc_u32 s9, s9, 0
	s_cmp_gt_u32 s42, 29
	s_cbranch_scc0 .LBB0_993
	s_and_b64 vcc, exec, s[88:89]
	s_cbranch_vccz .LBB0_996
	s_barrier
